# one static s_setprio 1 for waves 4-7 during the prompt GEMM K-loops (reset after the loop)
# speedup vs baseline: 1.0095x; 1.0005x over previous
.LBB0_271:
	s_add_i32 s35, s35, 1
	s_mov_b32 s49, s6
	s_lshl_b32 s6, s35, 5
	s_add_i32 s6, s6, s3
	s_mov_b64 s[24:25], s[8:9]
	s_lshl_b32 s8, s6, 3
	s_ashr_i32 s7, s6, 2
	s_add_i32 s8, s8, s38
	s_cmpk_lt_i32 s6, 0x104
	s_cselect_b32 s6, s7, s8
	s_mov_b32 s50, s28
	s_cselect_b32 s28, s39, 32
	s_cmpk_lt_i32 s6, 0x41
	s_cselect_b64 s[20:21], -1, 0
	s_lshl_b32 s7, s28, 21
	v_readlane_b32 s0, v250, 46
	s_mov_b64 s[22:23], s[10:11]
	v_readlane_b32 s1, v250, 47
	s_add_u32 s10, s0, s7
	s_addc_u32 s11, s1, 0
	s_and_b64 s[8:9], s[20:21], exec
	s_cselect_b32 s51, s11, s23
	s_cselect_b32 s52, s10, s22
	s_ashr_i32 s7, s6, 31
	s_lshl_b64 s[8:9], s[6:7], 21
	v_readlane_b32 s0, v250, 38
	v_readlane_b32 s1, v250, 39
	s_add_u32 s8, s0, s8
	s_addc_u32 s9, s1, s9
	s_and_b64 s[26:27], s[20:21], exec
	s_cselect_b32 s7, s9, s25
	s_cselect_b32 s53, s8, s24
	s_add_u32 s22, s22, 0x100080
	s_addc_u32 s23, s23, 0
	s_add_u32 s54, s24, 0x100
	s_addc_u32 s55, s25, 0
	s_mov_b32 s56, -2
	s_and_b64 vcc, exec, s[12:13]
	s_cbranch_vccz .Lsp_0
	s_setprio 1
.Lsp_0:
	s_add_u32 s58, s22, 0xfff00000
	s_addc_u32 s59, s23, -1
	s_mov_b32 m0, s36
	ds_read_b128 v[154:157], v148
	global_load_lds_dwordx4 v130, s[58:59]
	s_mov_b32 m0, s37
	ds_read_b128 v[158:161], v148 offset:1024
	global_load_lds_dwordx4 v134, s[58:59]
	s_mov_b32 m0, s40
	ds_read_b128 v[164:167], v148 offset:2048
	global_load_lds_dwordx4 v142, s[22:23]
	s_mov_b32 m0, s41
	ds_read_b128 v[168:171], v148 offset:3072
	global_load_lds_dwordx4 v144, s[22:23]
	ds_read_b128 v[172:175], v149
	ds_read_b128 v[176:179], v149 offset:1024
	ds_read_b128 v[180:183], v149 offset:2048
	ds_read_b128 v[184:187], v149 offset:3072
	s_add_u32 s24, s22, 0xfff00080
	s_addc_u32 s25, s23, -1
	s_cmp_eq_u32 s56, 60
	s_cselect_b32 s27, s51, s25
	s_cselect_b32 s26, s52, s24
	s_cselect_b32 s25, s7, s55
	s_cselect_b32 s24, s53, s54
	ds_read_b128 v[188:191], v150
	ds_read_b128 v[192:195], v150 offset:1024
	ds_read_b128 v[196:199], v150 offset:2048
	ds_read_b128 v[200:203], v150 offset:3072
	ds_read_b128 v[204:207], v150 offset:4096
	ds_read_b128 v[208:211], v150 offset:5120
	ds_read_b128 v[212:215], v150 offset:6144
	ds_read_b128 v[216:219], v150 offset:7168
	s_waitcnt vmcnt(8)
	s_waitcnt lgkmcnt(0)
	s_barrier
	v_mfma_f32_16x16x32_bf16 v[126:129], v[154:157], v[188:191], 0
	v_mfma_f32_16x16x32_bf16 v[126:129], v[158:161], v[192:195], v[126:129]
	v_mfma_f32_16x16x32_bf16 v[122:125], v[168:171], v[192:195], 0
	v_mfma_f32_16x16x32_bf16 v[122:125], v[164:167], v[188:191], v[122:125]
	v_mfma_f32_16x16x32_bf16 v[114:117], v[164:167], v[196:199], 0
	v_mfma_f32_16x16x32_bf16 v[114:117], v[168:171], v[200:203], v[114:117]
	v_mfma_f32_16x16x32_bf16 v[118:121], v[158:161], v[200:203], 0
	v_mfma_f32_16x16x32_bf16 v[118:121], v[154:157], v[196:199], v[118:121]
	v_mfma_f32_16x16x32_bf16 v[102:105], v[154:157], v[204:207], 0
	v_mfma_f32_16x16x32_bf16 v[102:105], v[158:161], v[208:211], v[102:105]
	v_mfma_f32_16x16x32_bf16 v[98:101], v[168:171], v[208:211], 0
	v_mfma_f32_16x16x32_bf16 v[98:101], v[164:167], v[204:207], v[98:101]
	v_mfma_f32_16x16x32_bf16 v[82:85], v[164:167], v[212:215], 0
	v_mfma_f32_16x16x32_bf16 v[82:85], v[168:171], v[216:219], v[82:85]
	v_mfma_f32_16x16x32_bf16 v[86:89], v[158:161], v[216:219], 0
	v_mfma_f32_16x16x32_bf16 v[86:89], v[154:157], v[212:215], v[86:89]
	v_mfma_f32_16x16x32_bf16 v[70:73], v[172:175], v[212:215], 0
	v_mfma_f32_16x16x32_bf16 v[70:73], v[176:179], v[216:219], v[70:73]
	v_mfma_f32_16x16x32_bf16 v[66:69], v[184:187], v[216:219], 0
	v_mfma_f32_16x16x32_bf16 v[66:69], v[180:183], v[212:215], v[66:69]
	v_mfma_f32_16x16x32_bf16 v[74:77], v[180:183], v[204:207], 0
	v_mfma_f32_16x16x32_bf16 v[74:77], v[184:187], v[208:211], v[74:77]
	v_mfma_f32_16x16x32_bf16 v[78:81], v[176:179], v[208:211], 0
	v_mfma_f32_16x16x32_bf16 v[78:81], v[172:175], v[204:207], v[78:81]
	v_mfma_f32_16x16x32_bf16 v[94:97], v[172:175], v[196:199], 0
	v_mfma_f32_16x16x32_bf16 v[94:97], v[176:179], v[200:203], v[94:97]
	v_mfma_f32_16x16x32_bf16 v[90:93], v[184:187], v[200:203], 0
	v_mfma_f32_16x16x32_bf16 v[90:93], v[180:183], v[196:199], v[90:93]
	v_mfma_f32_16x16x32_bf16 v[106:109], v[180:183], v[188:191], 0
	v_mfma_f32_16x16x32_bf16 v[106:109], v[184:187], v[192:195], v[106:109]
	v_mfma_f32_16x16x32_bf16 v[110:113], v[176:179], v[192:195], 0
	v_mfma_f32_16x16x32_bf16 v[110:113], v[172:175], v[188:191], v[110:113]
	s_barrier
	s_mov_b32 m0, s42
	s_add_u32 s58, s24, 0x100000
	global_load_lds_dwordx4 v132, s[24:25]
	s_mov_b32 m0, s43
	s_addc_u32 s59, s25, 0
	global_load_lds_dwordx4 v136, s[24:25]
	s_mov_b32 m0, s44
	ds_read_b128 v[188:191], v150 offset:16384
	global_load_lds_dwordx4 v132, s[58:59]
	s_mov_b32 m0, s45
	ds_read_b128 v[192:195], v150 offset:17408
	global_load_lds_dwordx4 v136, s[58:59]
	ds_read_b128 v[196:199], v150 offset:18432
	ds_read_b128 v[200:203], v150 offset:19456
	ds_read_b128 v[204:207], v150 offset:20480
	ds_read_b128 v[208:211], v150 offset:21504
	ds_read_b128 v[212:215], v150 offset:22528
	ds_read_b128 v[216:219], v150 offset:23552
	s_waitcnt vmcnt(6)
	s_waitcnt lgkmcnt(0)
	s_barrier
	v_mfma_f32_16x16x32_bf16 v[62:65], v[154:157], v[188:191], 0
	v_mfma_f32_16x16x32_bf16 v[62:65], v[158:161], v[192:195], v[62:65]
	v_mfma_f32_16x16x32_bf16 v[58:61], v[168:171], v[192:195], 0
	v_mfma_f32_16x16x32_bf16 v[58:61], v[164:167], v[188:191], v[58:61]
	v_mfma_f32_16x16x32_bf16 v[50:53], v[164:167], v[196:199], 0
	v_mfma_f32_16x16x32_bf16 v[50:53], v[168:171], v[200:203], v[50:53]
	v_mfma_f32_16x16x32_bf16 v[54:57], v[158:161], v[200:203], 0
	v_mfma_f32_16x16x32_bf16 v[54:57], v[154:157], v[196:199], v[54:57]
	v_mfma_f32_16x16x32_bf16 v[38:41], v[154:157], v[204:207], 0
	v_mfma_f32_16x16x32_bf16 v[38:41], v[158:161], v[208:211], v[38:41]
	v_mfma_f32_16x16x32_bf16 v[34:37], v[168:171], v[208:211], 0
	v_mfma_f32_16x16x32_bf16 v[34:37], v[164:167], v[204:207], v[34:37]
	v_mfma_f32_16x16x32_bf16 v[18:21], v[164:167], v[212:215], 0
	v_mfma_f32_16x16x32_bf16 v[18:21], v[168:171], v[216:219], v[18:21]
	v_mfma_f32_16x16x32_bf16 v[22:25], v[158:161], v[216:219], 0
	v_mfma_f32_16x16x32_bf16 v[22:25], v[154:157], v[212:215], v[22:25]
	v_mfma_f32_16x16x32_bf16 v[6:9], v[172:175], v[212:215], 0
	v_mfma_f32_16x16x32_bf16 v[6:9], v[176:179], v[216:219], v[6:9]
	v_mfma_f32_16x16x32_bf16 v[2:5], v[184:187], v[216:219], 0
	v_mfma_f32_16x16x32_bf16 v[2:5], v[180:183], v[212:215], v[2:5]
	v_mfma_f32_16x16x32_bf16 v[10:13], v[180:183], v[204:207], 0
	v_mfma_f32_16x16x32_bf16 v[10:13], v[184:187], v[208:211], v[10:13]
	v_mfma_f32_16x16x32_bf16 v[14:17], v[176:179], v[208:211], 0
	v_mfma_f32_16x16x32_bf16 v[14:17], v[172:175], v[204:207], v[14:17]
	v_mfma_f32_16x16x32_bf16 v[30:33], v[172:175], v[196:199], 0
	v_mfma_f32_16x16x32_bf16 v[30:33], v[176:179], v[200:203], v[30:33]
	v_mfma_f32_16x16x32_bf16 v[26:29], v[184:187], v[200:203], 0
	v_mfma_f32_16x16x32_bf16 v[26:29], v[180:183], v[196:199], v[26:29]
	v_mfma_f32_16x16x32_bf16 v[42:45], v[180:183], v[188:191], 0
	v_mfma_f32_16x16x32_bf16 v[42:45], v[184:187], v[192:195], v[42:45]
	v_mfma_f32_16x16x32_bf16 v[46:49], v[176:179], v[192:195], 0
	v_mfma_f32_16x16x32_bf16 v[46:49], v[172:175], v[188:191], v[46:49]
	s_barrier
	s_mov_b32 m0, s30
	ds_read_b128 v[154:157], v151
	global_load_lds_dwordx4 v130, s[26:27]
	s_mov_b32 m0, s31
	ds_read_b128 v[158:161], v151 offset:1024
	global_load_lds_dwordx4 v134, s[26:27]
	s_add_u32 s26, s26, 0x100000
	s_addc_u32 s27, s27, 0
	s_mov_b32 m0, s33
	ds_read_b128 v[164:167], v151 offset:2048
	global_load_lds_dwordx4 v130, s[26:27]
	s_mov_b32 m0, s34
	ds_read_b128 v[168:171], v151 offset:3072
	global_load_lds_dwordx4 v134, s[26:27]
	ds_read_b128 v[172:175], v152
	ds_read_b128 v[176:179], v152 offset:1024
	ds_read_b128 v[180:183], v152 offset:2048
	ds_read_b128 v[184:187], v152 offset:3072
	ds_read_b128 v[188:191], v150 offset:32768
	ds_read_b128 v[192:195], v150 offset:33792
	ds_read_b128 v[196:199], v150 offset:34816
	ds_read_b128 v[200:203], v150 offset:35840
	ds_read_b128 v[204:207], v150 offset:36864
	ds_read_b128 v[208:211], v150 offset:37888
	ds_read_b128 v[212:215], v150 offset:38912
	ds_read_b128 v[216:219], v150 offset:39936
	s_waitcnt vmcnt(8)
	s_waitcnt lgkmcnt(0)
	s_barrier
	v_mfma_f32_16x16x32_bf16 v[126:129], v[154:157], v[188:191], v[126:129]
	v_mfma_f32_16x16x32_bf16 v[126:129], v[158:161], v[192:195], v[126:129]
	v_mfma_f32_16x16x32_bf16 v[122:125], v[168:171], v[192:195], v[122:125]
	v_mfma_f32_16x16x32_bf16 v[122:125], v[164:167], v[188:191], v[122:125]
	v_mfma_f32_16x16x32_bf16 v[114:117], v[164:167], v[196:199], v[114:117]
	v_mfma_f32_16x16x32_bf16 v[114:117], v[168:171], v[200:203], v[114:117]
	v_mfma_f32_16x16x32_bf16 v[118:121], v[158:161], v[200:203], v[118:121]
	v_mfma_f32_16x16x32_bf16 v[118:121], v[154:157], v[196:199], v[118:121]
	v_mfma_f32_16x16x32_bf16 v[102:105], v[154:157], v[204:207], v[102:105]
	v_mfma_f32_16x16x32_bf16 v[102:105], v[158:161], v[208:211], v[102:105]
	v_mfma_f32_16x16x32_bf16 v[98:101], v[168:171], v[208:211], v[98:101]
	v_mfma_f32_16x16x32_bf16 v[98:101], v[164:167], v[204:207], v[98:101]
	v_mfma_f32_16x16x32_bf16 v[82:85], v[164:167], v[212:215], v[82:85]
	v_mfma_f32_16x16x32_bf16 v[82:85], v[168:171], v[216:219], v[82:85]
	v_mfma_f32_16x16x32_bf16 v[86:89], v[158:161], v[216:219], v[86:89]
	v_mfma_f32_16x16x32_bf16 v[86:89], v[154:157], v[212:215], v[86:89]
	v_mfma_f32_16x16x32_bf16 v[70:73], v[172:175], v[212:215], v[70:73]
	v_mfma_f32_16x16x32_bf16 v[70:73], v[176:179], v[216:219], v[70:73]
	v_mfma_f32_16x16x32_bf16 v[66:69], v[184:187], v[216:219], v[66:69]
	v_mfma_f32_16x16x32_bf16 v[66:69], v[180:183], v[212:215], v[66:69]
	v_mfma_f32_16x16x32_bf16 v[74:77], v[180:183], v[204:207], v[74:77]
	v_mfma_f32_16x16x32_bf16 v[74:77], v[184:187], v[208:211], v[74:77]
	v_mfma_f32_16x16x32_bf16 v[78:81], v[176:179], v[208:211], v[78:81]
	v_mfma_f32_16x16x32_bf16 v[78:81], v[172:175], v[204:207], v[78:81]
	v_mfma_f32_16x16x32_bf16 v[94:97], v[172:175], v[196:199], v[94:97]
	v_mfma_f32_16x16x32_bf16 v[94:97], v[176:179], v[200:203], v[94:97]
	v_mfma_f32_16x16x32_bf16 v[90:93], v[184:187], v[200:203], v[90:93]
	v_mfma_f32_16x16x32_bf16 v[90:93], v[180:183], v[196:199], v[90:93]
	v_mfma_f32_16x16x32_bf16 v[106:109], v[180:183], v[188:191], v[106:109]
	v_mfma_f32_16x16x32_bf16 v[106:109], v[184:187], v[192:195], v[106:109]
	v_mfma_f32_16x16x32_bf16 v[110:113], v[176:179], v[192:195], v[110:113]
	v_mfma_f32_16x16x32_bf16 v[110:113], v[172:175], v[188:191], v[110:113]
	s_barrier
	s_mov_b32 m0, s47
	s_add_u32 s24, s24, 0x80
	s_addc_u32 s25, s25, 0
	global_load_lds_dwordx4 v132, s[24:25]
	s_mov_b32 m0, s48
	ds_read_b128 v[188:191], v150 offset:49152
	global_load_lds_dwordx4 v136, s[24:25]
	s_add_i32 s26, s46, s29
	s_mov_b32 m0, s26
	s_add_u32 s24, s24, 0x100000
	s_addc_u32 s25, s25, 0
	global_load_lds_dwordx4 v132, s[24:25]
	s_add_i32 m0, s26, 0x2000
	ds_read_b128 v[192:195], v150 offset:50176
	global_load_lds_dwordx4 v136, s[24:25]
	ds_read_b128 v[196:199], v150 offset:51200
	ds_read_b128 v[200:203], v150 offset:52224
	ds_read_b128 v[204:207], v150 offset:53248
	ds_read_b128 v[208:211], v150 offset:54272
	ds_read_b128 v[212:215], v150 offset:55296
	ds_read_b128 v[216:219], v150 offset:56320
	s_waitcnt vmcnt(6)
	s_waitcnt lgkmcnt(0)
	s_barrier
	v_mfma_f32_16x16x32_bf16 v[62:65], v[154:157], v[188:191], v[62:65]
	v_mfma_f32_16x16x32_bf16 v[62:65], v[158:161], v[192:195], v[62:65]
	v_mfma_f32_16x16x32_bf16 v[58:61], v[168:171], v[192:195], v[58:61]
	v_mfma_f32_16x16x32_bf16 v[58:61], v[164:167], v[188:191], v[58:61]
	v_mfma_f32_16x16x32_bf16 v[50:53], v[164:167], v[196:199], v[50:53]
	v_mfma_f32_16x16x32_bf16 v[50:53], v[168:171], v[200:203], v[50:53]
	v_mfma_f32_16x16x32_bf16 v[54:57], v[158:161], v[200:203], v[54:57]
	v_mfma_f32_16x16x32_bf16 v[54:57], v[154:157], v[196:199], v[54:57]
	v_mfma_f32_16x16x32_bf16 v[38:41], v[154:157], v[204:207], v[38:41]
	v_mfma_f32_16x16x32_bf16 v[38:41], v[158:161], v[208:211], v[38:41]
	v_mfma_f32_16x16x32_bf16 v[34:37], v[168:171], v[208:211], v[34:37]
	v_mfma_f32_16x16x32_bf16 v[34:37], v[164:167], v[204:207], v[34:37]
	v_mfma_f32_16x16x32_bf16 v[18:21], v[164:167], v[212:215], v[18:21]
	v_mfma_f32_16x16x32_bf16 v[18:21], v[168:171], v[216:219], v[18:21]
	v_mfma_f32_16x16x32_bf16 v[22:25], v[158:161], v[216:219], v[22:25]
	v_mfma_f32_16x16x32_bf16 v[22:25], v[154:157], v[212:215], v[22:25]
	v_mfma_f32_16x16x32_bf16 v[6:9], v[172:175], v[212:215], v[6:9]
	v_mfma_f32_16x16x32_bf16 v[6:9], v[176:179], v[216:219], v[6:9]
	v_mfma_f32_16x16x32_bf16 v[2:5], v[184:187], v[216:219], v[2:5]
	v_mfma_f32_16x16x32_bf16 v[2:5], v[180:183], v[212:215], v[2:5]
	v_mfma_f32_16x16x32_bf16 v[10:13], v[180:183], v[204:207], v[10:13]
	v_mfma_f32_16x16x32_bf16 v[10:13], v[184:187], v[208:211], v[10:13]
	v_mfma_f32_16x16x32_bf16 v[14:17], v[176:179], v[208:211], v[14:17]
	v_mfma_f32_16x16x32_bf16 v[14:17], v[172:175], v[204:207], v[14:17]
	v_mfma_f32_16x16x32_bf16 v[30:33], v[172:175], v[196:199], v[30:33]
	v_mfma_f32_16x16x32_bf16 v[30:33], v[176:179], v[200:203], v[30:33]
	v_mfma_f32_16x16x32_bf16 v[26:29], v[184:187], v[200:203], v[26:29]
	v_mfma_f32_16x16x32_bf16 v[26:29], v[180:183], v[196:199], v[26:29]
	v_mfma_f32_16x16x32_bf16 v[42:45], v[180:183], v[188:191], v[42:45]
	v_mfma_f32_16x16x32_bf16 v[42:45], v[184:187], v[192:195], v[42:45]
	v_mfma_f32_16x16x32_bf16 v[46:49], v[176:179], v[192:195], v[46:49]
	v_mfma_f32_16x16x32_bf16 v[46:49], v[172:175], v[188:191], v[46:49]
	s_barrier
	s_add_i32 s56, s56, 2
	s_add_u32 s22, s22, 0x100
	s_addc_u32 s23, s23, 0
	s_add_u32 s54, s54, 0x100
	s_addc_u32 s55, s55, 0
.LBB0_272:
	s_add_u32 s58, s22, 0xfff00000
	s_addc_u32 s59, s23, -1
	s_mov_b32 m0, s36
	ds_read_b128 v[154:157], v148
	global_load_lds_dwordx4 v130, s[58:59]
	s_mov_b32 m0, s37
	ds_read_b128 v[158:161], v148 offset:1024
	global_load_lds_dwordx4 v134, s[58:59]
	s_mov_b32 m0, s40
	ds_read_b128 v[164:167], v148 offset:2048
	global_load_lds_dwordx4 v142, s[22:23]
	s_mov_b32 m0, s41
	ds_read_b128 v[168:171], v148 offset:3072
	global_load_lds_dwordx4 v144, s[22:23]
	ds_read_b128 v[172:175], v149
	ds_read_b128 v[176:179], v149 offset:1024
	ds_read_b128 v[180:183], v149 offset:2048
	ds_read_b128 v[184:187], v149 offset:3072
	s_add_u32 s24, s22, 0xfff00080
	s_addc_u32 s25, s23, -1
	s_cmp_eq_u32 s56, 60
	s_cselect_b32 s27, s51, s25
	s_cselect_b32 s26, s52, s24
	s_cselect_b32 s25, s7, s55
	s_cselect_b32 s24, s53, s54
	ds_read_b128 v[188:191], v150
	ds_read_b128 v[192:195], v150 offset:1024
	ds_read_b128 v[196:199], v150 offset:2048
	ds_read_b128 v[200:203], v150 offset:3072
	ds_read_b128 v[204:207], v150 offset:4096
	ds_read_b128 v[208:211], v150 offset:5120
	ds_read_b128 v[212:215], v150 offset:6144
	ds_read_b128 v[216:219], v150 offset:7168
	s_waitcnt vmcnt(8)
	s_waitcnt lgkmcnt(0)
	s_barrier
	v_mfma_f32_16x16x32_bf16 v[126:129], v[154:157], v[188:191], v[126:129]
	v_mfma_f32_16x16x32_bf16 v[126:129], v[158:161], v[192:195], v[126:129]
	v_mfma_f32_16x16x32_bf16 v[122:125], v[168:171], v[192:195], v[122:125]
	v_mfma_f32_16x16x32_bf16 v[122:125], v[164:167], v[188:191], v[122:125]
	v_mfma_f32_16x16x32_bf16 v[114:117], v[164:167], v[196:199], v[114:117]
	v_mfma_f32_16x16x32_bf16 v[114:117], v[168:171], v[200:203], v[114:117]
	v_mfma_f32_16x16x32_bf16 v[118:121], v[158:161], v[200:203], v[118:121]
	v_mfma_f32_16x16x32_bf16 v[118:121], v[154:157], v[196:199], v[118:121]
	v_mfma_f32_16x16x32_bf16 v[102:105], v[154:157], v[204:207], v[102:105]
	v_mfma_f32_16x16x32_bf16 v[102:105], v[158:161], v[208:211], v[102:105]
	v_mfma_f32_16x16x32_bf16 v[98:101], v[168:171], v[208:211], v[98:101]
	v_mfma_f32_16x16x32_bf16 v[98:101], v[164:167], v[204:207], v[98:101]
	v_mfma_f32_16x16x32_bf16 v[82:85], v[164:167], v[212:215], v[82:85]
	v_mfma_f32_16x16x32_bf16 v[82:85], v[168:171], v[216:219], v[82:85]
	v_mfma_f32_16x16x32_bf16 v[86:89], v[158:161], v[216:219], v[86:89]
	v_mfma_f32_16x16x32_bf16 v[86:89], v[154:157], v[212:215], v[86:89]
	v_mfma_f32_16x16x32_bf16 v[70:73], v[172:175], v[212:215], v[70:73]
	v_mfma_f32_16x16x32_bf16 v[70:73], v[176:179], v[216:219], v[70:73]
	v_mfma_f32_16x16x32_bf16 v[66:69], v[184:187], v[216:219], v[66:69]
	v_mfma_f32_16x16x32_bf16 v[66:69], v[180:183], v[212:215], v[66:69]
	v_mfma_f32_16x16x32_bf16 v[74:77], v[180:183], v[204:207], v[74:77]
	v_mfma_f32_16x16x32_bf16 v[74:77], v[184:187], v[208:211], v[74:77]
	v_mfma_f32_16x16x32_bf16 v[78:81], v[176:179], v[208:211], v[78:81]
	v_mfma_f32_16x16x32_bf16 v[78:81], v[172:175], v[204:207], v[78:81]
	v_mfma_f32_16x16x32_bf16 v[94:97], v[172:175], v[196:199], v[94:97]
	v_mfma_f32_16x16x32_bf16 v[94:97], v[176:179], v[200:203], v[94:97]
	v_mfma_f32_16x16x32_bf16 v[90:93], v[184:187], v[200:203], v[90:93]
	v_mfma_f32_16x16x32_bf16 v[90:93], v[180:183], v[196:199], v[90:93]
	v_mfma_f32_16x16x32_bf16 v[106:109], v[180:183], v[188:191], v[106:109]
	v_mfma_f32_16x16x32_bf16 v[106:109], v[184:187], v[192:195], v[106:109]
	v_mfma_f32_16x16x32_bf16 v[110:113], v[176:179], v[192:195], v[110:113]
	v_mfma_f32_16x16x32_bf16 v[110:113], v[172:175], v[188:191], v[110:113]
	s_barrier
	s_mov_b32 m0, s42
	s_add_u32 s58, s24, 0x100000
	global_load_lds_dwordx4 v132, s[24:25]
	s_mov_b32 m0, s43
	s_addc_u32 s59, s25, 0
	global_load_lds_dwordx4 v136, s[24:25]
	s_mov_b32 m0, s44
	ds_read_b128 v[188:191], v150 offset:16384
	global_load_lds_dwordx4 v132, s[58:59]
	s_mov_b32 m0, s45
	ds_read_b128 v[192:195], v150 offset:17408
	global_load_lds_dwordx4 v136, s[58:59]
	ds_read_b128 v[196:199], v150 offset:18432
	ds_read_b128 v[200:203], v150 offset:19456
	ds_read_b128 v[204:207], v150 offset:20480
	ds_read_b128 v[208:211], v150 offset:21504
	ds_read_b128 v[212:215], v150 offset:22528
	ds_read_b128 v[216:219], v150 offset:23552
	s_waitcnt vmcnt(6)
	s_waitcnt lgkmcnt(0)
	s_barrier
	v_mfma_f32_16x16x32_bf16 v[62:65], v[154:157], v[188:191], v[62:65]
	v_mfma_f32_16x16x32_bf16 v[62:65], v[158:161], v[192:195], v[62:65]
	v_mfma_f32_16x16x32_bf16 v[58:61], v[168:171], v[192:195], v[58:61]
	v_mfma_f32_16x16x32_bf16 v[58:61], v[164:167], v[188:191], v[58:61]
	v_mfma_f32_16x16x32_bf16 v[50:53], v[164:167], v[196:199], v[50:53]
	v_mfma_f32_16x16x32_bf16 v[50:53], v[168:171], v[200:203], v[50:53]
	v_mfma_f32_16x16x32_bf16 v[54:57], v[158:161], v[200:203], v[54:57]
	v_mfma_f32_16x16x32_bf16 v[54:57], v[154:157], v[196:199], v[54:57]
	v_mfma_f32_16x16x32_bf16 v[38:41], v[154:157], v[204:207], v[38:41]
	v_mfma_f32_16x16x32_bf16 v[38:41], v[158:161], v[208:211], v[38:41]
	v_mfma_f32_16x16x32_bf16 v[34:37], v[168:171], v[208:211], v[34:37]
	v_mfma_f32_16x16x32_bf16 v[34:37], v[164:167], v[204:207], v[34:37]
	v_mfma_f32_16x16x32_bf16 v[18:21], v[164:167], v[212:215], v[18:21]
	v_mfma_f32_16x16x32_bf16 v[18:21], v[168:171], v[216:219], v[18:21]
	v_mfma_f32_16x16x32_bf16 v[22:25], v[158:161], v[216:219], v[22:25]
	v_mfma_f32_16x16x32_bf16 v[22:25], v[154:157], v[212:215], v[22:25]
	v_mfma_f32_16x16x32_bf16 v[6:9], v[172:175], v[212:215], v[6:9]
	v_mfma_f32_16x16x32_bf16 v[6:9], v[176:179], v[216:219], v[6:9]
	v_mfma_f32_16x16x32_bf16 v[2:5], v[184:187], v[216:219], v[2:5]
	v_mfma_f32_16x16x32_bf16 v[2:5], v[180:183], v[212:215], v[2:5]
	v_mfma_f32_16x16x32_bf16 v[10:13], v[180:183], v[204:207], v[10:13]
	v_mfma_f32_16x16x32_bf16 v[10:13], v[184:187], v[208:211], v[10:13]
	v_mfma_f32_16x16x32_bf16 v[14:17], v[176:179], v[208:211], v[14:17]
	v_mfma_f32_16x16x32_bf16 v[14:17], v[172:175], v[204:207], v[14:17]
	v_mfma_f32_16x16x32_bf16 v[30:33], v[172:175], v[196:199], v[30:33]
	v_mfma_f32_16x16x32_bf16 v[30:33], v[176:179], v[200:203], v[30:33]
	v_mfma_f32_16x16x32_bf16 v[26:29], v[184:187], v[200:203], v[26:29]
	v_mfma_f32_16x16x32_bf16 v[26:29], v[180:183], v[196:199], v[26:29]
	v_mfma_f32_16x16x32_bf16 v[42:45], v[180:183], v[188:191], v[42:45]
	v_mfma_f32_16x16x32_bf16 v[42:45], v[184:187], v[192:195], v[42:45]
	v_mfma_f32_16x16x32_bf16 v[46:49], v[176:179], v[192:195], v[46:49]
	v_mfma_f32_16x16x32_bf16 v[46:49], v[172:175], v[188:191], v[46:49]
	s_barrier
	s_mov_b32 m0, s30
	ds_read_b128 v[154:157], v151
	global_load_lds_dwordx4 v130, s[26:27]
	s_mov_b32 m0, s31
	ds_read_b128 v[158:161], v151 offset:1024
	global_load_lds_dwordx4 v134, s[26:27]
	s_add_u32 s26, s26, 0x100000
	s_addc_u32 s27, s27, 0
	s_mov_b32 m0, s33
	ds_read_b128 v[164:167], v151 offset:2048
	global_load_lds_dwordx4 v130, s[26:27]
	s_mov_b32 m0, s34
	ds_read_b128 v[168:171], v151 offset:3072
	global_load_lds_dwordx4 v134, s[26:27]
	ds_read_b128 v[172:175], v152
	ds_read_b128 v[176:179], v152 offset:1024
	ds_read_b128 v[180:183], v152 offset:2048
	ds_read_b128 v[184:187], v152 offset:3072
	ds_read_b128 v[188:191], v150 offset:32768
	ds_read_b128 v[192:195], v150 offset:33792
	ds_read_b128 v[196:199], v150 offset:34816
	ds_read_b128 v[200:203], v150 offset:35840
	ds_read_b128 v[204:207], v150 offset:36864
	ds_read_b128 v[208:211], v150 offset:37888
	ds_read_b128 v[212:215], v150 offset:38912
	ds_read_b128 v[216:219], v150 offset:39936
	s_waitcnt vmcnt(8)
	s_waitcnt lgkmcnt(0)
	s_barrier
	v_mfma_f32_16x16x32_bf16 v[126:129], v[154:157], v[188:191], v[126:129]
	v_mfma_f32_16x16x32_bf16 v[126:129], v[158:161], v[192:195], v[126:129]
	v_mfma_f32_16x16x32_bf16 v[122:125], v[168:171], v[192:195], v[122:125]
	v_mfma_f32_16x16x32_bf16 v[122:125], v[164:167], v[188:191], v[122:125]
	v_mfma_f32_16x16x32_bf16 v[114:117], v[164:167], v[196:199], v[114:117]
	v_mfma_f32_16x16x32_bf16 v[114:117], v[168:171], v[200:203], v[114:117]
	v_mfma_f32_16x16x32_bf16 v[118:121], v[158:161], v[200:203], v[118:121]
	v_mfma_f32_16x16x32_bf16 v[118:121], v[154:157], v[196:199], v[118:121]
	v_mfma_f32_16x16x32_bf16 v[102:105], v[154:157], v[204:207], v[102:105]
	v_mfma_f32_16x16x32_bf16 v[102:105], v[158:161], v[208:211], v[102:105]
	v_mfma_f32_16x16x32_bf16 v[98:101], v[168:171], v[208:211], v[98:101]
	v_mfma_f32_16x16x32_bf16 v[98:101], v[164:167], v[204:207], v[98:101]
	v_mfma_f32_16x16x32_bf16 v[82:85], v[164:167], v[212:215], v[82:85]
	v_mfma_f32_16x16x32_bf16 v[82:85], v[168:171], v[216:219], v[82:85]
	v_mfma_f32_16x16x32_bf16 v[86:89], v[158:161], v[216:219], v[86:89]
	v_mfma_f32_16x16x32_bf16 v[86:89], v[154:157], v[212:215], v[86:89]
	v_mfma_f32_16x16x32_bf16 v[70:73], v[172:175], v[212:215], v[70:73]
	v_mfma_f32_16x16x32_bf16 v[70:73], v[176:179], v[216:219], v[70:73]
	v_mfma_f32_16x16x32_bf16 v[66:69], v[184:187], v[216:219], v[66:69]
	v_mfma_f32_16x16x32_bf16 v[66:69], v[180:183], v[212:215], v[66:69]
	v_mfma_f32_16x16x32_bf16 v[74:77], v[180:183], v[204:207], v[74:77]
	v_mfma_f32_16x16x32_bf16 v[74:77], v[184:187], v[208:211], v[74:77]
	v_mfma_f32_16x16x32_bf16 v[78:81], v[176:179], v[208:211], v[78:81]
	v_mfma_f32_16x16x32_bf16 v[78:81], v[172:175], v[204:207], v[78:81]
	v_mfma_f32_16x16x32_bf16 v[94:97], v[172:175], v[196:199], v[94:97]
	v_mfma_f32_16x16x32_bf16 v[94:97], v[176:179], v[200:203], v[94:97]
	v_mfma_f32_16x16x32_bf16 v[90:93], v[184:187], v[200:203], v[90:93]
	v_mfma_f32_16x16x32_bf16 v[90:93], v[180:183], v[196:199], v[90:93]
	v_mfma_f32_16x16x32_bf16 v[106:109], v[180:183], v[188:191], v[106:109]
	v_mfma_f32_16x16x32_bf16 v[106:109], v[184:187], v[192:195], v[106:109]
	v_mfma_f32_16x16x32_bf16 v[110:113], v[176:179], v[192:195], v[110:113]
	v_mfma_f32_16x16x32_bf16 v[110:113], v[172:175], v[188:191], v[110:113]
	s_barrier
	s_mov_b32 m0, s47
	s_add_u32 s24, s24, 0x80
	s_addc_u32 s25, s25, 0
	global_load_lds_dwordx4 v132, s[24:25]
	s_mov_b32 m0, s48
	ds_read_b128 v[188:191], v150 offset:49152
	global_load_lds_dwordx4 v136, s[24:25]
	s_add_i32 s26, s46, s29
	s_mov_b32 m0, s26
	s_add_u32 s24, s24, 0x100000
	s_addc_u32 s25, s25, 0
	global_load_lds_dwordx4 v132, s[24:25]
	s_add_i32 m0, s26, 0x2000
	ds_read_b128 v[192:195], v150 offset:50176
	global_load_lds_dwordx4 v136, s[24:25]
	ds_read_b128 v[196:199], v150 offset:51200
	ds_read_b128 v[200:203], v150 offset:52224
	ds_read_b128 v[204:207], v150 offset:53248
	ds_read_b128 v[208:211], v150 offset:54272
	ds_read_b128 v[212:215], v150 offset:55296
	ds_read_b128 v[216:219], v150 offset:56320
	s_waitcnt vmcnt(6)
	s_waitcnt lgkmcnt(0)
	s_barrier
	v_mfma_f32_16x16x32_bf16 v[62:65], v[154:157], v[188:191], v[62:65]
	v_mfma_f32_16x16x32_bf16 v[62:65], v[158:161], v[192:195], v[62:65]
	v_mfma_f32_16x16x32_bf16 v[58:61], v[168:171], v[192:195], v[58:61]
	v_mfma_f32_16x16x32_bf16 v[58:61], v[164:167], v[188:191], v[58:61]
	v_mfma_f32_16x16x32_bf16 v[50:53], v[164:167], v[196:199], v[50:53]
	v_mfma_f32_16x16x32_bf16 v[50:53], v[168:171], v[200:203], v[50:53]
	v_mfma_f32_16x16x32_bf16 v[54:57], v[158:161], v[200:203], v[54:57]
	v_mfma_f32_16x16x32_bf16 v[54:57], v[154:157], v[196:199], v[54:57]
	v_mfma_f32_16x16x32_bf16 v[38:41], v[154:157], v[204:207], v[38:41]
	v_mfma_f32_16x16x32_bf16 v[38:41], v[158:161], v[208:211], v[38:41]
	v_mfma_f32_16x16x32_bf16 v[34:37], v[168:171], v[208:211], v[34:37]
	v_mfma_f32_16x16x32_bf16 v[34:37], v[164:167], v[204:207], v[34:37]
	v_mfma_f32_16x16x32_bf16 v[18:21], v[164:167], v[212:215], v[18:21]
	v_mfma_f32_16x16x32_bf16 v[18:21], v[168:171], v[216:219], v[18:21]
	v_mfma_f32_16x16x32_bf16 v[22:25], v[158:161], v[216:219], v[22:25]
	v_mfma_f32_16x16x32_bf16 v[22:25], v[154:157], v[212:215], v[22:25]
	v_mfma_f32_16x16x32_bf16 v[6:9], v[172:175], v[212:215], v[6:9]
	v_mfma_f32_16x16x32_bf16 v[6:9], v[176:179], v[216:219], v[6:9]
	v_mfma_f32_16x16x32_bf16 v[2:5], v[184:187], v[216:219], v[2:5]
	v_mfma_f32_16x16x32_bf16 v[2:5], v[180:183], v[212:215], v[2:5]
	v_mfma_f32_16x16x32_bf16 v[10:13], v[180:183], v[204:207], v[10:13]
	v_mfma_f32_16x16x32_bf16 v[10:13], v[184:187], v[208:211], v[10:13]
	v_mfma_f32_16x16x32_bf16 v[14:17], v[176:179], v[208:211], v[14:17]
	v_mfma_f32_16x16x32_bf16 v[14:17], v[172:175], v[204:207], v[14:17]
	v_mfma_f32_16x16x32_bf16 v[30:33], v[172:175], v[196:199], v[30:33]
	v_mfma_f32_16x16x32_bf16 v[30:33], v[176:179], v[200:203], v[30:33]
	v_mfma_f32_16x16x32_bf16 v[26:29], v[184:187], v[200:203], v[26:29]
	v_mfma_f32_16x16x32_bf16 v[26:29], v[180:183], v[196:199], v[26:29]
	v_mfma_f32_16x16x32_bf16 v[42:45], v[180:183], v[188:191], v[42:45]
	v_mfma_f32_16x16x32_bf16 v[42:45], v[184:187], v[192:195], v[42:45]
	v_mfma_f32_16x16x32_bf16 v[46:49], v[176:179], v[192:195], v[46:49]
	v_mfma_f32_16x16x32_bf16 v[46:49], v[172:175], v[188:191], v[46:49]
	s_barrier
	s_add_i32 s56, s56, 2
	s_add_u32 s22, s22, 0x100
	s_addc_u32 s23, s23, 0
	s_add_u32 s54, s54, 0x100
	s_addc_u32 s55, s55, 0
	s_cmp_gt_u32 s56, 61
	s_cbranch_scc0 .LBB0_272
	s_setprio 0
	s_and_b64 vcc, exec, s[16:17]
	s_cbranch_vccz .LBB0_277
	s_barrier
	v_lshl_add_u32 v138, s50, 8, v1
	s_cmp_gt_i32 s49, 63
	s_mov_b64 s[22:23], -1
	s_cbranch_scc1 .LBB0_278

.LBB0_1008:
	s_add_i32 s37, s37, 1
	s_lshl_b32 s7, s37, 5
	s_add_i32 s7, s7, s3
	s_ashr_i32 s19, s7, 2
	s_cmp_lt_i32 s19, 16
	s_mov_b64 s[24:25], s[8:9]
	s_cselect_b64 s[8:9], -1, 0
	s_cmp_lt_i32 s7, 64
	s_mov_b64 s[22:23], s[10:11]
	s_cselect_b64 s[10:11], -1, 0
	s_and_b64 s[20:21], s[10:11], exec
	s_mov_b32 s46, s18
	s_cselect_b32 s18, s31, s18
	s_mov_b32 s45, s6
	s_cselect_b32 s6, s19, s6
	s_ashr_i32 s19, s18, 31
	s_and_b64 s[20:21], s[10:11], s[8:9]
	s_lshl_b64 s[8:9], s[18:19], 21
	v_readlane_b32 s0, v250, 46
	v_readlane_b32 s1, v250, 47
	s_add_u32 s10, s0, s8
	s_addc_u32 s11, s1, s9
	s_and_b64 s[8:9], s[20:21], exec
	s_cselect_b32 s19, s11, s23
	s_cselect_b32 s47, s10, s22
	s_ashr_i32 s7, s6, 31
	s_lshl_b64 s[8:9], s[6:7], 21
	v_readlane_b32 s0, v250, 40
	v_readlane_b32 s1, v250, 41
	s_add_u32 s8, s0, s8
	s_addc_u32 s9, s1, s9
	s_and_b64 s[26:27], s[20:21], exec
	s_cselect_b32 s7, s9, s25
	s_cselect_b32 s48, s8, s24
	s_add_u32 s22, s22, 0x100080
	s_addc_u32 s23, s23, 0
	s_add_u32 s49, s24, 0x100
	s_addc_u32 s50, s25, 0
	s_mov_b32 s51, -2
	s_and_b64 vcc, exec, s[12:13]
	s_cbranch_vccz .Lsp_1
	s_setprio 1
.Lsp_1:
	s_waitcnt lgkmcnt(0)
	ds_read_b128 v[142:145], v155
	ds_read_b128 v[158:161], v155 offset:1024
	ds_read_b128 v[168:171], v155 offset:2048
	ds_read_b128 v[176:179], v155 offset:3072
	ds_read_b128 v[180:183], v156
	ds_read_b128 v[184:187], v156 offset:1024
	ds_read_b128 v[188:191], v156 offset:2048
	ds_read_b128 v[192:195], v156 offset:3072
	s_add_u32 s24, s22, 0xfff00080
	s_addc_u32 s25, s23, -1
	s_cmp_eq_u32 s51, 60
	s_cselect_b32 s27, s19, s25
	s_cselect_b32 s26, s47, s24
	s_cselect_b32 s25, s7, s50
	s_cselect_b32 s24, s48, s49
	s_mov_b32 m0, s40
	ds_read_b128 v[202:205], v157
	ds_read_b128 v[206:209], v157 offset:1024
	ds_read_b128 v[210:213], v157 offset:2048
	ds_read_b128 v[214:217], v157 offset:3072
	ds_read_b128 v[218:221], v157 offset:4096
	ds_read_b128 v[222:225], v157 offset:5120
	ds_read_b128 v[226:229], v157 offset:6144
	ds_read_b128 v[230:233], v157 offset:7168
	global_load_lds_dwordx4 v138, s[22:23]
	s_mov_b32 m0, s41
	s_nop 0
	global_load_lds_dwordx4 v140, s[22:23]
	s_waitcnt vmcnt(8)
	s_waitcnt lgkmcnt(0)
	s_barrier
	v_mfma_f32_16x16x32_bf16 v[126:129], v[142:145], v[202:205], 0
	v_mfma_f32_16x16x32_bf16 v[126:129], v[158:161], v[206:209], v[126:129]
	v_mfma_f32_16x16x32_bf16 v[122:125], v[176:179], v[206:209], 0
	v_mfma_f32_16x16x32_bf16 v[122:125], v[168:171], v[202:205], v[122:125]
	v_mfma_f32_16x16x32_bf16 v[106:109], v[168:171], v[210:213], 0
	v_mfma_f32_16x16x32_bf16 v[106:109], v[176:179], v[214:217], v[106:109]
	v_mfma_f32_16x16x32_bf16 v[110:113], v[158:161], v[214:217], 0
	v_mfma_f32_16x16x32_bf16 v[110:113], v[142:145], v[210:213], v[110:113]
	v_mfma_f32_16x16x32_bf16 v[94:97], v[142:145], v[218:221], 0
	v_mfma_f32_16x16x32_bf16 v[94:97], v[158:161], v[222:225], v[94:97]
	v_mfma_f32_16x16x32_bf16 v[90:93], v[176:179], v[222:225], 0
	v_mfma_f32_16x16x32_bf16 v[90:93], v[168:171], v[218:221], v[90:93]
	v_mfma_f32_16x16x32_bf16 v[74:77], v[168:171], v[226:229], 0
	v_mfma_f32_16x16x32_bf16 v[74:77], v[176:179], v[230:233], v[74:77]
	v_mfma_f32_16x16x32_bf16 v[78:81], v[158:161], v[230:233], 0
	v_mfma_f32_16x16x32_bf16 v[78:81], v[142:145], v[226:229], v[78:81]
	v_mfma_f32_16x16x32_bf16 v[70:73], v[180:183], v[226:229], 0
	v_mfma_f32_16x16x32_bf16 v[70:73], v[184:187], v[230:233], v[70:73]
	v_mfma_f32_16x16x32_bf16 v[66:69], v[192:195], v[230:233], 0
	v_mfma_f32_16x16x32_bf16 v[66:69], v[188:191], v[226:229], v[66:69]
	v_mfma_f32_16x16x32_bf16 v[82:85], v[188:191], v[218:221], 0
	v_mfma_f32_16x16x32_bf16 v[82:85], v[192:195], v[222:225], v[82:85]
	v_mfma_f32_16x16x32_bf16 v[86:89], v[184:187], v[222:225], 0
	v_mfma_f32_16x16x32_bf16 v[86:89], v[180:183], v[218:221], v[86:89]
	v_mfma_f32_16x16x32_bf16 v[102:105], v[180:183], v[210:213], 0
	v_mfma_f32_16x16x32_bf16 v[102:105], v[184:187], v[214:217], v[102:105]
	v_mfma_f32_16x16x32_bf16 v[98:101], v[192:195], v[214:217], 0
	v_mfma_f32_16x16x32_bf16 v[98:101], v[188:191], v[210:213], v[98:101]
	v_mfma_f32_16x16x32_bf16 v[114:117], v[188:191], v[202:205], 0
	v_mfma_f32_16x16x32_bf16 v[114:117], v[192:195], v[206:209], v[114:117]
	v_mfma_f32_16x16x32_bf16 v[118:121], v[184:187], v[206:209], 0
	v_mfma_f32_16x16x32_bf16 v[118:121], v[180:183], v[202:205], v[118:121]
	s_barrier
	s_mov_b32 m0, s42
	s_add_u32 s52, s24, 0x100000
	ds_read_b128 v[202:205], v157 offset:16384
	ds_read_b128 v[206:209], v157 offset:17408
	ds_read_b128 v[210:213], v157 offset:18432
	ds_read_b128 v[214:217], v157 offset:19456
	ds_read_b128 v[218:221], v157 offset:20480
	ds_read_b128 v[222:225], v157 offset:21504
	ds_read_b128 v[226:229], v157 offset:22528
	ds_read_b128 v[230:233], v157 offset:23552
	global_load_lds_dwordx4 v132, s[24:25]
	s_mov_b32 m0, s43
	s_addc_u32 s53, s25, 0
	global_load_lds_dwordx4 v136, s[24:25]
	s_mov_b32 m0, s44
	s_nop 0
	global_load_lds_dwordx4 v132, s[52:53]
	s_add_i32 m0, s44, 0x2000
	s_nop 0
	global_load_lds_dwordx4 v136, s[52:53]
	s_mov_b32 m0, s33
	s_nop 0
	global_load_lds_dwordx4 v130, s[26:27]
	s_mov_b32 m0, s34
	s_nop 0
	global_load_lds_dwordx4 v134, s[26:27]
	s_waitcnt vmcnt(8)
	s_waitcnt lgkmcnt(0)
	s_barrier
	v_mfma_f32_16x16x32_bf16 v[62:65], v[142:145], v[202:205], 0
	v_mfma_f32_16x16x32_bf16 v[62:65], v[158:161], v[206:209], v[62:65]
	v_mfma_f32_16x16x32_bf16 v[58:61], v[176:179], v[206:209], 0
	v_mfma_f32_16x16x32_bf16 v[58:61], v[168:171], v[202:205], v[58:61]
	v_mfma_f32_16x16x32_bf16 v[42:45], v[168:171], v[210:213], 0
	v_mfma_f32_16x16x32_bf16 v[42:45], v[176:179], v[214:217], v[42:45]
	v_mfma_f32_16x16x32_bf16 v[46:49], v[158:161], v[214:217], 0
	v_mfma_f32_16x16x32_bf16 v[46:49], v[142:145], v[210:213], v[46:49]
	v_mfma_f32_16x16x32_bf16 v[30:33], v[142:145], v[218:221], 0
	v_mfma_f32_16x16x32_bf16 v[30:33], v[158:161], v[222:225], v[30:33]
	v_mfma_f32_16x16x32_bf16 v[26:29], v[176:179], v[222:225], 0
	v_mfma_f32_16x16x32_bf16 v[26:29], v[168:171], v[218:221], v[26:29]
	v_mfma_f32_16x16x32_bf16 v[10:13], v[168:171], v[226:229], 0
	v_mfma_f32_16x16x32_bf16 v[10:13], v[176:179], v[230:233], v[10:13]
	v_mfma_f32_16x16x32_bf16 v[14:17], v[158:161], v[230:233], 0
	v_mfma_f32_16x16x32_bf16 v[14:17], v[142:145], v[226:229], v[14:17]
	v_mfma_f32_16x16x32_bf16 v[6:9], v[180:183], v[226:229], 0
	v_mfma_f32_16x16x32_bf16 v[6:9], v[184:187], v[230:233], v[6:9]
	v_mfma_f32_16x16x32_bf16 v[2:5], v[192:195], v[230:233], 0
	v_mfma_f32_16x16x32_bf16 v[2:5], v[188:191], v[226:229], v[2:5]
	v_mfma_f32_16x16x32_bf16 v[18:21], v[188:191], v[218:221], 0
	v_mfma_f32_16x16x32_bf16 v[18:21], v[192:195], v[222:225], v[18:21]
	v_mfma_f32_16x16x32_bf16 v[22:25], v[184:187], v[222:225], 0
	v_mfma_f32_16x16x32_bf16 v[22:25], v[180:183], v[218:221], v[22:25]
	v_mfma_f32_16x16x32_bf16 v[38:41], v[180:183], v[210:213], 0
	v_mfma_f32_16x16x32_bf16 v[38:41], v[184:187], v[214:217], v[38:41]
	v_mfma_f32_16x16x32_bf16 v[34:37], v[192:195], v[214:217], 0
	v_mfma_f32_16x16x32_bf16 v[34:37], v[188:191], v[210:213], v[34:37]
	v_mfma_f32_16x16x32_bf16 v[50:53], v[188:191], v[202:205], 0
	v_mfma_f32_16x16x32_bf16 v[50:53], v[192:195], v[206:209], v[50:53]
	v_mfma_f32_16x16x32_bf16 v[54:57], v[184:187], v[206:209], 0
	v_mfma_f32_16x16x32_bf16 v[54:57], v[180:183], v[202:205], v[54:57]
	s_barrier
	s_add_i32 s52, 0, 0x18000
	v_add_u32_e32 v166, s52, v153
	s_add_i32 s53, 0, 0x1c000
	ds_read_b128 v[142:145], v166
	ds_read_b128 v[158:161], v166 offset:1024
	ds_read_b128 v[168:171], v166 offset:2048
	ds_read_b128 v[176:179], v166 offset:3072
	v_add_u32_e32 v166, s53, v153
	ds_read_b128 v[180:183], v166
	ds_read_b128 v[184:187], v166 offset:1024
	ds_read_b128 v[188:191], v166 offset:2048
	ds_read_b128 v[192:195], v166 offset:3072
	s_add_u32 s26, s26, 0x100000
	s_addc_u32 s27, s27, 0
	s_mov_b32 m0, s35
	ds_read_b128 v[202:205], v157 offset:32768
	ds_read_b128 v[206:209], v157 offset:33792
	ds_read_b128 v[210:213], v157 offset:34816
	ds_read_b128 v[214:217], v157 offset:35840
	ds_read_b128 v[218:221], v157 offset:36864
	ds_read_b128 v[222:225], v157 offset:37888
	ds_read_b128 v[226:229], v157 offset:38912
	ds_read_b128 v[230:233], v157 offset:39936
	global_load_lds_dwordx4 v130, s[26:27]
	s_mov_b32 m0, s36
	s_nop 0
	global_load_lds_dwordx4 v134, s[26:27]
	s_waitcnt vmcnt(8)
	s_waitcnt lgkmcnt(0)
	s_barrier
	v_mfma_f32_16x16x32_bf16 v[126:129], v[142:145], v[202:205], v[126:129]
	v_mfma_f32_16x16x32_bf16 v[126:129], v[158:161], v[206:209], v[126:129]
	v_mfma_f32_16x16x32_bf16 v[122:125], v[176:179], v[206:209], v[122:125]
	v_mfma_f32_16x16x32_bf16 v[122:125], v[168:171], v[202:205], v[122:125]
	v_mfma_f32_16x16x32_bf16 v[106:109], v[168:171], v[210:213], v[106:109]
	v_mfma_f32_16x16x32_bf16 v[106:109], v[176:179], v[214:217], v[106:109]
	v_mfma_f32_16x16x32_bf16 v[110:113], v[158:161], v[214:217], v[110:113]
	v_mfma_f32_16x16x32_bf16 v[110:113], v[142:145], v[210:213], v[110:113]
	v_mfma_f32_16x16x32_bf16 v[94:97], v[142:145], v[218:221], v[94:97]
	v_mfma_f32_16x16x32_bf16 v[94:97], v[158:161], v[222:225], v[94:97]
	v_mfma_f32_16x16x32_bf16 v[90:93], v[176:179], v[222:225], v[90:93]
	v_mfma_f32_16x16x32_bf16 v[90:93], v[168:171], v[218:221], v[90:93]
	v_mfma_f32_16x16x32_bf16 v[74:77], v[168:171], v[226:229], v[74:77]
	v_mfma_f32_16x16x32_bf16 v[74:77], v[176:179], v[230:233], v[74:77]
	v_mfma_f32_16x16x32_bf16 v[78:81], v[158:161], v[230:233], v[78:81]
	v_mfma_f32_16x16x32_bf16 v[78:81], v[142:145], v[226:229], v[78:81]
	v_mfma_f32_16x16x32_bf16 v[70:73], v[180:183], v[226:229], v[70:73]
	v_mfma_f32_16x16x32_bf16 v[70:73], v[184:187], v[230:233], v[70:73]
	v_mfma_f32_16x16x32_bf16 v[66:69], v[192:195], v[230:233], v[66:69]
	v_mfma_f32_16x16x32_bf16 v[66:69], v[188:191], v[226:229], v[66:69]
	v_mfma_f32_16x16x32_bf16 v[82:85], v[188:191], v[218:221], v[82:85]
	v_mfma_f32_16x16x32_bf16 v[82:85], v[192:195], v[222:225], v[82:85]
	v_mfma_f32_16x16x32_bf16 v[86:89], v[184:187], v[222:225], v[86:89]
	v_mfma_f32_16x16x32_bf16 v[86:89], v[180:183], v[218:221], v[86:89]
	v_mfma_f32_16x16x32_bf16 v[102:105], v[180:183], v[210:213], v[102:105]
	v_mfma_f32_16x16x32_bf16 v[102:105], v[184:187], v[214:217], v[102:105]
	v_mfma_f32_16x16x32_bf16 v[98:101], v[192:195], v[214:217], v[98:101]
	v_mfma_f32_16x16x32_bf16 v[98:101], v[188:191], v[210:213], v[98:101]
	v_mfma_f32_16x16x32_bf16 v[114:117], v[188:191], v[202:205], v[114:117]
	v_mfma_f32_16x16x32_bf16 v[114:117], v[192:195], v[206:209], v[114:117]
	v_mfma_f32_16x16x32_bf16 v[118:121], v[184:187], v[206:209], v[118:121]
	v_mfma_f32_16x16x32_bf16 v[118:121], v[180:183], v[202:205], v[118:121]
	s_barrier
	s_add_u32 s98, s26, 0xfff00080
	s_addc_u32 s99, s27, -1
	s_add_u32 s24, s24, 0x80
	s_addc_u32 s25, s25, 0
	s_add_i32 s26, s52, s30
	s_mov_b32 m0, s26
	ds_read_b128 v[202:205], v157 offset:49152
	ds_read_b128 v[206:209], v157 offset:50176
	ds_read_b128 v[210:213], v157 offset:51200
	ds_read_b128 v[214:217], v157 offset:52224
	ds_read_b128 v[218:221], v157 offset:53248
	ds_read_b128 v[222:225], v157 offset:54272
	ds_read_b128 v[226:229], v157 offset:55296
	ds_read_b128 v[230:233], v157 offset:56320
	global_load_lds_dwordx4 v132, s[24:25]
	s_add_i32 m0, s26, 0x2000
	s_add_i32 s26, s53, s30
	global_load_lds_dwordx4 v136, s[24:25]
	s_add_u32 s24, s24, 0x100000
	s_addc_u32 s25, s25, 0
	s_mov_b32 m0, s26
	s_nop 0
	global_load_lds_dwordx4 v132, s[24:25]
	s_add_i32 m0, s26, 0x2000
	s_nop 0
	global_load_lds_dwordx4 v136, s[24:25]
	s_mov_b32 m0, s38
	s_nop 0
	global_load_lds_dwordx4 v130, s[98:99]
	s_mov_b32 m0, s39
	s_nop 0
	global_load_lds_dwordx4 v134, s[98:99]
	s_waitcnt vmcnt(8)
	s_waitcnt lgkmcnt(0)
	s_barrier
	v_mfma_f32_16x16x32_bf16 v[62:65], v[142:145], v[202:205], v[62:65]
	v_mfma_f32_16x16x32_bf16 v[62:65], v[158:161], v[206:209], v[62:65]
	v_mfma_f32_16x16x32_bf16 v[58:61], v[176:179], v[206:209], v[58:61]
	v_mfma_f32_16x16x32_bf16 v[58:61], v[168:171], v[202:205], v[58:61]
	v_mfma_f32_16x16x32_bf16 v[42:45], v[168:171], v[210:213], v[42:45]
	v_mfma_f32_16x16x32_bf16 v[42:45], v[176:179], v[214:217], v[42:45]
	v_mfma_f32_16x16x32_bf16 v[46:49], v[158:161], v[214:217], v[46:49]
	v_mfma_f32_16x16x32_bf16 v[46:49], v[142:145], v[210:213], v[46:49]
	v_mfma_f32_16x16x32_bf16 v[30:33], v[142:145], v[218:221], v[30:33]
	v_mfma_f32_16x16x32_bf16 v[30:33], v[158:161], v[222:225], v[30:33]
	v_mfma_f32_16x16x32_bf16 v[26:29], v[176:179], v[222:225], v[26:29]
	v_mfma_f32_16x16x32_bf16 v[26:29], v[168:171], v[218:221], v[26:29]
	v_mfma_f32_16x16x32_bf16 v[10:13], v[168:171], v[226:229], v[10:13]
	v_mfma_f32_16x16x32_bf16 v[10:13], v[176:179], v[230:233], v[10:13]
	v_mfma_f32_16x16x32_bf16 v[14:17], v[158:161], v[230:233], v[14:17]
	v_mfma_f32_16x16x32_bf16 v[14:17], v[142:145], v[226:229], v[14:17]
	v_mfma_f32_16x16x32_bf16 v[6:9], v[180:183], v[226:229], v[6:9]
	v_mfma_f32_16x16x32_bf16 v[6:9], v[184:187], v[230:233], v[6:9]
	v_mfma_f32_16x16x32_bf16 v[2:5], v[192:195], v[230:233], v[2:5]
	v_mfma_f32_16x16x32_bf16 v[2:5], v[188:191], v[226:229], v[2:5]
	v_mfma_f32_16x16x32_bf16 v[18:21], v[188:191], v[218:221], v[18:21]
	v_mfma_f32_16x16x32_bf16 v[18:21], v[192:195], v[222:225], v[18:21]
	v_mfma_f32_16x16x32_bf16 v[22:25], v[184:187], v[222:225], v[22:25]
	v_mfma_f32_16x16x32_bf16 v[22:25], v[180:183], v[218:221], v[22:25]
	v_mfma_f32_16x16x32_bf16 v[38:41], v[180:183], v[210:213], v[38:41]
	v_mfma_f32_16x16x32_bf16 v[38:41], v[184:187], v[214:217], v[38:41]
	v_mfma_f32_16x16x32_bf16 v[34:37], v[192:195], v[214:217], v[34:37]
	v_mfma_f32_16x16x32_bf16 v[34:37], v[188:191], v[210:213], v[34:37]
	v_mfma_f32_16x16x32_bf16 v[50:53], v[188:191], v[202:205], v[50:53]
	v_mfma_f32_16x16x32_bf16 v[50:53], v[192:195], v[206:209], v[50:53]
	v_mfma_f32_16x16x32_bf16 v[54:57], v[184:187], v[206:209], v[54:57]
	v_mfma_f32_16x16x32_bf16 v[54:57], v[180:183], v[202:205], v[54:57]
	s_barrier
	s_add_i32 s51, s51, 2
	s_add_u32 s22, s22, 0x100
	s_addc_u32 s23, s23, 0
	s_add_u32 s49, s49, 0x100
	s_addc_u32 s50, s50, 0
.LBB0_1009:
	ds_read_b128 v[142:145], v155
	ds_read_b128 v[158:161], v155 offset:1024
	ds_read_b128 v[168:171], v155 offset:2048
	ds_read_b128 v[176:179], v155 offset:3072
	ds_read_b128 v[180:183], v156
	ds_read_b128 v[184:187], v156 offset:1024
	ds_read_b128 v[188:191], v156 offset:2048
	ds_read_b128 v[192:195], v156 offset:3072
	s_add_u32 s24, s22, 0xfff00080
	s_addc_u32 s25, s23, -1
	s_cmp_eq_u32 s51, 60
	s_cselect_b32 s27, s19, s25
	s_cselect_b32 s26, s47, s24
	s_cselect_b32 s25, s7, s50
	s_cselect_b32 s24, s48, s49
	s_mov_b32 m0, s40
	ds_read_b128 v[202:205], v157
	ds_read_b128 v[206:209], v157 offset:1024
	ds_read_b128 v[210:213], v157 offset:2048
	ds_read_b128 v[214:217], v157 offset:3072
	ds_read_b128 v[218:221], v157 offset:4096
	ds_read_b128 v[222:225], v157 offset:5120
	ds_read_b128 v[226:229], v157 offset:6144
	ds_read_b128 v[230:233], v157 offset:7168
	global_load_lds_dwordx4 v138, s[22:23]
	s_mov_b32 m0, s41
	s_nop 0
	global_load_lds_dwordx4 v140, s[22:23]
	s_waitcnt vmcnt(8)
	s_waitcnt lgkmcnt(0)
	s_barrier
	v_mfma_f32_16x16x32_bf16 v[126:129], v[142:145], v[202:205], v[126:129]
	v_mfma_f32_16x16x32_bf16 v[126:129], v[158:161], v[206:209], v[126:129]
	v_mfma_f32_16x16x32_bf16 v[122:125], v[176:179], v[206:209], v[122:125]
	v_mfma_f32_16x16x32_bf16 v[122:125], v[168:171], v[202:205], v[122:125]
	v_mfma_f32_16x16x32_bf16 v[106:109], v[168:171], v[210:213], v[106:109]
	v_mfma_f32_16x16x32_bf16 v[106:109], v[176:179], v[214:217], v[106:109]
	v_mfma_f32_16x16x32_bf16 v[110:113], v[158:161], v[214:217], v[110:113]
	v_mfma_f32_16x16x32_bf16 v[110:113], v[142:145], v[210:213], v[110:113]
	v_mfma_f32_16x16x32_bf16 v[94:97], v[142:145], v[218:221], v[94:97]
	v_mfma_f32_16x16x32_bf16 v[94:97], v[158:161], v[222:225], v[94:97]
	v_mfma_f32_16x16x32_bf16 v[90:93], v[176:179], v[222:225], v[90:93]
	v_mfma_f32_16x16x32_bf16 v[90:93], v[168:171], v[218:221], v[90:93]
	v_mfma_f32_16x16x32_bf16 v[74:77], v[168:171], v[226:229], v[74:77]
	v_mfma_f32_16x16x32_bf16 v[74:77], v[176:179], v[230:233], v[74:77]
	v_mfma_f32_16x16x32_bf16 v[78:81], v[158:161], v[230:233], v[78:81]
	v_mfma_f32_16x16x32_bf16 v[78:81], v[142:145], v[226:229], v[78:81]
	v_mfma_f32_16x16x32_bf16 v[70:73], v[180:183], v[226:229], v[70:73]
	v_mfma_f32_16x16x32_bf16 v[70:73], v[184:187], v[230:233], v[70:73]
	v_mfma_f32_16x16x32_bf16 v[66:69], v[192:195], v[230:233], v[66:69]
	v_mfma_f32_16x16x32_bf16 v[66:69], v[188:191], v[226:229], v[66:69]
	v_mfma_f32_16x16x32_bf16 v[82:85], v[188:191], v[218:221], v[82:85]
	v_mfma_f32_16x16x32_bf16 v[82:85], v[192:195], v[222:225], v[82:85]
	v_mfma_f32_16x16x32_bf16 v[86:89], v[184:187], v[222:225], v[86:89]
	v_mfma_f32_16x16x32_bf16 v[86:89], v[180:183], v[218:221], v[86:89]
	v_mfma_f32_16x16x32_bf16 v[102:105], v[180:183], v[210:213], v[102:105]
	v_mfma_f32_16x16x32_bf16 v[102:105], v[184:187], v[214:217], v[102:105]
	v_mfma_f32_16x16x32_bf16 v[98:101], v[192:195], v[214:217], v[98:101]
	v_mfma_f32_16x16x32_bf16 v[98:101], v[188:191], v[210:213], v[98:101]
	v_mfma_f32_16x16x32_bf16 v[114:117], v[188:191], v[202:205], v[114:117]
	v_mfma_f32_16x16x32_bf16 v[114:117], v[192:195], v[206:209], v[114:117]
	v_mfma_f32_16x16x32_bf16 v[118:121], v[184:187], v[206:209], v[118:121]
	v_mfma_f32_16x16x32_bf16 v[118:121], v[180:183], v[202:205], v[118:121]
	s_barrier
	s_mov_b32 m0, s42
	s_add_u32 s52, s24, 0x100000
	ds_read_b128 v[202:205], v157 offset:16384
	ds_read_b128 v[206:209], v157 offset:17408
	ds_read_b128 v[210:213], v157 offset:18432
	ds_read_b128 v[214:217], v157 offset:19456
	ds_read_b128 v[218:221], v157 offset:20480
	ds_read_b128 v[222:225], v157 offset:21504
	ds_read_b128 v[226:229], v157 offset:22528
	ds_read_b128 v[230:233], v157 offset:23552
	global_load_lds_dwordx4 v132, s[24:25]
	s_mov_b32 m0, s43
	s_addc_u32 s53, s25, 0
	global_load_lds_dwordx4 v136, s[24:25]
	s_mov_b32 m0, s44
	s_nop 0
	global_load_lds_dwordx4 v132, s[52:53]
	s_add_i32 m0, s44, 0x2000
	s_nop 0
	global_load_lds_dwordx4 v136, s[52:53]
	s_mov_b32 m0, s33
	s_nop 0
	global_load_lds_dwordx4 v130, s[26:27]
	s_mov_b32 m0, s34
	s_nop 0
	global_load_lds_dwordx4 v134, s[26:27]
	s_waitcnt vmcnt(8)
	s_waitcnt lgkmcnt(0)
	s_barrier
	v_mfma_f32_16x16x32_bf16 v[62:65], v[142:145], v[202:205], v[62:65]
	v_mfma_f32_16x16x32_bf16 v[62:65], v[158:161], v[206:209], v[62:65]
	v_mfma_f32_16x16x32_bf16 v[58:61], v[176:179], v[206:209], v[58:61]
	v_mfma_f32_16x16x32_bf16 v[58:61], v[168:171], v[202:205], v[58:61]
	v_mfma_f32_16x16x32_bf16 v[42:45], v[168:171], v[210:213], v[42:45]
	v_mfma_f32_16x16x32_bf16 v[42:45], v[176:179], v[214:217], v[42:45]
	v_mfma_f32_16x16x32_bf16 v[46:49], v[158:161], v[214:217], v[46:49]
	v_mfma_f32_16x16x32_bf16 v[46:49], v[142:145], v[210:213], v[46:49]
	v_mfma_f32_16x16x32_bf16 v[30:33], v[142:145], v[218:221], v[30:33]
	v_mfma_f32_16x16x32_bf16 v[30:33], v[158:161], v[222:225], v[30:33]
	v_mfma_f32_16x16x32_bf16 v[26:29], v[176:179], v[222:225], v[26:29]
	v_mfma_f32_16x16x32_bf16 v[26:29], v[168:171], v[218:221], v[26:29]
	v_mfma_f32_16x16x32_bf16 v[10:13], v[168:171], v[226:229], v[10:13]
	v_mfma_f32_16x16x32_bf16 v[10:13], v[176:179], v[230:233], v[10:13]
	v_mfma_f32_16x16x32_bf16 v[14:17], v[158:161], v[230:233], v[14:17]
	v_mfma_f32_16x16x32_bf16 v[14:17], v[142:145], v[226:229], v[14:17]
	v_mfma_f32_16x16x32_bf16 v[6:9], v[180:183], v[226:229], v[6:9]
	v_mfma_f32_16x16x32_bf16 v[6:9], v[184:187], v[230:233], v[6:9]
	v_mfma_f32_16x16x32_bf16 v[2:5], v[192:195], v[230:233], v[2:5]
	v_mfma_f32_16x16x32_bf16 v[2:5], v[188:191], v[226:229], v[2:5]
	v_mfma_f32_16x16x32_bf16 v[18:21], v[188:191], v[218:221], v[18:21]
	v_mfma_f32_16x16x32_bf16 v[18:21], v[192:195], v[222:225], v[18:21]
	v_mfma_f32_16x16x32_bf16 v[22:25], v[184:187], v[222:225], v[22:25]
	v_mfma_f32_16x16x32_bf16 v[22:25], v[180:183], v[218:221], v[22:25]
	v_mfma_f32_16x16x32_bf16 v[38:41], v[180:183], v[210:213], v[38:41]
	v_mfma_f32_16x16x32_bf16 v[38:41], v[184:187], v[214:217], v[38:41]
	v_mfma_f32_16x16x32_bf16 v[34:37], v[192:195], v[214:217], v[34:37]
	v_mfma_f32_16x16x32_bf16 v[34:37], v[188:191], v[210:213], v[34:37]
	v_mfma_f32_16x16x32_bf16 v[50:53], v[188:191], v[202:205], v[50:53]
	v_mfma_f32_16x16x32_bf16 v[50:53], v[192:195], v[206:209], v[50:53]
	v_mfma_f32_16x16x32_bf16 v[54:57], v[184:187], v[206:209], v[54:57]
	v_mfma_f32_16x16x32_bf16 v[54:57], v[180:183], v[202:205], v[54:57]
	s_barrier
	s_add_i32 s52, 0, 0x18000
	v_add_u32_e32 v166, s52, v153
	s_add_i32 s53, 0, 0x1c000
	ds_read_b128 v[142:145], v166
	ds_read_b128 v[158:161], v166 offset:1024
	ds_read_b128 v[168:171], v166 offset:2048
	ds_read_b128 v[176:179], v166 offset:3072
	v_add_u32_e32 v166, s53, v153
	ds_read_b128 v[180:183], v166
	ds_read_b128 v[184:187], v166 offset:1024
	ds_read_b128 v[188:191], v166 offset:2048
	ds_read_b128 v[192:195], v166 offset:3072
	s_add_u32 s26, s26, 0x100000
	s_addc_u32 s27, s27, 0
	s_mov_b32 m0, s35
	ds_read_b128 v[202:205], v157 offset:32768
	ds_read_b128 v[206:209], v157 offset:33792
	ds_read_b128 v[210:213], v157 offset:34816
	ds_read_b128 v[214:217], v157 offset:35840
	ds_read_b128 v[218:221], v157 offset:36864
	ds_read_b128 v[222:225], v157 offset:37888
	ds_read_b128 v[226:229], v157 offset:38912
	ds_read_b128 v[230:233], v157 offset:39936
	global_load_lds_dwordx4 v130, s[26:27]
	s_mov_b32 m0, s36
	s_nop 0
	global_load_lds_dwordx4 v134, s[26:27]
	s_waitcnt vmcnt(8)
	s_waitcnt lgkmcnt(0)
	s_barrier
	v_mfma_f32_16x16x32_bf16 v[126:129], v[142:145], v[202:205], v[126:129]
	v_mfma_f32_16x16x32_bf16 v[126:129], v[158:161], v[206:209], v[126:129]
	v_mfma_f32_16x16x32_bf16 v[122:125], v[176:179], v[206:209], v[122:125]
	v_mfma_f32_16x16x32_bf16 v[122:125], v[168:171], v[202:205], v[122:125]
	v_mfma_f32_16x16x32_bf16 v[106:109], v[168:171], v[210:213], v[106:109]
	v_mfma_f32_16x16x32_bf16 v[106:109], v[176:179], v[214:217], v[106:109]
	v_mfma_f32_16x16x32_bf16 v[110:113], v[158:161], v[214:217], v[110:113]
	v_mfma_f32_16x16x32_bf16 v[110:113], v[142:145], v[210:213], v[110:113]
	v_mfma_f32_16x16x32_bf16 v[94:97], v[142:145], v[218:221], v[94:97]
	v_mfma_f32_16x16x32_bf16 v[94:97], v[158:161], v[222:225], v[94:97]
	v_mfma_f32_16x16x32_bf16 v[90:93], v[176:179], v[222:225], v[90:93]
	v_mfma_f32_16x16x32_bf16 v[90:93], v[168:171], v[218:221], v[90:93]
	v_mfma_f32_16x16x32_bf16 v[74:77], v[168:171], v[226:229], v[74:77]
	v_mfma_f32_16x16x32_bf16 v[74:77], v[176:179], v[230:233], v[74:77]
	v_mfma_f32_16x16x32_bf16 v[78:81], v[158:161], v[230:233], v[78:81]
	v_mfma_f32_16x16x32_bf16 v[78:81], v[142:145], v[226:229], v[78:81]
	v_mfma_f32_16x16x32_bf16 v[70:73], v[180:183], v[226:229], v[70:73]
	v_mfma_f32_16x16x32_bf16 v[70:73], v[184:187], v[230:233], v[70:73]
	v_mfma_f32_16x16x32_bf16 v[66:69], v[192:195], v[230:233], v[66:69]
	v_mfma_f32_16x16x32_bf16 v[66:69], v[188:191], v[226:229], v[66:69]
	v_mfma_f32_16x16x32_bf16 v[82:85], v[188:191], v[218:221], v[82:85]
	v_mfma_f32_16x16x32_bf16 v[82:85], v[192:195], v[222:225], v[82:85]
	v_mfma_f32_16x16x32_bf16 v[86:89], v[184:187], v[222:225], v[86:89]
	v_mfma_f32_16x16x32_bf16 v[86:89], v[180:183], v[218:221], v[86:89]
	v_mfma_f32_16x16x32_bf16 v[102:105], v[180:183], v[210:213], v[102:105]
	v_mfma_f32_16x16x32_bf16 v[102:105], v[184:187], v[214:217], v[102:105]
	v_mfma_f32_16x16x32_bf16 v[98:101], v[192:195], v[214:217], v[98:101]
	v_mfma_f32_16x16x32_bf16 v[98:101], v[188:191], v[210:213], v[98:101]
	v_mfma_f32_16x16x32_bf16 v[114:117], v[188:191], v[202:205], v[114:117]
	v_mfma_f32_16x16x32_bf16 v[114:117], v[192:195], v[206:209], v[114:117]
	v_mfma_f32_16x16x32_bf16 v[118:121], v[184:187], v[206:209], v[118:121]
	v_mfma_f32_16x16x32_bf16 v[118:121], v[180:183], v[202:205], v[118:121]
	s_barrier
	s_add_u32 s98, s26, 0xfff00080
	s_addc_u32 s99, s27, -1
	s_add_u32 s24, s24, 0x80
	s_addc_u32 s25, s25, 0
	s_add_i32 s26, s52, s30
	s_mov_b32 m0, s26
	ds_read_b128 v[202:205], v157 offset:49152
	ds_read_b128 v[206:209], v157 offset:50176
	ds_read_b128 v[210:213], v157 offset:51200
	ds_read_b128 v[214:217], v157 offset:52224
	ds_read_b128 v[218:221], v157 offset:53248
	ds_read_b128 v[222:225], v157 offset:54272
	ds_read_b128 v[226:229], v157 offset:55296
	ds_read_b128 v[230:233], v157 offset:56320
	global_load_lds_dwordx4 v132, s[24:25]
	s_add_i32 m0, s26, 0x2000
	s_add_i32 s26, s53, s30
	global_load_lds_dwordx4 v136, s[24:25]
	s_add_u32 s24, s24, 0x100000
	s_addc_u32 s25, s25, 0
	s_mov_b32 m0, s26
	s_nop 0
	global_load_lds_dwordx4 v132, s[24:25]
	s_add_i32 m0, s26, 0x2000
	s_nop 0
	global_load_lds_dwordx4 v136, s[24:25]
	s_mov_b32 m0, s38
	s_nop 0
	global_load_lds_dwordx4 v130, s[98:99]
	s_mov_b32 m0, s39
	s_nop 0
	global_load_lds_dwordx4 v134, s[98:99]
	s_waitcnt vmcnt(8)
	s_waitcnt lgkmcnt(0)
	s_barrier
	v_mfma_f32_16x16x32_bf16 v[62:65], v[142:145], v[202:205], v[62:65]
	v_mfma_f32_16x16x32_bf16 v[62:65], v[158:161], v[206:209], v[62:65]
	v_mfma_f32_16x16x32_bf16 v[58:61], v[176:179], v[206:209], v[58:61]
	v_mfma_f32_16x16x32_bf16 v[58:61], v[168:171], v[202:205], v[58:61]
	v_mfma_f32_16x16x32_bf16 v[42:45], v[168:171], v[210:213], v[42:45]
	v_mfma_f32_16x16x32_bf16 v[42:45], v[176:179], v[214:217], v[42:45]
	v_mfma_f32_16x16x32_bf16 v[46:49], v[158:161], v[214:217], v[46:49]
	v_mfma_f32_16x16x32_bf16 v[46:49], v[142:145], v[210:213], v[46:49]
	v_mfma_f32_16x16x32_bf16 v[30:33], v[142:145], v[218:221], v[30:33]
	v_mfma_f32_16x16x32_bf16 v[30:33], v[158:161], v[222:225], v[30:33]
	v_mfma_f32_16x16x32_bf16 v[26:29], v[176:179], v[222:225], v[26:29]
	v_mfma_f32_16x16x32_bf16 v[26:29], v[168:171], v[218:221], v[26:29]
	v_mfma_f32_16x16x32_bf16 v[10:13], v[168:171], v[226:229], v[10:13]
	v_mfma_f32_16x16x32_bf16 v[10:13], v[176:179], v[230:233], v[10:13]
	v_mfma_f32_16x16x32_bf16 v[14:17], v[158:161], v[230:233], v[14:17]
	v_mfma_f32_16x16x32_bf16 v[14:17], v[142:145], v[226:229], v[14:17]
	v_mfma_f32_16x16x32_bf16 v[6:9], v[180:183], v[226:229], v[6:9]
	v_mfma_f32_16x16x32_bf16 v[6:9], v[184:187], v[230:233], v[6:9]
	v_mfma_f32_16x16x32_bf16 v[2:5], v[192:195], v[230:233], v[2:5]
	v_mfma_f32_16x16x32_bf16 v[2:5], v[188:191], v[226:229], v[2:5]
	v_mfma_f32_16x16x32_bf16 v[18:21], v[188:191], v[218:221], v[18:21]
	v_mfma_f32_16x16x32_bf16 v[18:21], v[192:195], v[222:225], v[18:21]
	v_mfma_f32_16x16x32_bf16 v[22:25], v[184:187], v[222:225], v[22:25]
	v_mfma_f32_16x16x32_bf16 v[22:25], v[180:183], v[218:221], v[22:25]
	v_mfma_f32_16x16x32_bf16 v[38:41], v[180:183], v[210:213], v[38:41]
	v_mfma_f32_16x16x32_bf16 v[38:41], v[184:187], v[214:217], v[38:41]
	v_mfma_f32_16x16x32_bf16 v[34:37], v[192:195], v[214:217], v[34:37]
	v_mfma_f32_16x16x32_bf16 v[34:37], v[188:191], v[210:213], v[34:37]
	v_mfma_f32_16x16x32_bf16 v[50:53], v[188:191], v[202:205], v[50:53]
	v_mfma_f32_16x16x32_bf16 v[50:53], v[192:195], v[206:209], v[50:53]
	v_mfma_f32_16x16x32_bf16 v[54:57], v[184:187], v[206:209], v[54:57]
	v_mfma_f32_16x16x32_bf16 v[54:57], v[180:183], v[202:205], v[54:57]
	s_barrier
	s_add_i32 s51, s51, 2
	s_add_u32 s22, s22, 0x100
	s_addc_u32 s23, s23, 0
	s_add_u32 s49, s49, 0x100
	s_addc_u32 s50, s50, 0
	s_cmp_gt_u32 s51, 61
	s_cbranch_scc0 .LBB0_1009
	s_setprio 0
	s_and_b64 vcc, exec, s[16:17]
	s_cbranch_vccz .LBB0_1012
	s_barrier

.LBB0_1171:
	s_add_i32 s36, s36, 1
	s_mov_b32 s52, s6
	s_lshl_b32 s6, s36, 5
	s_add_i32 s6, s6, s3
	s_mov_b64 s[22:23], s[8:9]
	s_lshl_b32 s8, s6, 3
	s_ashr_i32 s7, s6, 2
	s_add_i32 s8, s8, s39
	s_cmpk_lt_i32 s6, 0x158
	s_cselect_b32 s6, s7, s8
	s_mov_b32 s53, s26
	s_cselect_b32 s26, s40, 32
	s_cmpk_lt_i32 s6, 0x56
	s_cselect_b64 s[18:19], -1, 0
	s_lshl_b32 s7, s26, 21
	v_readlane_b32 s0, v250, 46
	s_mov_b64 s[20:21], s[10:11]
	v_readlane_b32 s1, v250, 47
	s_add_u32 s10, s0, s7
	s_addc_u32 s11, s1, 0
	s_and_b64 s[8:9], s[18:19], exec
	s_cselect_b32 s54, s11, s21
	s_cselect_b32 s55, s10, s20
	s_ashr_i32 s7, s6, 31
	s_lshl_b64 s[8:9], s[6:7], 21
	s_add_u32 s8, s27, s8
	s_addc_u32 s9, s30, s9
	s_and_b64 s[24:25], s[18:19], exec
	s_cselect_b32 s7, s9, s23
	s_cselect_b32 s56, s8, s22
	s_add_u32 s20, s20, 0x100080
	s_addc_u32 s21, s21, 0
	s_add_u32 s57, s22, 0x100
	s_addc_u32 s60, s23, 0
	s_mov_b32 s61, -2
	s_and_b64 vcc, exec, s[12:13]
	s_cbranch_vccz .Lsp_2
	s_setprio 1
.Lsp_2:
	s_waitcnt lgkmcnt(0)
	s_add_u32 s62, s20, 0xfff00000
	s_addc_u32 s63, s21, -1
	s_mov_b32 m0, s37
	ds_read_b128 v[142:145], v148
	global_load_lds_dwordx4 v130, s[62:63]
	s_mov_b32 m0, s38
	ds_read_b128 v[154:157], v148 offset:1024
	global_load_lds_dwordx4 v134, s[62:63]
	s_mov_b32 m0, s42
	ds_read_b128 v[158:161], v148 offset:2048
	global_load_lds_dwordx4 v138, s[20:21]
	s_mov_b32 m0, s43
	ds_read_b128 v[168:171], v148 offset:3072
	global_load_lds_dwordx4 v140, s[20:21]
	ds_read_b128 v[176:179], v149
	ds_read_b128 v[180:183], v149 offset:1024
	ds_read_b128 v[184:187], v149 offset:2048
	ds_read_b128 v[188:191], v149 offset:3072
	s_add_u32 s22, s20, 0xfff00080
	s_addc_u32 s23, s21, -1
	s_cmp_eq_u32 s61, 60
	s_cselect_b32 s25, s54, s23
	s_cselect_b32 s24, s55, s22
	s_cselect_b32 s23, s7, s60
	s_cselect_b32 s22, s56, s57
	ds_read_b128 v[192:195], v150
	ds_read_b128 v[202:205], v150 offset:1024
	ds_read_b128 v[206:209], v150 offset:2048
	ds_read_b128 v[210:213], v150 offset:3072
	ds_read_b128 v[214:217], v150 offset:4096
	ds_read_b128 v[218:221], v150 offset:5120
	ds_read_b128 v[222:225], v150 offset:6144
	ds_read_b128 v[226:229], v150 offset:7168
	s_waitcnt vmcnt(8)
	s_waitcnt lgkmcnt(0)
	s_barrier
	v_mfma_f32_16x16x32_bf16 v[126:129], v[142:145], v[192:195], 0
	v_mfma_f32_16x16x32_bf16 v[126:129], v[154:157], v[202:205], v[126:129]
	v_mfma_f32_16x16x32_bf16 v[118:121], v[168:171], v[202:205], 0
	v_mfma_f32_16x16x32_bf16 v[118:121], v[158:161], v[192:195], v[118:121]
	v_mfma_f32_16x16x32_bf16 v[102:105], v[158:161], v[206:209], 0
	v_mfma_f32_16x16x32_bf16 v[102:105], v[168:171], v[210:213], v[102:105]
	v_mfma_f32_16x16x32_bf16 v[110:113], v[154:157], v[210:213], 0
	v_mfma_f32_16x16x32_bf16 v[110:113], v[142:145], v[206:209], v[110:113]
	v_mfma_f32_16x16x32_bf16 v[94:97], v[142:145], v[214:217], 0
	v_mfma_f32_16x16x32_bf16 v[94:97], v[154:157], v[218:221], v[94:97]
	v_mfma_f32_16x16x32_bf16 v[86:89], v[168:171], v[218:221], 0
	v_mfma_f32_16x16x32_bf16 v[86:89], v[158:161], v[214:217], v[86:89]
	v_mfma_f32_16x16x32_bf16 v[70:73], v[158:161], v[222:225], 0
	v_mfma_f32_16x16x32_bf16 v[70:73], v[168:171], v[226:229], v[70:73]
	v_mfma_f32_16x16x32_bf16 v[78:81], v[154:157], v[226:229], 0
	v_mfma_f32_16x16x32_bf16 v[78:81], v[142:145], v[222:225], v[78:81]
	v_mfma_f32_16x16x32_bf16 v[74:77], v[176:179], v[222:225], 0
	v_mfma_f32_16x16x32_bf16 v[74:77], v[180:183], v[226:229], v[74:77]
	v_mfma_f32_16x16x32_bf16 v[66:69], v[188:191], v[226:229], 0
	v_mfma_f32_16x16x32_bf16 v[66:69], v[184:187], v[222:225], v[66:69]
	v_mfma_f32_16x16x32_bf16 v[82:85], v[184:187], v[214:217], 0
	v_mfma_f32_16x16x32_bf16 v[82:85], v[188:191], v[218:221], v[82:85]
	v_mfma_f32_16x16x32_bf16 v[90:93], v[180:183], v[218:221], 0
	v_mfma_f32_16x16x32_bf16 v[90:93], v[176:179], v[214:217], v[90:93]
	v_mfma_f32_16x16x32_bf16 v[106:109], v[176:179], v[206:209], 0
	v_mfma_f32_16x16x32_bf16 v[106:109], v[180:183], v[210:213], v[106:109]
	v_mfma_f32_16x16x32_bf16 v[98:101], v[188:191], v[210:213], 0
	v_mfma_f32_16x16x32_bf16 v[98:101], v[184:187], v[206:209], v[98:101]
	v_mfma_f32_16x16x32_bf16 v[114:117], v[184:187], v[192:195], 0
	v_mfma_f32_16x16x32_bf16 v[114:117], v[188:191], v[202:205], v[114:117]
	v_mfma_f32_16x16x32_bf16 v[122:125], v[180:183], v[202:205], 0
	v_mfma_f32_16x16x32_bf16 v[122:125], v[176:179], v[192:195], v[122:125]
	s_barrier
	s_mov_b32 m0, s44
	s_add_u32 s62, s22, 0x100000
	global_load_lds_dwordx4 v132, s[22:23]
	s_mov_b32 m0, s45
	s_addc_u32 s63, s23, 0
	global_load_lds_dwordx4 v136, s[22:23]
	s_mov_b32 m0, s46
	ds_read_b128 v[192:195], v150 offset:16384
	global_load_lds_dwordx4 v132, s[62:63]
	s_mov_b32 m0, s47
	ds_read_b128 v[202:205], v150 offset:17408
	global_load_lds_dwordx4 v136, s[62:63]
	ds_read_b128 v[206:209], v150 offset:18432
	ds_read_b128 v[210:213], v150 offset:19456
	ds_read_b128 v[214:217], v150 offset:20480
	ds_read_b128 v[218:221], v150 offset:21504
	ds_read_b128 v[222:225], v150 offset:22528
	ds_read_b128 v[226:229], v150 offset:23552
	s_waitcnt vmcnt(6)
	s_waitcnt lgkmcnt(0)
	s_barrier
	v_mfma_f32_16x16x32_bf16 v[62:65], v[142:145], v[192:195], 0
	v_mfma_f32_16x16x32_bf16 v[62:65], v[154:157], v[202:205], v[62:65]
	v_mfma_f32_16x16x32_bf16 v[54:57], v[168:171], v[202:205], 0
	v_mfma_f32_16x16x32_bf16 v[54:57], v[158:161], v[192:195], v[54:57]
	v_mfma_f32_16x16x32_bf16 v[38:41], v[158:161], v[206:209], 0
	v_mfma_f32_16x16x32_bf16 v[38:41], v[168:171], v[210:213], v[38:41]
	v_mfma_f32_16x16x32_bf16 v[46:49], v[154:157], v[210:213], 0
	v_mfma_f32_16x16x32_bf16 v[46:49], v[142:145], v[206:209], v[46:49]
	v_mfma_f32_16x16x32_bf16 v[30:33], v[142:145], v[214:217], 0
	v_mfma_f32_16x16x32_bf16 v[30:33], v[154:157], v[218:221], v[30:33]
	v_mfma_f32_16x16x32_bf16 v[22:25], v[168:171], v[218:221], 0
	v_mfma_f32_16x16x32_bf16 v[22:25], v[158:161], v[214:217], v[22:25]
	v_mfma_f32_16x16x32_bf16 v[6:9], v[158:161], v[222:225], 0
	v_mfma_f32_16x16x32_bf16 v[6:9], v[168:171], v[226:229], v[6:9]
	v_mfma_f32_16x16x32_bf16 v[14:17], v[154:157], v[226:229], 0
	v_mfma_f32_16x16x32_bf16 v[14:17], v[142:145], v[222:225], v[14:17]
	v_mfma_f32_16x16x32_bf16 v[10:13], v[176:179], v[222:225], 0
	v_mfma_f32_16x16x32_bf16 v[10:13], v[180:183], v[226:229], v[10:13]
	v_mfma_f32_16x16x32_bf16 v[2:5], v[188:191], v[226:229], 0
	v_mfma_f32_16x16x32_bf16 v[2:5], v[184:187], v[222:225], v[2:5]
	v_mfma_f32_16x16x32_bf16 v[18:21], v[184:187], v[214:217], 0
	v_mfma_f32_16x16x32_bf16 v[18:21], v[188:191], v[218:221], v[18:21]
	v_mfma_f32_16x16x32_bf16 v[26:29], v[180:183], v[218:221], 0
	v_mfma_f32_16x16x32_bf16 v[26:29], v[176:179], v[214:217], v[26:29]
	v_mfma_f32_16x16x32_bf16 v[42:45], v[176:179], v[206:209], 0
	v_mfma_f32_16x16x32_bf16 v[42:45], v[180:183], v[210:213], v[42:45]
	v_mfma_f32_16x16x32_bf16 v[34:37], v[188:191], v[210:213], 0
	v_mfma_f32_16x16x32_bf16 v[34:37], v[184:187], v[206:209], v[34:37]
	v_mfma_f32_16x16x32_bf16 v[50:53], v[184:187], v[192:195], 0
	v_mfma_f32_16x16x32_bf16 v[50:53], v[188:191], v[202:205], v[50:53]
	v_mfma_f32_16x16x32_bf16 v[58:61], v[180:183], v[202:205], 0
	v_mfma_f32_16x16x32_bf16 v[58:61], v[176:179], v[192:195], v[58:61]
	s_barrier
	s_mov_b32 m0, s31
	ds_read_b128 v[142:145], v151
	global_load_lds_dwordx4 v130, s[24:25]
	s_mov_b32 m0, s33
	ds_read_b128 v[154:157], v151 offset:1024
	global_load_lds_dwordx4 v134, s[24:25]
	s_add_u32 s24, s24, 0x100000
	s_addc_u32 s25, s25, 0
	s_mov_b32 m0, s34
	ds_read_b128 v[158:161], v151 offset:2048
	global_load_lds_dwordx4 v130, s[24:25]
	s_mov_b32 m0, s35
	ds_read_b128 v[168:171], v151 offset:3072
	global_load_lds_dwordx4 v134, s[24:25]
	ds_read_b128 v[176:179], v152
	ds_read_b128 v[180:183], v152 offset:1024
	ds_read_b128 v[184:187], v152 offset:2048
	ds_read_b128 v[188:191], v152 offset:3072
	ds_read_b128 v[192:195], v150 offset:32768
	ds_read_b128 v[202:205], v150 offset:33792
	ds_read_b128 v[206:209], v150 offset:34816
	ds_read_b128 v[210:213], v150 offset:35840
	ds_read_b128 v[214:217], v150 offset:36864
	ds_read_b128 v[218:221], v150 offset:37888
	ds_read_b128 v[222:225], v150 offset:38912
	ds_read_b128 v[226:229], v150 offset:39936
	s_waitcnt vmcnt(8)
	s_waitcnt lgkmcnt(0)
	s_barrier
	v_mfma_f32_16x16x32_bf16 v[126:129], v[142:145], v[192:195], v[126:129]
	v_mfma_f32_16x16x32_bf16 v[126:129], v[154:157], v[202:205], v[126:129]
	v_mfma_f32_16x16x32_bf16 v[118:121], v[168:171], v[202:205], v[118:121]
	v_mfma_f32_16x16x32_bf16 v[118:121], v[158:161], v[192:195], v[118:121]
	v_mfma_f32_16x16x32_bf16 v[102:105], v[158:161], v[206:209], v[102:105]
	v_mfma_f32_16x16x32_bf16 v[102:105], v[168:171], v[210:213], v[102:105]
	v_mfma_f32_16x16x32_bf16 v[110:113], v[154:157], v[210:213], v[110:113]
	v_mfma_f32_16x16x32_bf16 v[110:113], v[142:145], v[206:209], v[110:113]
	v_mfma_f32_16x16x32_bf16 v[94:97], v[142:145], v[214:217], v[94:97]
	v_mfma_f32_16x16x32_bf16 v[94:97], v[154:157], v[218:221], v[94:97]
	v_mfma_f32_16x16x32_bf16 v[86:89], v[168:171], v[218:221], v[86:89]
	v_mfma_f32_16x16x32_bf16 v[86:89], v[158:161], v[214:217], v[86:89]
	v_mfma_f32_16x16x32_bf16 v[70:73], v[158:161], v[222:225], v[70:73]
	v_mfma_f32_16x16x32_bf16 v[70:73], v[168:171], v[226:229], v[70:73]
	v_mfma_f32_16x16x32_bf16 v[78:81], v[154:157], v[226:229], v[78:81]
	v_mfma_f32_16x16x32_bf16 v[78:81], v[142:145], v[222:225], v[78:81]
	v_mfma_f32_16x16x32_bf16 v[74:77], v[176:179], v[222:225], v[74:77]
	v_mfma_f32_16x16x32_bf16 v[74:77], v[180:183], v[226:229], v[74:77]
	v_mfma_f32_16x16x32_bf16 v[66:69], v[188:191], v[226:229], v[66:69]
	v_mfma_f32_16x16x32_bf16 v[66:69], v[184:187], v[222:225], v[66:69]
	v_mfma_f32_16x16x32_bf16 v[82:85], v[184:187], v[214:217], v[82:85]
	v_mfma_f32_16x16x32_bf16 v[82:85], v[188:191], v[218:221], v[82:85]
	v_mfma_f32_16x16x32_bf16 v[90:93], v[180:183], v[218:221], v[90:93]
	v_mfma_f32_16x16x32_bf16 v[90:93], v[176:179], v[214:217], v[90:93]
	v_mfma_f32_16x16x32_bf16 v[106:109], v[176:179], v[206:209], v[106:109]
	v_mfma_f32_16x16x32_bf16 v[106:109], v[180:183], v[210:213], v[106:109]
	v_mfma_f32_16x16x32_bf16 v[98:101], v[188:191], v[210:213], v[98:101]
	v_mfma_f32_16x16x32_bf16 v[98:101], v[184:187], v[206:209], v[98:101]
	v_mfma_f32_16x16x32_bf16 v[114:117], v[184:187], v[192:195], v[114:117]
	v_mfma_f32_16x16x32_bf16 v[114:117], v[188:191], v[202:205], v[114:117]
	v_mfma_f32_16x16x32_bf16 v[122:125], v[180:183], v[202:205], v[122:125]
	v_mfma_f32_16x16x32_bf16 v[122:125], v[176:179], v[192:195], v[122:125]
	s_barrier
	s_mov_b32 m0, s48
	s_add_u32 s22, s22, 0x80
	s_addc_u32 s23, s23, 0
	global_load_lds_dwordx4 v132, s[22:23]
	s_mov_b32 m0, s49
	ds_read_b128 v[192:195], v150 offset:49152
	global_load_lds_dwordx4 v136, s[22:23]
	s_mov_b32 m0, s50
	s_add_u32 s22, s22, 0x100000
	s_addc_u32 s23, s23, 0
	global_load_lds_dwordx4 v132, s[22:23]
	s_mov_b32 m0, s51
	ds_read_b128 v[202:205], v150 offset:50176
	global_load_lds_dwordx4 v136, s[22:23]
	ds_read_b128 v[206:209], v150 offset:51200
	ds_read_b128 v[210:213], v150 offset:52224
	ds_read_b128 v[214:217], v150 offset:53248
	ds_read_b128 v[218:221], v150 offset:54272
	ds_read_b128 v[222:225], v150 offset:55296
	ds_read_b128 v[226:229], v150 offset:56320
	s_waitcnt vmcnt(6)
	s_waitcnt lgkmcnt(0)
	s_barrier
	v_mfma_f32_16x16x32_bf16 v[62:65], v[142:145], v[192:195], v[62:65]
	v_mfma_f32_16x16x32_bf16 v[62:65], v[154:157], v[202:205], v[62:65]
	v_mfma_f32_16x16x32_bf16 v[54:57], v[168:171], v[202:205], v[54:57]
	v_mfma_f32_16x16x32_bf16 v[54:57], v[158:161], v[192:195], v[54:57]
	v_mfma_f32_16x16x32_bf16 v[38:41], v[158:161], v[206:209], v[38:41]
	v_mfma_f32_16x16x32_bf16 v[38:41], v[168:171], v[210:213], v[38:41]
	v_mfma_f32_16x16x32_bf16 v[46:49], v[154:157], v[210:213], v[46:49]
	v_mfma_f32_16x16x32_bf16 v[46:49], v[142:145], v[206:209], v[46:49]
	v_mfma_f32_16x16x32_bf16 v[30:33], v[142:145], v[214:217], v[30:33]
	v_mfma_f32_16x16x32_bf16 v[30:33], v[154:157], v[218:221], v[30:33]
	v_mfma_f32_16x16x32_bf16 v[22:25], v[168:171], v[218:221], v[22:25]
	v_mfma_f32_16x16x32_bf16 v[22:25], v[158:161], v[214:217], v[22:25]
	v_mfma_f32_16x16x32_bf16 v[6:9], v[158:161], v[222:225], v[6:9]
	v_mfma_f32_16x16x32_bf16 v[6:9], v[168:171], v[226:229], v[6:9]
	v_mfma_f32_16x16x32_bf16 v[14:17], v[154:157], v[226:229], v[14:17]
	v_mfma_f32_16x16x32_bf16 v[14:17], v[142:145], v[222:225], v[14:17]
	v_mfma_f32_16x16x32_bf16 v[10:13], v[176:179], v[222:225], v[10:13]
	v_mfma_f32_16x16x32_bf16 v[10:13], v[180:183], v[226:229], v[10:13]
	v_mfma_f32_16x16x32_bf16 v[2:5], v[188:191], v[226:229], v[2:5]
	v_mfma_f32_16x16x32_bf16 v[2:5], v[184:187], v[222:225], v[2:5]
	v_mfma_f32_16x16x32_bf16 v[18:21], v[184:187], v[214:217], v[18:21]
	v_mfma_f32_16x16x32_bf16 v[18:21], v[188:191], v[218:221], v[18:21]
	v_mfma_f32_16x16x32_bf16 v[26:29], v[180:183], v[218:221], v[26:29]
	v_mfma_f32_16x16x32_bf16 v[26:29], v[176:179], v[214:217], v[26:29]
	v_mfma_f32_16x16x32_bf16 v[42:45], v[176:179], v[206:209], v[42:45]
	v_mfma_f32_16x16x32_bf16 v[42:45], v[180:183], v[210:213], v[42:45]
	v_mfma_f32_16x16x32_bf16 v[34:37], v[188:191], v[210:213], v[34:37]
	v_mfma_f32_16x16x32_bf16 v[34:37], v[184:187], v[206:209], v[34:37]
	v_mfma_f32_16x16x32_bf16 v[50:53], v[184:187], v[192:195], v[50:53]
	v_mfma_f32_16x16x32_bf16 v[50:53], v[188:191], v[202:205], v[50:53]
	v_mfma_f32_16x16x32_bf16 v[58:61], v[180:183], v[202:205], v[58:61]
	v_mfma_f32_16x16x32_bf16 v[58:61], v[176:179], v[192:195], v[58:61]
	s_barrier
	s_add_i32 s61, s61, 2
	s_add_u32 s20, s20, 0x100
	s_addc_u32 s21, s21, 0
	s_add_u32 s57, s57, 0x100
	s_addc_u32 s60, s60, 0
.LBB0_1172:
	s_add_u32 s62, s20, 0xfff00000
	s_addc_u32 s63, s21, -1
	s_mov_b32 m0, s37
	ds_read_b128 v[142:145], v148
	global_load_lds_dwordx4 v130, s[62:63]
	s_mov_b32 m0, s38
	ds_read_b128 v[154:157], v148 offset:1024
	global_load_lds_dwordx4 v134, s[62:63]
	s_mov_b32 m0, s42
	ds_read_b128 v[158:161], v148 offset:2048
	global_load_lds_dwordx4 v138, s[20:21]
	s_mov_b32 m0, s43
	ds_read_b128 v[168:171], v148 offset:3072
	global_load_lds_dwordx4 v140, s[20:21]
	ds_read_b128 v[176:179], v149
	ds_read_b128 v[180:183], v149 offset:1024
	ds_read_b128 v[184:187], v149 offset:2048
	ds_read_b128 v[188:191], v149 offset:3072
	s_add_u32 s22, s20, 0xfff00080
	s_addc_u32 s23, s21, -1
	s_cmp_eq_u32 s61, 60
	s_cselect_b32 s25, s54, s23
	s_cselect_b32 s24, s55, s22
	s_cselect_b32 s23, s7, s60
	s_cselect_b32 s22, s56, s57
	ds_read_b128 v[192:195], v150
	ds_read_b128 v[202:205], v150 offset:1024
	ds_read_b128 v[206:209], v150 offset:2048
	ds_read_b128 v[210:213], v150 offset:3072
	ds_read_b128 v[214:217], v150 offset:4096
	ds_read_b128 v[218:221], v150 offset:5120
	ds_read_b128 v[222:225], v150 offset:6144
	ds_read_b128 v[226:229], v150 offset:7168
	s_waitcnt vmcnt(8)
	s_waitcnt lgkmcnt(0)
	s_barrier
	v_mfma_f32_16x16x32_bf16 v[126:129], v[142:145], v[192:195], v[126:129]
	v_mfma_f32_16x16x32_bf16 v[126:129], v[154:157], v[202:205], v[126:129]
	v_mfma_f32_16x16x32_bf16 v[118:121], v[168:171], v[202:205], v[118:121]
	v_mfma_f32_16x16x32_bf16 v[118:121], v[158:161], v[192:195], v[118:121]
	v_mfma_f32_16x16x32_bf16 v[102:105], v[158:161], v[206:209], v[102:105]
	v_mfma_f32_16x16x32_bf16 v[102:105], v[168:171], v[210:213], v[102:105]
	v_mfma_f32_16x16x32_bf16 v[110:113], v[154:157], v[210:213], v[110:113]
	v_mfma_f32_16x16x32_bf16 v[110:113], v[142:145], v[206:209], v[110:113]
	v_mfma_f32_16x16x32_bf16 v[94:97], v[142:145], v[214:217], v[94:97]
	v_mfma_f32_16x16x32_bf16 v[94:97], v[154:157], v[218:221], v[94:97]
	v_mfma_f32_16x16x32_bf16 v[86:89], v[168:171], v[218:221], v[86:89]
	v_mfma_f32_16x16x32_bf16 v[86:89], v[158:161], v[214:217], v[86:89]
	v_mfma_f32_16x16x32_bf16 v[70:73], v[158:161], v[222:225], v[70:73]
	v_mfma_f32_16x16x32_bf16 v[70:73], v[168:171], v[226:229], v[70:73]
	v_mfma_f32_16x16x32_bf16 v[78:81], v[154:157], v[226:229], v[78:81]
	v_mfma_f32_16x16x32_bf16 v[78:81], v[142:145], v[222:225], v[78:81]
	v_mfma_f32_16x16x32_bf16 v[74:77], v[176:179], v[222:225], v[74:77]
	v_mfma_f32_16x16x32_bf16 v[74:77], v[180:183], v[226:229], v[74:77]
	v_mfma_f32_16x16x32_bf16 v[66:69], v[188:191], v[226:229], v[66:69]
	v_mfma_f32_16x16x32_bf16 v[66:69], v[184:187], v[222:225], v[66:69]
	v_mfma_f32_16x16x32_bf16 v[82:85], v[184:187], v[214:217], v[82:85]
	v_mfma_f32_16x16x32_bf16 v[82:85], v[188:191], v[218:221], v[82:85]
	v_mfma_f32_16x16x32_bf16 v[90:93], v[180:183], v[218:221], v[90:93]
	v_mfma_f32_16x16x32_bf16 v[90:93], v[176:179], v[214:217], v[90:93]
	v_mfma_f32_16x16x32_bf16 v[106:109], v[176:179], v[206:209], v[106:109]
	v_mfma_f32_16x16x32_bf16 v[106:109], v[180:183], v[210:213], v[106:109]
	v_mfma_f32_16x16x32_bf16 v[98:101], v[188:191], v[210:213], v[98:101]
	v_mfma_f32_16x16x32_bf16 v[98:101], v[184:187], v[206:209], v[98:101]
	v_mfma_f32_16x16x32_bf16 v[114:117], v[184:187], v[192:195], v[114:117]
	v_mfma_f32_16x16x32_bf16 v[114:117], v[188:191], v[202:205], v[114:117]
	v_mfma_f32_16x16x32_bf16 v[122:125], v[180:183], v[202:205], v[122:125]
	v_mfma_f32_16x16x32_bf16 v[122:125], v[176:179], v[192:195], v[122:125]
	s_barrier
	s_mov_b32 m0, s44
	s_add_u32 s62, s22, 0x100000
	global_load_lds_dwordx4 v132, s[22:23]
	s_mov_b32 m0, s45
	s_addc_u32 s63, s23, 0
	global_load_lds_dwordx4 v136, s[22:23]
	s_mov_b32 m0, s46
	ds_read_b128 v[192:195], v150 offset:16384
	global_load_lds_dwordx4 v132, s[62:63]
	s_mov_b32 m0, s47
	ds_read_b128 v[202:205], v150 offset:17408
	global_load_lds_dwordx4 v136, s[62:63]
	ds_read_b128 v[206:209], v150 offset:18432
	ds_read_b128 v[210:213], v150 offset:19456
	ds_read_b128 v[214:217], v150 offset:20480
	ds_read_b128 v[218:221], v150 offset:21504
	ds_read_b128 v[222:225], v150 offset:22528
	ds_read_b128 v[226:229], v150 offset:23552
	s_waitcnt vmcnt(6)
	s_waitcnt lgkmcnt(0)
	s_barrier
	v_mfma_f32_16x16x32_bf16 v[62:65], v[142:145], v[192:195], v[62:65]
	v_mfma_f32_16x16x32_bf16 v[62:65], v[154:157], v[202:205], v[62:65]
	v_mfma_f32_16x16x32_bf16 v[54:57], v[168:171], v[202:205], v[54:57]
	v_mfma_f32_16x16x32_bf16 v[54:57], v[158:161], v[192:195], v[54:57]
	v_mfma_f32_16x16x32_bf16 v[38:41], v[158:161], v[206:209], v[38:41]
	v_mfma_f32_16x16x32_bf16 v[38:41], v[168:171], v[210:213], v[38:41]
	v_mfma_f32_16x16x32_bf16 v[46:49], v[154:157], v[210:213], v[46:49]
	v_mfma_f32_16x16x32_bf16 v[46:49], v[142:145], v[206:209], v[46:49]
	v_mfma_f32_16x16x32_bf16 v[30:33], v[142:145], v[214:217], v[30:33]
	v_mfma_f32_16x16x32_bf16 v[30:33], v[154:157], v[218:221], v[30:33]
	v_mfma_f32_16x16x32_bf16 v[22:25], v[168:171], v[218:221], v[22:25]
	v_mfma_f32_16x16x32_bf16 v[22:25], v[158:161], v[214:217], v[22:25]
	v_mfma_f32_16x16x32_bf16 v[6:9], v[158:161], v[222:225], v[6:9]
	v_mfma_f32_16x16x32_bf16 v[6:9], v[168:171], v[226:229], v[6:9]
	v_mfma_f32_16x16x32_bf16 v[14:17], v[154:157], v[226:229], v[14:17]
	v_mfma_f32_16x16x32_bf16 v[14:17], v[142:145], v[222:225], v[14:17]
	v_mfma_f32_16x16x32_bf16 v[10:13], v[176:179], v[222:225], v[10:13]
	v_mfma_f32_16x16x32_bf16 v[10:13], v[180:183], v[226:229], v[10:13]
	v_mfma_f32_16x16x32_bf16 v[2:5], v[188:191], v[226:229], v[2:5]
	v_mfma_f32_16x16x32_bf16 v[2:5], v[184:187], v[222:225], v[2:5]
	v_mfma_f32_16x16x32_bf16 v[18:21], v[184:187], v[214:217], v[18:21]
	v_mfma_f32_16x16x32_bf16 v[18:21], v[188:191], v[218:221], v[18:21]
	v_mfma_f32_16x16x32_bf16 v[26:29], v[180:183], v[218:221], v[26:29]
	v_mfma_f32_16x16x32_bf16 v[26:29], v[176:179], v[214:217], v[26:29]
	v_mfma_f32_16x16x32_bf16 v[42:45], v[176:179], v[206:209], v[42:45]
	v_mfma_f32_16x16x32_bf16 v[42:45], v[180:183], v[210:213], v[42:45]
	v_mfma_f32_16x16x32_bf16 v[34:37], v[188:191], v[210:213], v[34:37]
	v_mfma_f32_16x16x32_bf16 v[34:37], v[184:187], v[206:209], v[34:37]
	v_mfma_f32_16x16x32_bf16 v[50:53], v[184:187], v[192:195], v[50:53]
	v_mfma_f32_16x16x32_bf16 v[50:53], v[188:191], v[202:205], v[50:53]
	v_mfma_f32_16x16x32_bf16 v[58:61], v[180:183], v[202:205], v[58:61]
	v_mfma_f32_16x16x32_bf16 v[58:61], v[176:179], v[192:195], v[58:61]
	s_barrier
	s_mov_b32 m0, s31
	ds_read_b128 v[142:145], v151
	global_load_lds_dwordx4 v130, s[24:25]
	s_mov_b32 m0, s33
	ds_read_b128 v[154:157], v151 offset:1024
	global_load_lds_dwordx4 v134, s[24:25]
	s_add_u32 s24, s24, 0x100000
	s_addc_u32 s25, s25, 0
	s_mov_b32 m0, s34
	ds_read_b128 v[158:161], v151 offset:2048
	global_load_lds_dwordx4 v130, s[24:25]
	s_mov_b32 m0, s35
	ds_read_b128 v[168:171], v151 offset:3072
	global_load_lds_dwordx4 v134, s[24:25]
	ds_read_b128 v[176:179], v152
	ds_read_b128 v[180:183], v152 offset:1024
	ds_read_b128 v[184:187], v152 offset:2048
	ds_read_b128 v[188:191], v152 offset:3072
	ds_read_b128 v[192:195], v150 offset:32768
	ds_read_b128 v[202:205], v150 offset:33792
	ds_read_b128 v[206:209], v150 offset:34816
	ds_read_b128 v[210:213], v150 offset:35840
	ds_read_b128 v[214:217], v150 offset:36864
	ds_read_b128 v[218:221], v150 offset:37888
	ds_read_b128 v[222:225], v150 offset:38912
	ds_read_b128 v[226:229], v150 offset:39936
	s_waitcnt vmcnt(8)
	s_waitcnt lgkmcnt(0)
	s_barrier
	v_mfma_f32_16x16x32_bf16 v[126:129], v[142:145], v[192:195], v[126:129]
	v_mfma_f32_16x16x32_bf16 v[126:129], v[154:157], v[202:205], v[126:129]
	v_mfma_f32_16x16x32_bf16 v[118:121], v[168:171], v[202:205], v[118:121]
	v_mfma_f32_16x16x32_bf16 v[118:121], v[158:161], v[192:195], v[118:121]
	v_mfma_f32_16x16x32_bf16 v[102:105], v[158:161], v[206:209], v[102:105]
	v_mfma_f32_16x16x32_bf16 v[102:105], v[168:171], v[210:213], v[102:105]
	v_mfma_f32_16x16x32_bf16 v[110:113], v[154:157], v[210:213], v[110:113]
	v_mfma_f32_16x16x32_bf16 v[110:113], v[142:145], v[206:209], v[110:113]
	v_mfma_f32_16x16x32_bf16 v[94:97], v[142:145], v[214:217], v[94:97]
	v_mfma_f32_16x16x32_bf16 v[94:97], v[154:157], v[218:221], v[94:97]
	v_mfma_f32_16x16x32_bf16 v[86:89], v[168:171], v[218:221], v[86:89]
	v_mfma_f32_16x16x32_bf16 v[86:89], v[158:161], v[214:217], v[86:89]
	v_mfma_f32_16x16x32_bf16 v[70:73], v[158:161], v[222:225], v[70:73]
	v_mfma_f32_16x16x32_bf16 v[70:73], v[168:171], v[226:229], v[70:73]
	v_mfma_f32_16x16x32_bf16 v[78:81], v[154:157], v[226:229], v[78:81]
	v_mfma_f32_16x16x32_bf16 v[78:81], v[142:145], v[222:225], v[78:81]
	v_mfma_f32_16x16x32_bf16 v[74:77], v[176:179], v[222:225], v[74:77]
	v_mfma_f32_16x16x32_bf16 v[74:77], v[180:183], v[226:229], v[74:77]
	v_mfma_f32_16x16x32_bf16 v[66:69], v[188:191], v[226:229], v[66:69]
	v_mfma_f32_16x16x32_bf16 v[66:69], v[184:187], v[222:225], v[66:69]
	v_mfma_f32_16x16x32_bf16 v[82:85], v[184:187], v[214:217], v[82:85]
	v_mfma_f32_16x16x32_bf16 v[82:85], v[188:191], v[218:221], v[82:85]
	v_mfma_f32_16x16x32_bf16 v[90:93], v[180:183], v[218:221], v[90:93]
	v_mfma_f32_16x16x32_bf16 v[90:93], v[176:179], v[214:217], v[90:93]
	v_mfma_f32_16x16x32_bf16 v[106:109], v[176:179], v[206:209], v[106:109]
	v_mfma_f32_16x16x32_bf16 v[106:109], v[180:183], v[210:213], v[106:109]
	v_mfma_f32_16x16x32_bf16 v[98:101], v[188:191], v[210:213], v[98:101]
	v_mfma_f32_16x16x32_bf16 v[98:101], v[184:187], v[206:209], v[98:101]
	v_mfma_f32_16x16x32_bf16 v[114:117], v[184:187], v[192:195], v[114:117]
	v_mfma_f32_16x16x32_bf16 v[114:117], v[188:191], v[202:205], v[114:117]
	v_mfma_f32_16x16x32_bf16 v[122:125], v[180:183], v[202:205], v[122:125]
	v_mfma_f32_16x16x32_bf16 v[122:125], v[176:179], v[192:195], v[122:125]
	s_barrier
	s_mov_b32 m0, s48
	s_add_u32 s22, s22, 0x80
	s_addc_u32 s23, s23, 0
	global_load_lds_dwordx4 v132, s[22:23]
	s_mov_b32 m0, s49
	ds_read_b128 v[192:195], v150 offset:49152
	global_load_lds_dwordx4 v136, s[22:23]
	s_mov_b32 m0, s50
	s_add_u32 s22, s22, 0x100000
	s_addc_u32 s23, s23, 0
	global_load_lds_dwordx4 v132, s[22:23]
	s_mov_b32 m0, s51
	ds_read_b128 v[202:205], v150 offset:50176
	global_load_lds_dwordx4 v136, s[22:23]
	ds_read_b128 v[206:209], v150 offset:51200
	ds_read_b128 v[210:213], v150 offset:52224
	ds_read_b128 v[214:217], v150 offset:53248
	ds_read_b128 v[218:221], v150 offset:54272
	ds_read_b128 v[222:225], v150 offset:55296
	ds_read_b128 v[226:229], v150 offset:56320
	s_waitcnt vmcnt(6)
	s_waitcnt lgkmcnt(0)
	s_barrier
	v_mfma_f32_16x16x32_bf16 v[62:65], v[142:145], v[192:195], v[62:65]
	v_mfma_f32_16x16x32_bf16 v[62:65], v[154:157], v[202:205], v[62:65]
	v_mfma_f32_16x16x32_bf16 v[54:57], v[168:171], v[202:205], v[54:57]
	v_mfma_f32_16x16x32_bf16 v[54:57], v[158:161], v[192:195], v[54:57]
	v_mfma_f32_16x16x32_bf16 v[38:41], v[158:161], v[206:209], v[38:41]
	v_mfma_f32_16x16x32_bf16 v[38:41], v[168:171], v[210:213], v[38:41]
	v_mfma_f32_16x16x32_bf16 v[46:49], v[154:157], v[210:213], v[46:49]
	v_mfma_f32_16x16x32_bf16 v[46:49], v[142:145], v[206:209], v[46:49]
	v_mfma_f32_16x16x32_bf16 v[30:33], v[142:145], v[214:217], v[30:33]
	v_mfma_f32_16x16x32_bf16 v[30:33], v[154:157], v[218:221], v[30:33]
	v_mfma_f32_16x16x32_bf16 v[22:25], v[168:171], v[218:221], v[22:25]
	v_mfma_f32_16x16x32_bf16 v[22:25], v[158:161], v[214:217], v[22:25]
	v_mfma_f32_16x16x32_bf16 v[6:9], v[158:161], v[222:225], v[6:9]
	v_mfma_f32_16x16x32_bf16 v[6:9], v[168:171], v[226:229], v[6:9]
	v_mfma_f32_16x16x32_bf16 v[14:17], v[154:157], v[226:229], v[14:17]
	v_mfma_f32_16x16x32_bf16 v[14:17], v[142:145], v[222:225], v[14:17]
	v_mfma_f32_16x16x32_bf16 v[10:13], v[176:179], v[222:225], v[10:13]
	v_mfma_f32_16x16x32_bf16 v[10:13], v[180:183], v[226:229], v[10:13]
	v_mfma_f32_16x16x32_bf16 v[2:5], v[188:191], v[226:229], v[2:5]
	v_mfma_f32_16x16x32_bf16 v[2:5], v[184:187], v[222:225], v[2:5]
	v_mfma_f32_16x16x32_bf16 v[18:21], v[184:187], v[214:217], v[18:21]
	v_mfma_f32_16x16x32_bf16 v[18:21], v[188:191], v[218:221], v[18:21]
	v_mfma_f32_16x16x32_bf16 v[26:29], v[180:183], v[218:221], v[26:29]
	v_mfma_f32_16x16x32_bf16 v[26:29], v[176:179], v[214:217], v[26:29]
	v_mfma_f32_16x16x32_bf16 v[42:45], v[176:179], v[206:209], v[42:45]
	v_mfma_f32_16x16x32_bf16 v[42:45], v[180:183], v[210:213], v[42:45]
	v_mfma_f32_16x16x32_bf16 v[34:37], v[188:191], v[210:213], v[34:37]
	v_mfma_f32_16x16x32_bf16 v[34:37], v[184:187], v[206:209], v[34:37]
	v_mfma_f32_16x16x32_bf16 v[50:53], v[184:187], v[192:195], v[50:53]
	v_mfma_f32_16x16x32_bf16 v[50:53], v[188:191], v[202:205], v[50:53]
	v_mfma_f32_16x16x32_bf16 v[58:61], v[180:183], v[202:205], v[58:61]
	v_mfma_f32_16x16x32_bf16 v[58:61], v[176:179], v[192:195], v[58:61]
	s_barrier
	s_add_i32 s61, s61, 2
	s_add_u32 s20, s20, 0x100
	s_addc_u32 s21, s21, 0
	s_add_u32 s57, s57, 0x100
	s_addc_u32 s60, s60, 0
	s_cmp_gt_u32 s61, 61
	s_cbranch_scc0 .LBB0_1172
	s_setprio 0
	s_and_b64 vcc, exec, s[16:17]
	s_cbranch_vccz .LBB0_1175
	s_barrier

.LBB0_1417:
	s_and_b64 s[18:19], s[18:19], exec
	s_cselect_b32 s19, s9, s23
	s_cselect_b32 s18, s8, s22
	s_add_u32 s22, s22, 0x2b0080
	s_addc_u32 s23, s23, 0
	s_add_u32 s53, s24, 0x100
	s_addc_u32 s54, s25, 0
	s_mov_b32 s55, -2
	s_and_b64 vcc, exec, s[10:11]
	s_cbranch_vccz .Lsp_3
	s_setprio 1
.Lsp_3:
	s_waitcnt lgkmcnt(0)
	s_add_u32 s56, s22, 0xffd50000
	s_addc_u32 s57, s23, -1
	s_mov_b32 m0, s40
	ds_read_b128 v[142:145], v156
	global_load_lds_dwordx4 v130, s[56:57]
	s_mov_b32 m0, s41
	ds_read_b128 v[168:171], v156 offset:1024
	global_load_lds_dwordx4 v134, s[56:57]
	s_mov_b32 m0, s42
	ds_read_b128 v[176:179], v156 offset:2048
	global_load_lds_dwordx4 v138, s[22:23]
	s_mov_b32 m0, s43
	ds_read_b128 v[180:183], v156 offset:3072
	global_load_lds_dwordx4 v140, s[22:23]
	ds_read_b128 v[184:187], v157
	ds_read_b128 v[188:191], v157 offset:1024
	ds_read_b128 v[192:195], v157 offset:2048
	ds_read_b128 v[204:207], v157 offset:3072
	s_add_u32 s24, s22, 0xffd50080
	s_addc_u32 s25, s23, -1
	s_cmpk_eq_i32 s55, 0xa8
	s_cselect_b32 s27, s19, s25
	s_cselect_b32 s26, s18, s24
	s_cselect_b32 s25, s17, s54
	s_cselect_b32 s24, s16, s53
	ds_read_b128 v[208:211], v158
	ds_read_b128 v[212:215], v158 offset:1024
	ds_read_b128 v[216:219], v158 offset:2048
	ds_read_b128 v[220:223], v158 offset:3072
	ds_read_b128 v[224:227], v158 offset:4096
	ds_read_b128 v[228:231], v158 offset:5120
	ds_read_b128 v[232:235], v158 offset:6144
	ds_read_b128 v[236:239], v158 offset:7168
	s_waitcnt vmcnt(8)
	s_waitcnt lgkmcnt(0)
	s_barrier
	v_mfma_f32_16x16x32_bf16 v[126:129], v[142:145], v[208:211], 0
	v_mfma_f32_16x16x32_bf16 v[126:129], v[168:171], v[212:215], v[126:129]
	v_mfma_f32_16x16x32_bf16 v[122:125], v[180:183], v[212:215], 0
	v_mfma_f32_16x16x32_bf16 v[122:125], v[176:179], v[208:211], v[122:125]
	v_mfma_f32_16x16x32_bf16 v[106:109], v[176:179], v[216:219], 0
	v_mfma_f32_16x16x32_bf16 v[106:109], v[180:183], v[220:223], v[106:109]
	v_mfma_f32_16x16x32_bf16 v[110:113], v[168:171], v[220:223], 0
	v_mfma_f32_16x16x32_bf16 v[110:113], v[142:145], v[216:219], v[110:113]
	v_mfma_f32_16x16x32_bf16 v[94:97], v[142:145], v[224:227], 0
	v_mfma_f32_16x16x32_bf16 v[94:97], v[168:171], v[228:231], v[94:97]
	v_mfma_f32_16x16x32_bf16 v[90:93], v[180:183], v[228:231], 0
	v_mfma_f32_16x16x32_bf16 v[90:93], v[176:179], v[224:227], v[90:93]
	v_mfma_f32_16x16x32_bf16 v[74:77], v[176:179], v[232:235], 0
	v_mfma_f32_16x16x32_bf16 v[74:77], v[180:183], v[236:239], v[74:77]
	v_mfma_f32_16x16x32_bf16 v[78:81], v[168:171], v[236:239], 0
	v_mfma_f32_16x16x32_bf16 v[78:81], v[142:145], v[232:235], v[78:81]
	v_mfma_f32_16x16x32_bf16 v[70:73], v[184:187], v[232:235], 0
	v_mfma_f32_16x16x32_bf16 v[70:73], v[188:191], v[236:239], v[70:73]
	v_mfma_f32_16x16x32_bf16 v[66:69], v[204:207], v[236:239], 0
	v_mfma_f32_16x16x32_bf16 v[66:69], v[192:195], v[232:235], v[66:69]
	v_mfma_f32_16x16x32_bf16 v[82:85], v[192:195], v[224:227], 0
	v_mfma_f32_16x16x32_bf16 v[82:85], v[204:207], v[228:231], v[82:85]
	v_mfma_f32_16x16x32_bf16 v[86:89], v[188:191], v[228:231], 0
	v_mfma_f32_16x16x32_bf16 v[86:89], v[184:187], v[224:227], v[86:89]
	v_mfma_f32_16x16x32_bf16 v[102:105], v[184:187], v[216:219], 0
	v_mfma_f32_16x16x32_bf16 v[102:105], v[188:191], v[220:223], v[102:105]
	v_mfma_f32_16x16x32_bf16 v[98:101], v[204:207], v[220:223], 0
	v_mfma_f32_16x16x32_bf16 v[98:101], v[192:195], v[216:219], v[98:101]
	v_mfma_f32_16x16x32_bf16 v[114:117], v[192:195], v[208:211], 0
	v_mfma_f32_16x16x32_bf16 v[114:117], v[204:207], v[212:215], v[114:117]
	v_mfma_f32_16x16x32_bf16 v[118:121], v[188:191], v[212:215], 0
	v_mfma_f32_16x16x32_bf16 v[118:121], v[184:187], v[208:211], v[118:121]
	s_barrier
	s_mov_b32 m0, s44
	s_add_u32 s56, s24, 0x2b0000
	global_load_lds_dwordx4 v132, s[24:25]
	s_mov_b32 m0, s45
	s_addc_u32 s57, s25, 0
	global_load_lds_dwordx4 v136, s[24:25]
	s_mov_b32 m0, s46
	ds_read_b128 v[208:211], v158 offset:16384
	global_load_lds_dwordx4 v132, s[56:57]
	s_mov_b32 m0, s47
	ds_read_b128 v[212:215], v158 offset:17408
	global_load_lds_dwordx4 v136, s[56:57]
	ds_read_b128 v[216:219], v158 offset:18432
	ds_read_b128 v[220:223], v158 offset:19456
	ds_read_b128 v[224:227], v158 offset:20480
	ds_read_b128 v[228:231], v158 offset:21504
	ds_read_b128 v[232:235], v158 offset:22528
	ds_read_b128 v[236:239], v158 offset:23552
	s_waitcnt vmcnt(6)
	s_waitcnt lgkmcnt(0)
	s_barrier
	v_mfma_f32_16x16x32_bf16 v[62:65], v[142:145], v[208:211], 0
	v_mfma_f32_16x16x32_bf16 v[62:65], v[168:171], v[212:215], v[62:65]
	v_mfma_f32_16x16x32_bf16 v[58:61], v[180:183], v[212:215], 0
	v_mfma_f32_16x16x32_bf16 v[58:61], v[176:179], v[208:211], v[58:61]
	v_mfma_f32_16x16x32_bf16 v[42:45], v[176:179], v[216:219], 0
	v_mfma_f32_16x16x32_bf16 v[42:45], v[180:183], v[220:223], v[42:45]
	v_mfma_f32_16x16x32_bf16 v[46:49], v[168:171], v[220:223], 0
	v_mfma_f32_16x16x32_bf16 v[46:49], v[142:145], v[216:219], v[46:49]
	v_mfma_f32_16x16x32_bf16 v[30:33], v[142:145], v[224:227], 0
	v_mfma_f32_16x16x32_bf16 v[30:33], v[168:171], v[228:231], v[30:33]
	v_mfma_f32_16x16x32_bf16 v[26:29], v[180:183], v[228:231], 0
	v_mfma_f32_16x16x32_bf16 v[26:29], v[176:179], v[224:227], v[26:29]
	v_mfma_f32_16x16x32_bf16 v[10:13], v[176:179], v[232:235], 0
	v_mfma_f32_16x16x32_bf16 v[10:13], v[180:183], v[236:239], v[10:13]
	v_mfma_f32_16x16x32_bf16 v[14:17], v[168:171], v[236:239], 0
	v_mfma_f32_16x16x32_bf16 v[14:17], v[142:145], v[232:235], v[14:17]
	v_mfma_f32_16x16x32_bf16 v[6:9], v[184:187], v[232:235], 0
	v_mfma_f32_16x16x32_bf16 v[6:9], v[188:191], v[236:239], v[6:9]
	v_mfma_f32_16x16x32_bf16 v[2:5], v[204:207], v[236:239], 0
	v_mfma_f32_16x16x32_bf16 v[2:5], v[192:195], v[232:235], v[2:5]
	v_mfma_f32_16x16x32_bf16 v[18:21], v[192:195], v[224:227], 0
	v_mfma_f32_16x16x32_bf16 v[18:21], v[204:207], v[228:231], v[18:21]
	v_mfma_f32_16x16x32_bf16 v[22:25], v[188:191], v[228:231], 0
	v_mfma_f32_16x16x32_bf16 v[22:25], v[184:187], v[224:227], v[22:25]
	v_mfma_f32_16x16x32_bf16 v[38:41], v[184:187], v[216:219], 0
	v_mfma_f32_16x16x32_bf16 v[38:41], v[188:191], v[220:223], v[38:41]
	v_mfma_f32_16x16x32_bf16 v[34:37], v[204:207], v[220:223], 0
	v_mfma_f32_16x16x32_bf16 v[34:37], v[192:195], v[216:219], v[34:37]
	v_mfma_f32_16x16x32_bf16 v[50:53], v[192:195], v[208:211], 0
	v_mfma_f32_16x16x32_bf16 v[50:53], v[204:207], v[212:215], v[50:53]
	v_mfma_f32_16x16x32_bf16 v[54:57], v[188:191], v[212:215], 0
	v_mfma_f32_16x16x32_bf16 v[54:57], v[184:187], v[208:211], v[54:57]
	s_barrier
	s_mov_b32 m0, s35
	ds_read_b128 v[142:145], v159
	global_load_lds_dwordx4 v130, s[26:27]
	s_mov_b32 m0, s36
	ds_read_b128 v[168:171], v159 offset:1024
	global_load_lds_dwordx4 v134, s[26:27]
	s_add_u32 s26, s26, 0x2b0000
	s_addc_u32 s27, s27, 0
	s_mov_b32 m0, s37
	ds_read_b128 v[176:179], v159 offset:2048
	global_load_lds_dwordx4 v130, s[26:27]
	s_mov_b32 m0, s38
	ds_read_b128 v[180:183], v159 offset:3072
	global_load_lds_dwordx4 v134, s[26:27]
	ds_read_b128 v[184:187], v160
	ds_read_b128 v[188:191], v160 offset:1024
	ds_read_b128 v[192:195], v160 offset:2048
	ds_read_b128 v[204:207], v160 offset:3072
	ds_read_b128 v[208:211], v158 offset:32768
	ds_read_b128 v[212:215], v158 offset:33792
	ds_read_b128 v[216:219], v158 offset:34816
	ds_read_b128 v[220:223], v158 offset:35840
	ds_read_b128 v[224:227], v158 offset:36864
	ds_read_b128 v[228:231], v158 offset:37888
	ds_read_b128 v[232:235], v158 offset:38912
	ds_read_b128 v[236:239], v158 offset:39936
	s_waitcnt vmcnt(8)
	s_waitcnt lgkmcnt(0)
	s_barrier
	v_mfma_f32_16x16x32_bf16 v[126:129], v[142:145], v[208:211], v[126:129]
	v_mfma_f32_16x16x32_bf16 v[126:129], v[168:171], v[212:215], v[126:129]
	v_mfma_f32_16x16x32_bf16 v[122:125], v[180:183], v[212:215], v[122:125]
	v_mfma_f32_16x16x32_bf16 v[122:125], v[176:179], v[208:211], v[122:125]
	v_mfma_f32_16x16x32_bf16 v[106:109], v[176:179], v[216:219], v[106:109]
	v_mfma_f32_16x16x32_bf16 v[106:109], v[180:183], v[220:223], v[106:109]
	v_mfma_f32_16x16x32_bf16 v[110:113], v[168:171], v[220:223], v[110:113]
	v_mfma_f32_16x16x32_bf16 v[110:113], v[142:145], v[216:219], v[110:113]
	v_mfma_f32_16x16x32_bf16 v[94:97], v[142:145], v[224:227], v[94:97]
	v_mfma_f32_16x16x32_bf16 v[94:97], v[168:171], v[228:231], v[94:97]
	v_mfma_f32_16x16x32_bf16 v[90:93], v[180:183], v[228:231], v[90:93]
	v_mfma_f32_16x16x32_bf16 v[90:93], v[176:179], v[224:227], v[90:93]
	v_mfma_f32_16x16x32_bf16 v[74:77], v[176:179], v[232:235], v[74:77]
	v_mfma_f32_16x16x32_bf16 v[74:77], v[180:183], v[236:239], v[74:77]
	v_mfma_f32_16x16x32_bf16 v[78:81], v[168:171], v[236:239], v[78:81]
	v_mfma_f32_16x16x32_bf16 v[78:81], v[142:145], v[232:235], v[78:81]
	v_mfma_f32_16x16x32_bf16 v[70:73], v[184:187], v[232:235], v[70:73]
	v_mfma_f32_16x16x32_bf16 v[70:73], v[188:191], v[236:239], v[70:73]
	v_mfma_f32_16x16x32_bf16 v[66:69], v[204:207], v[236:239], v[66:69]
	v_mfma_f32_16x16x32_bf16 v[66:69], v[192:195], v[232:235], v[66:69]
	v_mfma_f32_16x16x32_bf16 v[82:85], v[192:195], v[224:227], v[82:85]
	v_mfma_f32_16x16x32_bf16 v[82:85], v[204:207], v[228:231], v[82:85]
	v_mfma_f32_16x16x32_bf16 v[86:89], v[188:191], v[228:231], v[86:89]
	v_mfma_f32_16x16x32_bf16 v[86:89], v[184:187], v[224:227], v[86:89]
	v_mfma_f32_16x16x32_bf16 v[102:105], v[184:187], v[216:219], v[102:105]
	v_mfma_f32_16x16x32_bf16 v[102:105], v[188:191], v[220:223], v[102:105]
	v_mfma_f32_16x16x32_bf16 v[98:101], v[204:207], v[220:223], v[98:101]
	v_mfma_f32_16x16x32_bf16 v[98:101], v[192:195], v[216:219], v[98:101]
	v_mfma_f32_16x16x32_bf16 v[114:117], v[192:195], v[208:211], v[114:117]
	v_mfma_f32_16x16x32_bf16 v[114:117], v[204:207], v[212:215], v[114:117]
	v_mfma_f32_16x16x32_bf16 v[118:121], v[188:191], v[212:215], v[118:121]
	v_mfma_f32_16x16x32_bf16 v[118:121], v[184:187], v[208:211], v[118:121]
	s_barrier
	s_mov_b32 m0, s48
	s_add_u32 s24, s24, 0x80
	s_addc_u32 s25, s25, 0
	global_load_lds_dwordx4 v132, s[24:25]
	s_mov_b32 m0, s49
	ds_read_b128 v[208:211], v158 offset:49152
	global_load_lds_dwordx4 v136, s[24:25]
	s_mov_b32 m0, s50
	s_add_u32 s24, s24, 0x2b0000
	s_addc_u32 s25, s25, 0
	global_load_lds_dwordx4 v132, s[24:25]
	s_add_i32 m0, s50, 0x2000
	ds_read_b128 v[212:215], v158 offset:50176
	global_load_lds_dwordx4 v136, s[24:25]
	ds_read_b128 v[216:219], v158 offset:51200
	ds_read_b128 v[220:223], v158 offset:52224
	ds_read_b128 v[224:227], v158 offset:53248
	ds_read_b128 v[228:231], v158 offset:54272
	ds_read_b128 v[232:235], v158 offset:55296
	ds_read_b128 v[236:239], v158 offset:56320
	s_waitcnt vmcnt(6)
	s_waitcnt lgkmcnt(0)
	s_barrier
	v_mfma_f32_16x16x32_bf16 v[62:65], v[142:145], v[208:211], v[62:65]
	v_mfma_f32_16x16x32_bf16 v[62:65], v[168:171], v[212:215], v[62:65]
	v_mfma_f32_16x16x32_bf16 v[58:61], v[180:183], v[212:215], v[58:61]
	v_mfma_f32_16x16x32_bf16 v[58:61], v[176:179], v[208:211], v[58:61]
	v_mfma_f32_16x16x32_bf16 v[42:45], v[176:179], v[216:219], v[42:45]
	v_mfma_f32_16x16x32_bf16 v[42:45], v[180:183], v[220:223], v[42:45]
	v_mfma_f32_16x16x32_bf16 v[46:49], v[168:171], v[220:223], v[46:49]
	v_mfma_f32_16x16x32_bf16 v[46:49], v[142:145], v[216:219], v[46:49]
	v_mfma_f32_16x16x32_bf16 v[30:33], v[142:145], v[224:227], v[30:33]
	v_mfma_f32_16x16x32_bf16 v[30:33], v[168:171], v[228:231], v[30:33]
	v_mfma_f32_16x16x32_bf16 v[26:29], v[180:183], v[228:231], v[26:29]
	v_mfma_f32_16x16x32_bf16 v[26:29], v[176:179], v[224:227], v[26:29]
	v_mfma_f32_16x16x32_bf16 v[10:13], v[176:179], v[232:235], v[10:13]
	v_mfma_f32_16x16x32_bf16 v[10:13], v[180:183], v[236:239], v[10:13]
	v_mfma_f32_16x16x32_bf16 v[14:17], v[168:171], v[236:239], v[14:17]
	v_mfma_f32_16x16x32_bf16 v[14:17], v[142:145], v[232:235], v[14:17]
	v_mfma_f32_16x16x32_bf16 v[6:9], v[184:187], v[232:235], v[6:9]
	v_mfma_f32_16x16x32_bf16 v[6:9], v[188:191], v[236:239], v[6:9]
	v_mfma_f32_16x16x32_bf16 v[2:5], v[204:207], v[236:239], v[2:5]
	v_mfma_f32_16x16x32_bf16 v[2:5], v[192:195], v[232:235], v[2:5]
	v_mfma_f32_16x16x32_bf16 v[18:21], v[192:195], v[224:227], v[18:21]
	v_mfma_f32_16x16x32_bf16 v[18:21], v[204:207], v[228:231], v[18:21]
	v_mfma_f32_16x16x32_bf16 v[22:25], v[188:191], v[228:231], v[22:25]
	v_mfma_f32_16x16x32_bf16 v[22:25], v[184:187], v[224:227], v[22:25]
	v_mfma_f32_16x16x32_bf16 v[38:41], v[184:187], v[216:219], v[38:41]
	v_mfma_f32_16x16x32_bf16 v[38:41], v[188:191], v[220:223], v[38:41]
	v_mfma_f32_16x16x32_bf16 v[34:37], v[204:207], v[220:223], v[34:37]
	v_mfma_f32_16x16x32_bf16 v[34:37], v[192:195], v[216:219], v[34:37]
	v_mfma_f32_16x16x32_bf16 v[50:53], v[192:195], v[208:211], v[50:53]
	v_mfma_f32_16x16x32_bf16 v[50:53], v[204:207], v[212:215], v[50:53]
	v_mfma_f32_16x16x32_bf16 v[54:57], v[188:191], v[212:215], v[54:57]
	v_mfma_f32_16x16x32_bf16 v[54:57], v[184:187], v[208:211], v[54:57]
	s_barrier
	s_add_i32 s55, s55, 2
	s_add_u32 s22, s22, 0x100
	s_addc_u32 s23, s23, 0
	s_add_u32 s53, s53, 0x100
	s_addc_u32 s54, s54, 0
.LBB0_1418:
	s_add_u32 s56, s22, 0xffd50000
	s_addc_u32 s57, s23, -1
	s_mov_b32 m0, s40
	ds_read_b128 v[142:145], v156
	global_load_lds_dwordx4 v130, s[56:57]
	s_mov_b32 m0, s41
	ds_read_b128 v[168:171], v156 offset:1024
	global_load_lds_dwordx4 v134, s[56:57]
	s_mov_b32 m0, s42
	ds_read_b128 v[176:179], v156 offset:2048
	global_load_lds_dwordx4 v138, s[22:23]
	s_mov_b32 m0, s43
	ds_read_b128 v[180:183], v156 offset:3072
	global_load_lds_dwordx4 v140, s[22:23]
	ds_read_b128 v[184:187], v157
	ds_read_b128 v[188:191], v157 offset:1024
	ds_read_b128 v[192:195], v157 offset:2048
	ds_read_b128 v[204:207], v157 offset:3072
	s_add_u32 s24, s22, 0xffd50080
	s_addc_u32 s25, s23, -1
	s_cmpk_eq_i32 s55, 0xa8
	s_cselect_b32 s27, s19, s25
	s_cselect_b32 s26, s18, s24
	s_cselect_b32 s25, s17, s54
	s_cselect_b32 s24, s16, s53
	ds_read_b128 v[208:211], v158
	ds_read_b128 v[212:215], v158 offset:1024
	ds_read_b128 v[216:219], v158 offset:2048
	ds_read_b128 v[220:223], v158 offset:3072
	ds_read_b128 v[224:227], v158 offset:4096
	ds_read_b128 v[228:231], v158 offset:5120
	ds_read_b128 v[232:235], v158 offset:6144
	ds_read_b128 v[236:239], v158 offset:7168
	s_waitcnt vmcnt(8)
	s_waitcnt lgkmcnt(0)
	s_barrier
	v_mfma_f32_16x16x32_bf16 v[126:129], v[142:145], v[208:211], v[126:129]
	v_mfma_f32_16x16x32_bf16 v[126:129], v[168:171], v[212:215], v[126:129]
	v_mfma_f32_16x16x32_bf16 v[122:125], v[180:183], v[212:215], v[122:125]
	v_mfma_f32_16x16x32_bf16 v[122:125], v[176:179], v[208:211], v[122:125]
	v_mfma_f32_16x16x32_bf16 v[106:109], v[176:179], v[216:219], v[106:109]
	v_mfma_f32_16x16x32_bf16 v[106:109], v[180:183], v[220:223], v[106:109]
	v_mfma_f32_16x16x32_bf16 v[110:113], v[168:171], v[220:223], v[110:113]
	v_mfma_f32_16x16x32_bf16 v[110:113], v[142:145], v[216:219], v[110:113]
	v_mfma_f32_16x16x32_bf16 v[94:97], v[142:145], v[224:227], v[94:97]
	v_mfma_f32_16x16x32_bf16 v[94:97], v[168:171], v[228:231], v[94:97]
	v_mfma_f32_16x16x32_bf16 v[90:93], v[180:183], v[228:231], v[90:93]
	v_mfma_f32_16x16x32_bf16 v[90:93], v[176:179], v[224:227], v[90:93]
	v_mfma_f32_16x16x32_bf16 v[74:77], v[176:179], v[232:235], v[74:77]
	v_mfma_f32_16x16x32_bf16 v[74:77], v[180:183], v[236:239], v[74:77]
	v_mfma_f32_16x16x32_bf16 v[78:81], v[168:171], v[236:239], v[78:81]
	v_mfma_f32_16x16x32_bf16 v[78:81], v[142:145], v[232:235], v[78:81]
	v_mfma_f32_16x16x32_bf16 v[70:73], v[184:187], v[232:235], v[70:73]
	v_mfma_f32_16x16x32_bf16 v[70:73], v[188:191], v[236:239], v[70:73]
	v_mfma_f32_16x16x32_bf16 v[66:69], v[204:207], v[236:239], v[66:69]
	v_mfma_f32_16x16x32_bf16 v[66:69], v[192:195], v[232:235], v[66:69]
	v_mfma_f32_16x16x32_bf16 v[82:85], v[192:195], v[224:227], v[82:85]
	v_mfma_f32_16x16x32_bf16 v[82:85], v[204:207], v[228:231], v[82:85]
	v_mfma_f32_16x16x32_bf16 v[86:89], v[188:191], v[228:231], v[86:89]
	v_mfma_f32_16x16x32_bf16 v[86:89], v[184:187], v[224:227], v[86:89]
	v_mfma_f32_16x16x32_bf16 v[102:105], v[184:187], v[216:219], v[102:105]
	v_mfma_f32_16x16x32_bf16 v[102:105], v[188:191], v[220:223], v[102:105]
	v_mfma_f32_16x16x32_bf16 v[98:101], v[204:207], v[220:223], v[98:101]
	v_mfma_f32_16x16x32_bf16 v[98:101], v[192:195], v[216:219], v[98:101]
	v_mfma_f32_16x16x32_bf16 v[114:117], v[192:195], v[208:211], v[114:117]
	v_mfma_f32_16x16x32_bf16 v[114:117], v[204:207], v[212:215], v[114:117]
	v_mfma_f32_16x16x32_bf16 v[118:121], v[188:191], v[212:215], v[118:121]
	v_mfma_f32_16x16x32_bf16 v[118:121], v[184:187], v[208:211], v[118:121]
	s_barrier
	s_mov_b32 m0, s44
	s_add_u32 s56, s24, 0x2b0000
	global_load_lds_dwordx4 v132, s[24:25]
	s_mov_b32 m0, s45
	s_addc_u32 s57, s25, 0
	global_load_lds_dwordx4 v136, s[24:25]
	s_mov_b32 m0, s46
	ds_read_b128 v[208:211], v158 offset:16384
	global_load_lds_dwordx4 v132, s[56:57]
	s_mov_b32 m0, s47
	ds_read_b128 v[212:215], v158 offset:17408
	global_load_lds_dwordx4 v136, s[56:57]
	ds_read_b128 v[216:219], v158 offset:18432
	ds_read_b128 v[220:223], v158 offset:19456
	ds_read_b128 v[224:227], v158 offset:20480
	ds_read_b128 v[228:231], v158 offset:21504
	ds_read_b128 v[232:235], v158 offset:22528
	ds_read_b128 v[236:239], v158 offset:23552
	s_waitcnt vmcnt(6)
	s_waitcnt lgkmcnt(0)
	s_barrier
	v_mfma_f32_16x16x32_bf16 v[62:65], v[142:145], v[208:211], v[62:65]
	v_mfma_f32_16x16x32_bf16 v[62:65], v[168:171], v[212:215], v[62:65]
	v_mfma_f32_16x16x32_bf16 v[58:61], v[180:183], v[212:215], v[58:61]
	v_mfma_f32_16x16x32_bf16 v[58:61], v[176:179], v[208:211], v[58:61]
	v_mfma_f32_16x16x32_bf16 v[42:45], v[176:179], v[216:219], v[42:45]
	v_mfma_f32_16x16x32_bf16 v[42:45], v[180:183], v[220:223], v[42:45]
	v_mfma_f32_16x16x32_bf16 v[46:49], v[168:171], v[220:223], v[46:49]
	v_mfma_f32_16x16x32_bf16 v[46:49], v[142:145], v[216:219], v[46:49]
	v_mfma_f32_16x16x32_bf16 v[30:33], v[142:145], v[224:227], v[30:33]
	v_mfma_f32_16x16x32_bf16 v[30:33], v[168:171], v[228:231], v[30:33]
	v_mfma_f32_16x16x32_bf16 v[26:29], v[180:183], v[228:231], v[26:29]
	v_mfma_f32_16x16x32_bf16 v[26:29], v[176:179], v[224:227], v[26:29]
	v_mfma_f32_16x16x32_bf16 v[10:13], v[176:179], v[232:235], v[10:13]
	v_mfma_f32_16x16x32_bf16 v[10:13], v[180:183], v[236:239], v[10:13]
	v_mfma_f32_16x16x32_bf16 v[14:17], v[168:171], v[236:239], v[14:17]
	v_mfma_f32_16x16x32_bf16 v[14:17], v[142:145], v[232:235], v[14:17]
	v_mfma_f32_16x16x32_bf16 v[6:9], v[184:187], v[232:235], v[6:9]
	v_mfma_f32_16x16x32_bf16 v[6:9], v[188:191], v[236:239], v[6:9]
	v_mfma_f32_16x16x32_bf16 v[2:5], v[204:207], v[236:239], v[2:5]
	v_mfma_f32_16x16x32_bf16 v[2:5], v[192:195], v[232:235], v[2:5]
	v_mfma_f32_16x16x32_bf16 v[18:21], v[192:195], v[224:227], v[18:21]
	v_mfma_f32_16x16x32_bf16 v[18:21], v[204:207], v[228:231], v[18:21]
	v_mfma_f32_16x16x32_bf16 v[22:25], v[188:191], v[228:231], v[22:25]
	v_mfma_f32_16x16x32_bf16 v[22:25], v[184:187], v[224:227], v[22:25]
	v_mfma_f32_16x16x32_bf16 v[38:41], v[184:187], v[216:219], v[38:41]
	v_mfma_f32_16x16x32_bf16 v[38:41], v[188:191], v[220:223], v[38:41]
	v_mfma_f32_16x16x32_bf16 v[34:37], v[204:207], v[220:223], v[34:37]
	v_mfma_f32_16x16x32_bf16 v[34:37], v[192:195], v[216:219], v[34:37]
	v_mfma_f32_16x16x32_bf16 v[50:53], v[192:195], v[208:211], v[50:53]
	v_mfma_f32_16x16x32_bf16 v[50:53], v[204:207], v[212:215], v[50:53]
	v_mfma_f32_16x16x32_bf16 v[54:57], v[188:191], v[212:215], v[54:57]
	v_mfma_f32_16x16x32_bf16 v[54:57], v[184:187], v[208:211], v[54:57]
	s_barrier
	s_mov_b32 m0, s35
	ds_read_b128 v[142:145], v159
	global_load_lds_dwordx4 v130, s[26:27]
	s_mov_b32 m0, s36
	ds_read_b128 v[168:171], v159 offset:1024
	global_load_lds_dwordx4 v134, s[26:27]
	s_add_u32 s26, s26, 0x2b0000
	s_addc_u32 s27, s27, 0
	s_mov_b32 m0, s37
	ds_read_b128 v[176:179], v159 offset:2048
	global_load_lds_dwordx4 v130, s[26:27]
	s_mov_b32 m0, s38
	ds_read_b128 v[180:183], v159 offset:3072
	global_load_lds_dwordx4 v134, s[26:27]
	ds_read_b128 v[184:187], v160
	ds_read_b128 v[188:191], v160 offset:1024
	ds_read_b128 v[192:195], v160 offset:2048
	ds_read_b128 v[204:207], v160 offset:3072
	ds_read_b128 v[208:211], v158 offset:32768
	ds_read_b128 v[212:215], v158 offset:33792
	ds_read_b128 v[216:219], v158 offset:34816
	ds_read_b128 v[220:223], v158 offset:35840
	ds_read_b128 v[224:227], v158 offset:36864
	ds_read_b128 v[228:231], v158 offset:37888
	ds_read_b128 v[232:235], v158 offset:38912
	ds_read_b128 v[236:239], v158 offset:39936
	s_waitcnt vmcnt(8)
	s_waitcnt lgkmcnt(0)
	s_barrier
	v_mfma_f32_16x16x32_bf16 v[126:129], v[142:145], v[208:211], v[126:129]
	v_mfma_f32_16x16x32_bf16 v[126:129], v[168:171], v[212:215], v[126:129]
	v_mfma_f32_16x16x32_bf16 v[122:125], v[180:183], v[212:215], v[122:125]
	v_mfma_f32_16x16x32_bf16 v[122:125], v[176:179], v[208:211], v[122:125]
	v_mfma_f32_16x16x32_bf16 v[106:109], v[176:179], v[216:219], v[106:109]
	v_mfma_f32_16x16x32_bf16 v[106:109], v[180:183], v[220:223], v[106:109]
	v_mfma_f32_16x16x32_bf16 v[110:113], v[168:171], v[220:223], v[110:113]
	v_mfma_f32_16x16x32_bf16 v[110:113], v[142:145], v[216:219], v[110:113]
	v_mfma_f32_16x16x32_bf16 v[94:97], v[142:145], v[224:227], v[94:97]
	v_mfma_f32_16x16x32_bf16 v[94:97], v[168:171], v[228:231], v[94:97]
	v_mfma_f32_16x16x32_bf16 v[90:93], v[180:183], v[228:231], v[90:93]
	v_mfma_f32_16x16x32_bf16 v[90:93], v[176:179], v[224:227], v[90:93]
	v_mfma_f32_16x16x32_bf16 v[74:77], v[176:179], v[232:235], v[74:77]
	v_mfma_f32_16x16x32_bf16 v[74:77], v[180:183], v[236:239], v[74:77]
	v_mfma_f32_16x16x32_bf16 v[78:81], v[168:171], v[236:239], v[78:81]
	v_mfma_f32_16x16x32_bf16 v[78:81], v[142:145], v[232:235], v[78:81]
	v_mfma_f32_16x16x32_bf16 v[70:73], v[184:187], v[232:235], v[70:73]
	v_mfma_f32_16x16x32_bf16 v[70:73], v[188:191], v[236:239], v[70:73]
	v_mfma_f32_16x16x32_bf16 v[66:69], v[204:207], v[236:239], v[66:69]
	v_mfma_f32_16x16x32_bf16 v[66:69], v[192:195], v[232:235], v[66:69]
	v_mfma_f32_16x16x32_bf16 v[82:85], v[192:195], v[224:227], v[82:85]
	v_mfma_f32_16x16x32_bf16 v[82:85], v[204:207], v[228:231], v[82:85]
	v_mfma_f32_16x16x32_bf16 v[86:89], v[188:191], v[228:231], v[86:89]
	v_mfma_f32_16x16x32_bf16 v[86:89], v[184:187], v[224:227], v[86:89]
	v_mfma_f32_16x16x32_bf16 v[102:105], v[184:187], v[216:219], v[102:105]
	v_mfma_f32_16x16x32_bf16 v[102:105], v[188:191], v[220:223], v[102:105]
	v_mfma_f32_16x16x32_bf16 v[98:101], v[204:207], v[220:223], v[98:101]
	v_mfma_f32_16x16x32_bf16 v[98:101], v[192:195], v[216:219], v[98:101]
	v_mfma_f32_16x16x32_bf16 v[114:117], v[192:195], v[208:211], v[114:117]
	v_mfma_f32_16x16x32_bf16 v[114:117], v[204:207], v[212:215], v[114:117]
	v_mfma_f32_16x16x32_bf16 v[118:121], v[188:191], v[212:215], v[118:121]
	v_mfma_f32_16x16x32_bf16 v[118:121], v[184:187], v[208:211], v[118:121]
	s_barrier
	s_mov_b32 m0, s48
	s_add_u32 s24, s24, 0x80
	s_addc_u32 s25, s25, 0
	global_load_lds_dwordx4 v132, s[24:25]
	s_mov_b32 m0, s49
	ds_read_b128 v[208:211], v158 offset:49152
	global_load_lds_dwordx4 v136, s[24:25]
	s_mov_b32 m0, s50
	s_add_u32 s24, s24, 0x2b0000
	s_addc_u32 s25, s25, 0
	global_load_lds_dwordx4 v132, s[24:25]
	s_add_i32 m0, s50, 0x2000
	ds_read_b128 v[212:215], v158 offset:50176
	global_load_lds_dwordx4 v136, s[24:25]
	ds_read_b128 v[216:219], v158 offset:51200
	ds_read_b128 v[220:223], v158 offset:52224
	ds_read_b128 v[224:227], v158 offset:53248
	ds_read_b128 v[228:231], v158 offset:54272
	ds_read_b128 v[232:235], v158 offset:55296
	ds_read_b128 v[236:239], v158 offset:56320
	s_waitcnt vmcnt(6)
	s_waitcnt lgkmcnt(0)
	s_barrier
	v_mfma_f32_16x16x32_bf16 v[62:65], v[142:145], v[208:211], v[62:65]
	v_mfma_f32_16x16x32_bf16 v[62:65], v[168:171], v[212:215], v[62:65]
	v_mfma_f32_16x16x32_bf16 v[58:61], v[180:183], v[212:215], v[58:61]
	v_mfma_f32_16x16x32_bf16 v[58:61], v[176:179], v[208:211], v[58:61]
	v_mfma_f32_16x16x32_bf16 v[42:45], v[176:179], v[216:219], v[42:45]
	v_mfma_f32_16x16x32_bf16 v[42:45], v[180:183], v[220:223], v[42:45]
	v_mfma_f32_16x16x32_bf16 v[46:49], v[168:171], v[220:223], v[46:49]
	v_mfma_f32_16x16x32_bf16 v[46:49], v[142:145], v[216:219], v[46:49]
	v_mfma_f32_16x16x32_bf16 v[30:33], v[142:145], v[224:227], v[30:33]
	v_mfma_f32_16x16x32_bf16 v[30:33], v[168:171], v[228:231], v[30:33]
	v_mfma_f32_16x16x32_bf16 v[26:29], v[180:183], v[228:231], v[26:29]
	v_mfma_f32_16x16x32_bf16 v[26:29], v[176:179], v[224:227], v[26:29]
	v_mfma_f32_16x16x32_bf16 v[10:13], v[176:179], v[232:235], v[10:13]
	v_mfma_f32_16x16x32_bf16 v[10:13], v[180:183], v[236:239], v[10:13]
	v_mfma_f32_16x16x32_bf16 v[14:17], v[168:171], v[236:239], v[14:17]
	v_mfma_f32_16x16x32_bf16 v[14:17], v[142:145], v[232:235], v[14:17]
	v_mfma_f32_16x16x32_bf16 v[6:9], v[184:187], v[232:235], v[6:9]
	v_mfma_f32_16x16x32_bf16 v[6:9], v[188:191], v[236:239], v[6:9]
	v_mfma_f32_16x16x32_bf16 v[2:5], v[204:207], v[236:239], v[2:5]
	v_mfma_f32_16x16x32_bf16 v[2:5], v[192:195], v[232:235], v[2:5]
	v_mfma_f32_16x16x32_bf16 v[18:21], v[192:195], v[224:227], v[18:21]
	v_mfma_f32_16x16x32_bf16 v[18:21], v[204:207], v[228:231], v[18:21]
	v_mfma_f32_16x16x32_bf16 v[22:25], v[188:191], v[228:231], v[22:25]
	v_mfma_f32_16x16x32_bf16 v[22:25], v[184:187], v[224:227], v[22:25]
	v_mfma_f32_16x16x32_bf16 v[38:41], v[184:187], v[216:219], v[38:41]
	v_mfma_f32_16x16x32_bf16 v[38:41], v[188:191], v[220:223], v[38:41]
	v_mfma_f32_16x16x32_bf16 v[34:37], v[204:207], v[220:223], v[34:37]
	v_mfma_f32_16x16x32_bf16 v[34:37], v[192:195], v[216:219], v[34:37]
	v_mfma_f32_16x16x32_bf16 v[50:53], v[192:195], v[208:211], v[50:53]
	v_mfma_f32_16x16x32_bf16 v[50:53], v[204:207], v[212:215], v[50:53]
	v_mfma_f32_16x16x32_bf16 v[54:57], v[188:191], v[212:215], v[54:57]
	v_mfma_f32_16x16x32_bf16 v[54:57], v[184:187], v[208:211], v[54:57]
	s_barrier
	s_add_i32 s55, s55, 2
	s_add_u32 s22, s22, 0x100
	s_addc_u32 s23, s23, 0
	s_add_u32 s53, s53, 0x100
	s_addc_u32 s54, s54, 0
	s_cmpk_gt_u32 s55, 0xa9
	s_cbranch_scc0 .LBB0_1418
	s_setprio 0
	s_and_b64 vcc, exec, s[14:15]
	s_cbranch_vccz .LBB0_1421
	s_barrier

.LBB0_1564:
	s_add_i32 s92, s92, 1
	s_mov_b32 s18, s12
	s_lshl_b32 s12, s92, 5
	s_add_i32 s12, s12, s3
	s_mov_b64 s[8:9], s[14:15]
	s_lshl_b32 s14, s12, 3
	s_ashr_i32 s13, s12, 2
	s_add_i32 s14, s14, s52
	s_cmpk_lt_i32 s12, 0x50
	s_cselect_b32 s12, s13, s14
	s_mov_b32 s40, s33
	s_cselect_b32 s33, s53, 32
	s_cmp_lt_i32 s12, 20
	s_cselect_b64 s[64:65], -1, 0
	s_lshl_b32 s13, s33, 21
	v_readlane_b32 s14, v250, 46
	s_mov_b64 s[6:7], s[16:17]
	v_readlane_b32 s15, v250, 47
	s_add_u32 s16, s14, s13
	s_addc_u32 s17, s15, 0
	s_and_b64 s[14:15], s[64:65], exec
	s_cselect_b32 s41, s17, s7
	s_cselect_b32 s50, s16, s6
	s_ashr_i32 s13, s12, 31
	s_lshl_b64 s[14:15], s[12:13], 21
	v_readlane_b32 s28, v250, 42
	v_readlane_b32 s29, v250, 43
	s_add_u32 s14, s28, s14
	s_addc_u32 s15, s29, s15
	s_and_b64 s[56:57], s[64:65], exec
	s_cselect_b32 s13, s15, s9
	s_cselect_b32 s51, s14, s8
	s_add_u32 s6, s6, 0x100080
	s_addc_u32 s7, s7, 0
	s_add_u32 s56, s8, 0x100
	s_addc_u32 s57, s9, 0
	s_mov_b32 s66, -2
	s_and_b64 vcc, exec, s[20:21]
	s_cbranch_vccz .Lsp_4
	s_setprio 1
.Lsp_4:
	s_waitcnt lgkmcnt(0)
	ds_read_b128 v[130:133], v204
	ds_read_b128 v[134:137], v204 offset:1024
	ds_read_b128 v[138:141], v204 offset:2048
	ds_read_b128 v[142:145], v204 offset:3072
	ds_read_b128 v[146:149], v205
	ds_read_b128 v[150:153], v205 offset:1024
	ds_read_b128 v[154:157], v205 offset:2048
	ds_read_b128 v[158:161], v205 offset:3072
	s_add_u32 s8, s6, 0xfff00080
	s_addc_u32 s9, s7, -1
	s_cmp_eq_u32 s66, 60
	s_cselect_b32 s73, s41, s9
	s_cselect_b32 s72, s50, s8
	s_cselect_b32 s9, s13, s57
	s_cselect_b32 s8, s51, s56
	s_add_i32 m0, s42, 0xc000
	ds_read_b128 v[184:187], v206
	ds_read_b128 v[188:191], v206 offset:1024
	ds_read_b128 v[192:195], v206 offset:2048
	ds_read_b128 v[210:213], v206 offset:3072
	ds_read_b128 v[214:217], v206 offset:4096
	ds_read_b128 v[218:221], v206 offset:5120
	ds_read_b128 v[222:225], v206 offset:6144
	ds_read_b128 v[226:229], v206 offset:7168
	global_load_lds_dwordx4 v180, s[6:7]
	s_add_i32 m0, s42, 0xe000
	s_nop 0
	global_load_lds_dwordx4 v182, s[6:7]
	s_waitcnt vmcnt(8)
	s_waitcnt lgkmcnt(0)
	s_barrier
	v_mfma_f32_16x16x32_bf16 v[126:129], v[130:133], v[184:187], 0
	v_mfma_f32_16x16x32_bf16 v[126:129], v[134:137], v[188:191], v[126:129]
	v_mfma_f32_16x16x32_bf16 v[122:125], v[142:145], v[188:191], 0
	v_mfma_f32_16x16x32_bf16 v[122:125], v[138:141], v[184:187], v[122:125]
	v_mfma_f32_16x16x32_bf16 v[106:109], v[138:141], v[192:195], 0
	v_mfma_f32_16x16x32_bf16 v[106:109], v[142:145], v[210:213], v[106:109]
	v_mfma_f32_16x16x32_bf16 v[110:113], v[134:137], v[210:213], 0
	v_mfma_f32_16x16x32_bf16 v[110:113], v[130:133], v[192:195], v[110:113]
	v_mfma_f32_16x16x32_bf16 v[94:97], v[130:133], v[214:217], 0
	v_mfma_f32_16x16x32_bf16 v[94:97], v[134:137], v[218:221], v[94:97]
	v_mfma_f32_16x16x32_bf16 v[90:93], v[142:145], v[218:221], 0
	v_mfma_f32_16x16x32_bf16 v[90:93], v[138:141], v[214:217], v[90:93]
	v_mfma_f32_16x16x32_bf16 v[74:77], v[138:141], v[222:225], 0
	v_mfma_f32_16x16x32_bf16 v[74:77], v[142:145], v[226:229], v[74:77]
	v_mfma_f32_16x16x32_bf16 v[78:81], v[134:137], v[226:229], 0
	v_mfma_f32_16x16x32_bf16 v[78:81], v[130:133], v[222:225], v[78:81]
	v_mfma_f32_16x16x32_bf16 v[70:73], v[146:149], v[222:225], 0
	v_mfma_f32_16x16x32_bf16 v[70:73], v[150:153], v[226:229], v[70:73]
	v_mfma_f32_16x16x32_bf16 v[66:69], v[158:161], v[226:229], 0
	v_mfma_f32_16x16x32_bf16 v[66:69], v[154:157], v[222:225], v[66:69]
	v_mfma_f32_16x16x32_bf16 v[82:85], v[154:157], v[214:217], 0
	v_mfma_f32_16x16x32_bf16 v[82:85], v[158:161], v[218:221], v[82:85]
	v_mfma_f32_16x16x32_bf16 v[86:89], v[150:153], v[218:221], 0
	v_mfma_f32_16x16x32_bf16 v[86:89], v[146:149], v[214:217], v[86:89]
	v_mfma_f32_16x16x32_bf16 v[102:105], v[146:149], v[192:195], 0
	v_mfma_f32_16x16x32_bf16 v[102:105], v[150:153], v[210:213], v[102:105]
	v_mfma_f32_16x16x32_bf16 v[98:101], v[158:161], v[210:213], 0
	v_mfma_f32_16x16x32_bf16 v[98:101], v[154:157], v[192:195], v[98:101]
	v_mfma_f32_16x16x32_bf16 v[114:117], v[154:157], v[184:187], 0
	v_mfma_f32_16x16x32_bf16 v[114:117], v[158:161], v[188:191], v[114:117]
	v_mfma_f32_16x16x32_bf16 v[118:121], v[150:153], v[188:191], 0
	v_mfma_f32_16x16x32_bf16 v[118:121], v[146:149], v[184:187], v[118:121]
	s_barrier
	s_add_i32 s67, s54, s35
	s_mov_b32 m0, s67
	ds_read_b128 v[184:187], v206 offset:16384
	ds_read_b128 v[188:191], v206 offset:17408
	ds_read_b128 v[192:195], v206 offset:18432
	ds_read_b128 v[210:213], v206 offset:19456
	ds_read_b128 v[214:217], v206 offset:20480
	ds_read_b128 v[218:221], v206 offset:21504
	ds_read_b128 v[222:225], v206 offset:22528
	ds_read_b128 v[226:229], v206 offset:23552
	global_load_lds_dwordx4 v168, s[8:9]
	s_add_i32 m0, s67, 0x2000
	s_add_u32 s68, s8, 0x100000
	s_addc_u32 s69, s9, 0
	s_add_i32 s67, s55, s35
	global_load_lds_dwordx4 v170, s[8:9]
	s_mov_b32 m0, s67
	s_nop 0
	global_load_lds_dwordx4 v168, s[68:69]
	s_add_i32 m0, s67, 0x2000
	s_nop 0
	global_load_lds_dwordx4 v170, s[68:69]
	s_mov_b32 m0, s42
	s_nop 0
	global_load_lds_dwordx4 v168, s[72:73]
	s_mov_b32 m0, s43
	s_nop 0
	global_load_lds_dwordx4 v170, s[72:73]
	s_waitcnt vmcnt(8)
	s_waitcnt lgkmcnt(0)
	s_barrier
	v_mfma_f32_16x16x32_bf16 v[62:65], v[130:133], v[184:187], 0
	v_mfma_f32_16x16x32_bf16 v[62:65], v[134:137], v[188:191], v[62:65]
	v_mfma_f32_16x16x32_bf16 v[58:61], v[142:145], v[188:191], 0
	v_mfma_f32_16x16x32_bf16 v[58:61], v[138:141], v[184:187], v[58:61]
	v_mfma_f32_16x16x32_bf16 v[42:45], v[138:141], v[192:195], 0
	v_mfma_f32_16x16x32_bf16 v[42:45], v[142:145], v[210:213], v[42:45]
	v_mfma_f32_16x16x32_bf16 v[46:49], v[134:137], v[210:213], 0
	v_mfma_f32_16x16x32_bf16 v[46:49], v[130:133], v[192:195], v[46:49]
	v_mfma_f32_16x16x32_bf16 v[30:33], v[130:133], v[214:217], 0
	v_mfma_f32_16x16x32_bf16 v[30:33], v[134:137], v[218:221], v[30:33]
	v_mfma_f32_16x16x32_bf16 v[26:29], v[142:145], v[218:221], 0
	v_mfma_f32_16x16x32_bf16 v[26:29], v[138:141], v[214:217], v[26:29]
	v_mfma_f32_16x16x32_bf16 v[10:13], v[138:141], v[222:225], 0
	v_mfma_f32_16x16x32_bf16 v[10:13], v[142:145], v[226:229], v[10:13]
	v_mfma_f32_16x16x32_bf16 v[14:17], v[134:137], v[226:229], 0
	v_mfma_f32_16x16x32_bf16 v[14:17], v[130:133], v[222:225], v[14:17]
	v_mfma_f32_16x16x32_bf16 v[6:9], v[146:149], v[222:225], 0
	v_mfma_f32_16x16x32_bf16 v[6:9], v[150:153], v[226:229], v[6:9]
	v_mfma_f32_16x16x32_bf16 v[2:5], v[158:161], v[226:229], 0
	v_mfma_f32_16x16x32_bf16 v[2:5], v[154:157], v[222:225], v[2:5]
	v_mfma_f32_16x16x32_bf16 v[18:21], v[154:157], v[214:217], 0
	v_mfma_f32_16x16x32_bf16 v[18:21], v[158:161], v[218:221], v[18:21]
	v_mfma_f32_16x16x32_bf16 v[22:25], v[150:153], v[218:221], 0
	v_mfma_f32_16x16x32_bf16 v[22:25], v[146:149], v[214:217], v[22:25]
	v_mfma_f32_16x16x32_bf16 v[38:41], v[146:149], v[192:195], 0
	v_mfma_f32_16x16x32_bf16 v[38:41], v[150:153], v[210:213], v[38:41]
	v_mfma_f32_16x16x32_bf16 v[34:37], v[158:161], v[210:213], 0
	v_mfma_f32_16x16x32_bf16 v[34:37], v[154:157], v[192:195], v[34:37]
	v_mfma_f32_16x16x32_bf16 v[50:53], v[154:157], v[184:187], 0
	v_mfma_f32_16x16x32_bf16 v[50:53], v[158:161], v[188:191], v[50:53]
	v_mfma_f32_16x16x32_bf16 v[54:57], v[150:153], v[188:191], 0
	v_mfma_f32_16x16x32_bf16 v[54:57], v[146:149], v[184:187], v[54:57]
	s_barrier
	s_add_i32 s67, 0, 0x18000
	s_add_i32 s70, 0, 0x1c000
	v_add_u32_e32 v142, s67, v203
	v_add_u32_e32 v158, s70, v203
	ds_read_b128 v[130:133], v142
	ds_read_b128 v[134:137], v142 offset:1024
	ds_read_b128 v[138:141], v142 offset:2048
	ds_read_b128 v[142:145], v142 offset:3072
	ds_read_b128 v[146:149], v158
	ds_read_b128 v[150:153], v158 offset:1024
	ds_read_b128 v[154:157], v158 offset:2048
	ds_read_b128 v[158:161], v158 offset:3072
	s_add_u32 s68, s72, 0x100000
	s_addc_u32 s69, s73, 0
	s_mov_b32 m0, s44
	ds_read_b128 v[184:187], v206 offset:32768
	ds_read_b128 v[188:191], v206 offset:33792
	ds_read_b128 v[192:195], v206 offset:34816
	ds_read_b128 v[210:213], v206 offset:35840
	ds_read_b128 v[214:217], v206 offset:36864
	ds_read_b128 v[218:221], v206 offset:37888
	ds_read_b128 v[222:225], v206 offset:38912
	ds_read_b128 v[226:229], v206 offset:39936
	global_load_lds_dwordx4 v168, s[68:69]
	s_mov_b32 m0, s45
	s_nop 0
	global_load_lds_dwordx4 v170, s[68:69]
	s_waitcnt vmcnt(8)
	s_waitcnt lgkmcnt(0)
	s_barrier
	v_mfma_f32_16x16x32_bf16 v[126:129], v[130:133], v[184:187], v[126:129]
	v_mfma_f32_16x16x32_bf16 v[126:129], v[134:137], v[188:191], v[126:129]
	v_mfma_f32_16x16x32_bf16 v[122:125], v[142:145], v[188:191], v[122:125]
	v_mfma_f32_16x16x32_bf16 v[122:125], v[138:141], v[184:187], v[122:125]
	v_mfma_f32_16x16x32_bf16 v[106:109], v[138:141], v[192:195], v[106:109]
	v_mfma_f32_16x16x32_bf16 v[106:109], v[142:145], v[210:213], v[106:109]
	v_mfma_f32_16x16x32_bf16 v[110:113], v[134:137], v[210:213], v[110:113]
	v_mfma_f32_16x16x32_bf16 v[110:113], v[130:133], v[192:195], v[110:113]
	v_mfma_f32_16x16x32_bf16 v[94:97], v[130:133], v[214:217], v[94:97]
	v_mfma_f32_16x16x32_bf16 v[94:97], v[134:137], v[218:221], v[94:97]
	v_mfma_f32_16x16x32_bf16 v[90:93], v[142:145], v[218:221], v[90:93]
	v_mfma_f32_16x16x32_bf16 v[90:93], v[138:141], v[214:217], v[90:93]
	v_mfma_f32_16x16x32_bf16 v[74:77], v[138:141], v[222:225], v[74:77]
	v_mfma_f32_16x16x32_bf16 v[74:77], v[142:145], v[226:229], v[74:77]
	v_mfma_f32_16x16x32_bf16 v[78:81], v[134:137], v[226:229], v[78:81]
	v_mfma_f32_16x16x32_bf16 v[78:81], v[130:133], v[222:225], v[78:81]
	v_mfma_f32_16x16x32_bf16 v[70:73], v[146:149], v[222:225], v[70:73]
	v_mfma_f32_16x16x32_bf16 v[70:73], v[150:153], v[226:229], v[70:73]
	v_mfma_f32_16x16x32_bf16 v[66:69], v[158:161], v[226:229], v[66:69]
	v_mfma_f32_16x16x32_bf16 v[66:69], v[154:157], v[222:225], v[66:69]
	v_mfma_f32_16x16x32_bf16 v[82:85], v[154:157], v[214:217], v[82:85]
	v_mfma_f32_16x16x32_bf16 v[82:85], v[158:161], v[218:221], v[82:85]
	v_mfma_f32_16x16x32_bf16 v[86:89], v[150:153], v[218:221], v[86:89]
	v_mfma_f32_16x16x32_bf16 v[86:89], v[146:149], v[214:217], v[86:89]
	v_mfma_f32_16x16x32_bf16 v[102:105], v[146:149], v[192:195], v[102:105]
	v_mfma_f32_16x16x32_bf16 v[102:105], v[150:153], v[210:213], v[102:105]
	v_mfma_f32_16x16x32_bf16 v[98:101], v[158:161], v[210:213], v[98:101]
	v_mfma_f32_16x16x32_bf16 v[98:101], v[154:157], v[192:195], v[98:101]
	v_mfma_f32_16x16x32_bf16 v[114:117], v[154:157], v[184:187], v[114:117]
	v_mfma_f32_16x16x32_bf16 v[114:117], v[158:161], v[188:191], v[114:117]
	v_mfma_f32_16x16x32_bf16 v[118:121], v[150:153], v[188:191], v[118:121]
	v_mfma_f32_16x16x32_bf16 v[118:121], v[146:149], v[184:187], v[118:121]
	s_barrier
	s_add_u32 s68, s72, 0x80
	s_addc_u32 s69, s73, 0
	s_add_u32 s8, s8, 0x80
	s_addc_u32 s9, s9, 0
	s_add_i32 s67, s67, s35
	s_mov_b32 m0, s67
	ds_read_b128 v[184:187], v206 offset:49152
	ds_read_b128 v[188:191], v206 offset:50176
	ds_read_b128 v[192:195], v206 offset:51200
	ds_read_b128 v[210:213], v206 offset:52224
	ds_read_b128 v[214:217], v206 offset:53248
	ds_read_b128 v[218:221], v206 offset:54272
	ds_read_b128 v[222:225], v206 offset:55296
	ds_read_b128 v[226:229], v206 offset:56320
	global_load_lds_dwordx4 v168, s[8:9]
	s_add_i32 m0, s67, 0x2000
	s_add_i32 s67, s70, s35
	global_load_lds_dwordx4 v170, s[8:9]
	s_add_u32 s8, s8, 0x100000
	s_addc_u32 s9, s9, 0
	s_mov_b32 m0, s67
	s_nop 0
	global_load_lds_dwordx4 v168, s[8:9]
	s_add_i32 m0, s67, 0x2000
	s_nop 0
	global_load_lds_dwordx4 v170, s[8:9]
	s_mov_b32 m0, s48
	s_nop 0
	global_load_lds_dwordx4 v168, s[68:69]
	s_mov_b32 m0, s49
	s_nop 0
	global_load_lds_dwordx4 v170, s[68:69]
	s_waitcnt vmcnt(8)
	s_waitcnt lgkmcnt(0)
	s_barrier
	v_mfma_f32_16x16x32_bf16 v[62:65], v[130:133], v[184:187], v[62:65]
	v_mfma_f32_16x16x32_bf16 v[62:65], v[134:137], v[188:191], v[62:65]
	v_mfma_f32_16x16x32_bf16 v[58:61], v[142:145], v[188:191], v[58:61]
	v_mfma_f32_16x16x32_bf16 v[58:61], v[138:141], v[184:187], v[58:61]
	v_mfma_f32_16x16x32_bf16 v[42:45], v[138:141], v[192:195], v[42:45]
	v_mfma_f32_16x16x32_bf16 v[42:45], v[142:145], v[210:213], v[42:45]
	v_mfma_f32_16x16x32_bf16 v[46:49], v[134:137], v[210:213], v[46:49]
	v_mfma_f32_16x16x32_bf16 v[46:49], v[130:133], v[192:195], v[46:49]
	v_mfma_f32_16x16x32_bf16 v[30:33], v[130:133], v[214:217], v[30:33]
	v_mfma_f32_16x16x32_bf16 v[30:33], v[134:137], v[218:221], v[30:33]
	v_mfma_f32_16x16x32_bf16 v[26:29], v[142:145], v[218:221], v[26:29]
	v_mfma_f32_16x16x32_bf16 v[26:29], v[138:141], v[214:217], v[26:29]
	v_mfma_f32_16x16x32_bf16 v[10:13], v[138:141], v[222:225], v[10:13]
	v_mfma_f32_16x16x32_bf16 v[10:13], v[142:145], v[226:229], v[10:13]
	v_mfma_f32_16x16x32_bf16 v[14:17], v[134:137], v[226:229], v[14:17]
	v_mfma_f32_16x16x32_bf16 v[14:17], v[130:133], v[222:225], v[14:17]
	v_mfma_f32_16x16x32_bf16 v[6:9], v[146:149], v[222:225], v[6:9]
	v_mfma_f32_16x16x32_bf16 v[6:9], v[150:153], v[226:229], v[6:9]
	v_mfma_f32_16x16x32_bf16 v[2:5], v[158:161], v[226:229], v[2:5]
	v_mfma_f32_16x16x32_bf16 v[2:5], v[154:157], v[222:225], v[2:5]
	v_mfma_f32_16x16x32_bf16 v[18:21], v[154:157], v[214:217], v[18:21]
	v_mfma_f32_16x16x32_bf16 v[18:21], v[158:161], v[218:221], v[18:21]
	v_mfma_f32_16x16x32_bf16 v[22:25], v[150:153], v[218:221], v[22:25]
	v_mfma_f32_16x16x32_bf16 v[22:25], v[146:149], v[214:217], v[22:25]
	v_mfma_f32_16x16x32_bf16 v[38:41], v[146:149], v[192:195], v[38:41]
	v_mfma_f32_16x16x32_bf16 v[38:41], v[150:153], v[210:213], v[38:41]
	v_mfma_f32_16x16x32_bf16 v[34:37], v[158:161], v[210:213], v[34:37]
	v_mfma_f32_16x16x32_bf16 v[34:37], v[154:157], v[192:195], v[34:37]
	v_mfma_f32_16x16x32_bf16 v[50:53], v[154:157], v[184:187], v[50:53]
	v_mfma_f32_16x16x32_bf16 v[50:53], v[158:161], v[188:191], v[50:53]
	v_mfma_f32_16x16x32_bf16 v[54:57], v[150:153], v[188:191], v[54:57]
	v_mfma_f32_16x16x32_bf16 v[54:57], v[146:149], v[184:187], v[54:57]
	s_barrier
	s_add_i32 s66, s66, 2
	s_add_u32 s6, s6, 0x100
	s_addc_u32 s7, s7, 0
	s_add_u32 s56, s56, 0x100
	s_addc_u32 s57, s57, 0
.LBB0_1565:
	ds_read_b128 v[130:133], v204
	ds_read_b128 v[134:137], v204 offset:1024
	ds_read_b128 v[138:141], v204 offset:2048
	ds_read_b128 v[142:145], v204 offset:3072
	ds_read_b128 v[146:149], v205
	ds_read_b128 v[150:153], v205 offset:1024
	ds_read_b128 v[154:157], v205 offset:2048
	ds_read_b128 v[158:161], v205 offset:3072
	s_add_u32 s8, s6, 0xfff00080
	s_addc_u32 s9, s7, -1
	s_cmp_eq_u32 s66, 60
	s_cselect_b32 s73, s41, s9
	s_cselect_b32 s72, s50, s8
	s_cselect_b32 s9, s13, s57
	s_cselect_b32 s8, s51, s56
	s_add_i32 m0, s42, 0xc000
	ds_read_b128 v[184:187], v206
	ds_read_b128 v[188:191], v206 offset:1024
	ds_read_b128 v[192:195], v206 offset:2048
	ds_read_b128 v[210:213], v206 offset:3072
	ds_read_b128 v[214:217], v206 offset:4096
	ds_read_b128 v[218:221], v206 offset:5120
	ds_read_b128 v[222:225], v206 offset:6144
	ds_read_b128 v[226:229], v206 offset:7168
	global_load_lds_dwordx4 v180, s[6:7]
	s_add_i32 m0, s42, 0xe000
	s_nop 0
	global_load_lds_dwordx4 v182, s[6:7]
	s_waitcnt vmcnt(8)
	s_waitcnt lgkmcnt(0)
	s_barrier
	v_mfma_f32_16x16x32_bf16 v[126:129], v[130:133], v[184:187], v[126:129]
	v_mfma_f32_16x16x32_bf16 v[126:129], v[134:137], v[188:191], v[126:129]
	v_mfma_f32_16x16x32_bf16 v[122:125], v[142:145], v[188:191], v[122:125]
	v_mfma_f32_16x16x32_bf16 v[122:125], v[138:141], v[184:187], v[122:125]
	v_mfma_f32_16x16x32_bf16 v[106:109], v[138:141], v[192:195], v[106:109]
	v_mfma_f32_16x16x32_bf16 v[106:109], v[142:145], v[210:213], v[106:109]
	v_mfma_f32_16x16x32_bf16 v[110:113], v[134:137], v[210:213], v[110:113]
	v_mfma_f32_16x16x32_bf16 v[110:113], v[130:133], v[192:195], v[110:113]
	v_mfma_f32_16x16x32_bf16 v[94:97], v[130:133], v[214:217], v[94:97]
	v_mfma_f32_16x16x32_bf16 v[94:97], v[134:137], v[218:221], v[94:97]
	v_mfma_f32_16x16x32_bf16 v[90:93], v[142:145], v[218:221], v[90:93]
	v_mfma_f32_16x16x32_bf16 v[90:93], v[138:141], v[214:217], v[90:93]
	v_mfma_f32_16x16x32_bf16 v[74:77], v[138:141], v[222:225], v[74:77]
	v_mfma_f32_16x16x32_bf16 v[74:77], v[142:145], v[226:229], v[74:77]
	v_mfma_f32_16x16x32_bf16 v[78:81], v[134:137], v[226:229], v[78:81]
	v_mfma_f32_16x16x32_bf16 v[78:81], v[130:133], v[222:225], v[78:81]
	v_mfma_f32_16x16x32_bf16 v[70:73], v[146:149], v[222:225], v[70:73]
	v_mfma_f32_16x16x32_bf16 v[70:73], v[150:153], v[226:229], v[70:73]
	v_mfma_f32_16x16x32_bf16 v[66:69], v[158:161], v[226:229], v[66:69]
	v_mfma_f32_16x16x32_bf16 v[66:69], v[154:157], v[222:225], v[66:69]
	v_mfma_f32_16x16x32_bf16 v[82:85], v[154:157], v[214:217], v[82:85]
	v_mfma_f32_16x16x32_bf16 v[82:85], v[158:161], v[218:221], v[82:85]
	v_mfma_f32_16x16x32_bf16 v[86:89], v[150:153], v[218:221], v[86:89]
	v_mfma_f32_16x16x32_bf16 v[86:89], v[146:149], v[214:217], v[86:89]
	v_mfma_f32_16x16x32_bf16 v[102:105], v[146:149], v[192:195], v[102:105]
	v_mfma_f32_16x16x32_bf16 v[102:105], v[150:153], v[210:213], v[102:105]
	v_mfma_f32_16x16x32_bf16 v[98:101], v[158:161], v[210:213], v[98:101]
	v_mfma_f32_16x16x32_bf16 v[98:101], v[154:157], v[192:195], v[98:101]
	v_mfma_f32_16x16x32_bf16 v[114:117], v[154:157], v[184:187], v[114:117]
	v_mfma_f32_16x16x32_bf16 v[114:117], v[158:161], v[188:191], v[114:117]
	v_mfma_f32_16x16x32_bf16 v[118:121], v[150:153], v[188:191], v[118:121]
	v_mfma_f32_16x16x32_bf16 v[118:121], v[146:149], v[184:187], v[118:121]
	s_barrier
	s_add_i32 s67, s54, s35
	s_mov_b32 m0, s67
	ds_read_b128 v[184:187], v206 offset:16384
	ds_read_b128 v[188:191], v206 offset:17408
	ds_read_b128 v[192:195], v206 offset:18432
	ds_read_b128 v[210:213], v206 offset:19456
	ds_read_b128 v[214:217], v206 offset:20480
	ds_read_b128 v[218:221], v206 offset:21504
	ds_read_b128 v[222:225], v206 offset:22528
	ds_read_b128 v[226:229], v206 offset:23552
	global_load_lds_dwordx4 v168, s[8:9]
	s_add_i32 m0, s67, 0x2000
	s_add_u32 s68, s8, 0x100000
	s_addc_u32 s69, s9, 0
	s_add_i32 s67, s55, s35
	global_load_lds_dwordx4 v170, s[8:9]
	s_mov_b32 m0, s67
	s_nop 0
	global_load_lds_dwordx4 v168, s[68:69]
	s_add_i32 m0, s67, 0x2000
	s_nop 0
	global_load_lds_dwordx4 v170, s[68:69]
	s_mov_b32 m0, s42
	s_nop 0
	global_load_lds_dwordx4 v168, s[72:73]
	s_mov_b32 m0, s43
	s_nop 0
	global_load_lds_dwordx4 v170, s[72:73]
	s_waitcnt vmcnt(8)
	s_waitcnt lgkmcnt(0)
	s_barrier
	v_mfma_f32_16x16x32_bf16 v[62:65], v[130:133], v[184:187], v[62:65]
	v_mfma_f32_16x16x32_bf16 v[62:65], v[134:137], v[188:191], v[62:65]
	v_mfma_f32_16x16x32_bf16 v[58:61], v[142:145], v[188:191], v[58:61]
	v_mfma_f32_16x16x32_bf16 v[58:61], v[138:141], v[184:187], v[58:61]
	v_mfma_f32_16x16x32_bf16 v[42:45], v[138:141], v[192:195], v[42:45]
	v_mfma_f32_16x16x32_bf16 v[42:45], v[142:145], v[210:213], v[42:45]
	v_mfma_f32_16x16x32_bf16 v[46:49], v[134:137], v[210:213], v[46:49]
	v_mfma_f32_16x16x32_bf16 v[46:49], v[130:133], v[192:195], v[46:49]
	v_mfma_f32_16x16x32_bf16 v[30:33], v[130:133], v[214:217], v[30:33]
	v_mfma_f32_16x16x32_bf16 v[30:33], v[134:137], v[218:221], v[30:33]
	v_mfma_f32_16x16x32_bf16 v[26:29], v[142:145], v[218:221], v[26:29]
	v_mfma_f32_16x16x32_bf16 v[26:29], v[138:141], v[214:217], v[26:29]
	v_mfma_f32_16x16x32_bf16 v[10:13], v[138:141], v[222:225], v[10:13]
	v_mfma_f32_16x16x32_bf16 v[10:13], v[142:145], v[226:229], v[10:13]
	v_mfma_f32_16x16x32_bf16 v[14:17], v[134:137], v[226:229], v[14:17]
	v_mfma_f32_16x16x32_bf16 v[14:17], v[130:133], v[222:225], v[14:17]
	v_mfma_f32_16x16x32_bf16 v[6:9], v[146:149], v[222:225], v[6:9]
	v_mfma_f32_16x16x32_bf16 v[6:9], v[150:153], v[226:229], v[6:9]
	v_mfma_f32_16x16x32_bf16 v[2:5], v[158:161], v[226:229], v[2:5]
	v_mfma_f32_16x16x32_bf16 v[2:5], v[154:157], v[222:225], v[2:5]
	v_mfma_f32_16x16x32_bf16 v[18:21], v[154:157], v[214:217], v[18:21]
	v_mfma_f32_16x16x32_bf16 v[18:21], v[158:161], v[218:221], v[18:21]
	v_mfma_f32_16x16x32_bf16 v[22:25], v[150:153], v[218:221], v[22:25]
	v_mfma_f32_16x16x32_bf16 v[22:25], v[146:149], v[214:217], v[22:25]
	v_mfma_f32_16x16x32_bf16 v[38:41], v[146:149], v[192:195], v[38:41]
	v_mfma_f32_16x16x32_bf16 v[38:41], v[150:153], v[210:213], v[38:41]
	v_mfma_f32_16x16x32_bf16 v[34:37], v[158:161], v[210:213], v[34:37]
	v_mfma_f32_16x16x32_bf16 v[34:37], v[154:157], v[192:195], v[34:37]
	v_mfma_f32_16x16x32_bf16 v[50:53], v[154:157], v[184:187], v[50:53]
	v_mfma_f32_16x16x32_bf16 v[50:53], v[158:161], v[188:191], v[50:53]
	v_mfma_f32_16x16x32_bf16 v[54:57], v[150:153], v[188:191], v[54:57]
	v_mfma_f32_16x16x32_bf16 v[54:57], v[146:149], v[184:187], v[54:57]
	s_barrier
	s_add_i32 s67, 0, 0x18000
	s_add_i32 s70, 0, 0x1c000
	v_add_u32_e32 v142, s67, v203
	v_add_u32_e32 v158, s70, v203
	ds_read_b128 v[130:133], v142
	ds_read_b128 v[134:137], v142 offset:1024
	ds_read_b128 v[138:141], v142 offset:2048
	ds_read_b128 v[142:145], v142 offset:3072
	ds_read_b128 v[146:149], v158
	ds_read_b128 v[150:153], v158 offset:1024
	ds_read_b128 v[154:157], v158 offset:2048
	ds_read_b128 v[158:161], v158 offset:3072
	s_add_u32 s68, s72, 0x100000
	s_addc_u32 s69, s73, 0
	s_mov_b32 m0, s44
	ds_read_b128 v[184:187], v206 offset:32768
	ds_read_b128 v[188:191], v206 offset:33792
	ds_read_b128 v[192:195], v206 offset:34816
	ds_read_b128 v[210:213], v206 offset:35840
	ds_read_b128 v[214:217], v206 offset:36864
	ds_read_b128 v[218:221], v206 offset:37888
	ds_read_b128 v[222:225], v206 offset:38912
	ds_read_b128 v[226:229], v206 offset:39936
	global_load_lds_dwordx4 v168, s[68:69]
	s_mov_b32 m0, s45
	s_nop 0
	global_load_lds_dwordx4 v170, s[68:69]
	s_waitcnt vmcnt(8)
	s_waitcnt lgkmcnt(0)
	s_barrier
	v_mfma_f32_16x16x32_bf16 v[126:129], v[130:133], v[184:187], v[126:129]
	v_mfma_f32_16x16x32_bf16 v[126:129], v[134:137], v[188:191], v[126:129]
	v_mfma_f32_16x16x32_bf16 v[122:125], v[142:145], v[188:191], v[122:125]
	v_mfma_f32_16x16x32_bf16 v[122:125], v[138:141], v[184:187], v[122:125]
	v_mfma_f32_16x16x32_bf16 v[106:109], v[138:141], v[192:195], v[106:109]
	v_mfma_f32_16x16x32_bf16 v[106:109], v[142:145], v[210:213], v[106:109]
	v_mfma_f32_16x16x32_bf16 v[110:113], v[134:137], v[210:213], v[110:113]
	v_mfma_f32_16x16x32_bf16 v[110:113], v[130:133], v[192:195], v[110:113]
	v_mfma_f32_16x16x32_bf16 v[94:97], v[130:133], v[214:217], v[94:97]
	v_mfma_f32_16x16x32_bf16 v[94:97], v[134:137], v[218:221], v[94:97]
	v_mfma_f32_16x16x32_bf16 v[90:93], v[142:145], v[218:221], v[90:93]
	v_mfma_f32_16x16x32_bf16 v[90:93], v[138:141], v[214:217], v[90:93]
	v_mfma_f32_16x16x32_bf16 v[74:77], v[138:141], v[222:225], v[74:77]
	v_mfma_f32_16x16x32_bf16 v[74:77], v[142:145], v[226:229], v[74:77]
	v_mfma_f32_16x16x32_bf16 v[78:81], v[134:137], v[226:229], v[78:81]
	v_mfma_f32_16x16x32_bf16 v[78:81], v[130:133], v[222:225], v[78:81]
	v_mfma_f32_16x16x32_bf16 v[70:73], v[146:149], v[222:225], v[70:73]
	v_mfma_f32_16x16x32_bf16 v[70:73], v[150:153], v[226:229], v[70:73]
	v_mfma_f32_16x16x32_bf16 v[66:69], v[158:161], v[226:229], v[66:69]
	v_mfma_f32_16x16x32_bf16 v[66:69], v[154:157], v[222:225], v[66:69]
	v_mfma_f32_16x16x32_bf16 v[82:85], v[154:157], v[214:217], v[82:85]
	v_mfma_f32_16x16x32_bf16 v[82:85], v[158:161], v[218:221], v[82:85]
	v_mfma_f32_16x16x32_bf16 v[86:89], v[150:153], v[218:221], v[86:89]
	v_mfma_f32_16x16x32_bf16 v[86:89], v[146:149], v[214:217], v[86:89]
	v_mfma_f32_16x16x32_bf16 v[102:105], v[146:149], v[192:195], v[102:105]
	v_mfma_f32_16x16x32_bf16 v[102:105], v[150:153], v[210:213], v[102:105]
	v_mfma_f32_16x16x32_bf16 v[98:101], v[158:161], v[210:213], v[98:101]
	v_mfma_f32_16x16x32_bf16 v[98:101], v[154:157], v[192:195], v[98:101]
	v_mfma_f32_16x16x32_bf16 v[114:117], v[154:157], v[184:187], v[114:117]
	v_mfma_f32_16x16x32_bf16 v[114:117], v[158:161], v[188:191], v[114:117]
	v_mfma_f32_16x16x32_bf16 v[118:121], v[150:153], v[188:191], v[118:121]
	v_mfma_f32_16x16x32_bf16 v[118:121], v[146:149], v[184:187], v[118:121]
	s_barrier
	s_add_u32 s68, s72, 0x80
	s_addc_u32 s69, s73, 0
	s_add_u32 s8, s8, 0x80
	s_addc_u32 s9, s9, 0
	s_add_i32 s67, s67, s35
	s_mov_b32 m0, s67
	ds_read_b128 v[184:187], v206 offset:49152
	ds_read_b128 v[188:191], v206 offset:50176
	ds_read_b128 v[192:195], v206 offset:51200
	ds_read_b128 v[210:213], v206 offset:52224
	ds_read_b128 v[214:217], v206 offset:53248
	ds_read_b128 v[218:221], v206 offset:54272
	ds_read_b128 v[222:225], v206 offset:55296
	ds_read_b128 v[226:229], v206 offset:56320
	global_load_lds_dwordx4 v168, s[8:9]
	s_add_i32 m0, s67, 0x2000
	s_add_i32 s67, s70, s35
	global_load_lds_dwordx4 v170, s[8:9]
	s_add_u32 s8, s8, 0x100000
	s_addc_u32 s9, s9, 0
	s_mov_b32 m0, s67
	s_nop 0
	global_load_lds_dwordx4 v168, s[8:9]
	s_add_i32 m0, s67, 0x2000
	s_nop 0
	global_load_lds_dwordx4 v170, s[8:9]
	s_mov_b32 m0, s48
	s_nop 0
	global_load_lds_dwordx4 v168, s[68:69]
	s_mov_b32 m0, s49
	s_nop 0
	global_load_lds_dwordx4 v170, s[68:69]
	s_waitcnt vmcnt(8)
	s_waitcnt lgkmcnt(0)
	s_barrier
	v_mfma_f32_16x16x32_bf16 v[62:65], v[130:133], v[184:187], v[62:65]
	v_mfma_f32_16x16x32_bf16 v[62:65], v[134:137], v[188:191], v[62:65]
	v_mfma_f32_16x16x32_bf16 v[58:61], v[142:145], v[188:191], v[58:61]
	v_mfma_f32_16x16x32_bf16 v[58:61], v[138:141], v[184:187], v[58:61]
	v_mfma_f32_16x16x32_bf16 v[42:45], v[138:141], v[192:195], v[42:45]
	v_mfma_f32_16x16x32_bf16 v[42:45], v[142:145], v[210:213], v[42:45]
	v_mfma_f32_16x16x32_bf16 v[46:49], v[134:137], v[210:213], v[46:49]
	v_mfma_f32_16x16x32_bf16 v[46:49], v[130:133], v[192:195], v[46:49]
	v_mfma_f32_16x16x32_bf16 v[30:33], v[130:133], v[214:217], v[30:33]
	v_mfma_f32_16x16x32_bf16 v[30:33], v[134:137], v[218:221], v[30:33]
	v_mfma_f32_16x16x32_bf16 v[26:29], v[142:145], v[218:221], v[26:29]
	v_mfma_f32_16x16x32_bf16 v[26:29], v[138:141], v[214:217], v[26:29]
	v_mfma_f32_16x16x32_bf16 v[10:13], v[138:141], v[222:225], v[10:13]
	v_mfma_f32_16x16x32_bf16 v[10:13], v[142:145], v[226:229], v[10:13]
	v_mfma_f32_16x16x32_bf16 v[14:17], v[134:137], v[226:229], v[14:17]
	v_mfma_f32_16x16x32_bf16 v[14:17], v[130:133], v[222:225], v[14:17]
	v_mfma_f32_16x16x32_bf16 v[6:9], v[146:149], v[222:225], v[6:9]
	v_mfma_f32_16x16x32_bf16 v[6:9], v[150:153], v[226:229], v[6:9]
	v_mfma_f32_16x16x32_bf16 v[2:5], v[158:161], v[226:229], v[2:5]
	v_mfma_f32_16x16x32_bf16 v[2:5], v[154:157], v[222:225], v[2:5]
	v_mfma_f32_16x16x32_bf16 v[18:21], v[154:157], v[214:217], v[18:21]
	v_mfma_f32_16x16x32_bf16 v[18:21], v[158:161], v[218:221], v[18:21]
	v_mfma_f32_16x16x32_bf16 v[22:25], v[150:153], v[218:221], v[22:25]
	v_mfma_f32_16x16x32_bf16 v[22:25], v[146:149], v[214:217], v[22:25]
	v_mfma_f32_16x16x32_bf16 v[38:41], v[146:149], v[192:195], v[38:41]
	v_mfma_f32_16x16x32_bf16 v[38:41], v[150:153], v[210:213], v[38:41]
	v_mfma_f32_16x16x32_bf16 v[34:37], v[158:161], v[210:213], v[34:37]
	v_mfma_f32_16x16x32_bf16 v[34:37], v[154:157], v[192:195], v[34:37]
	v_mfma_f32_16x16x32_bf16 v[50:53], v[154:157], v[184:187], v[50:53]
	v_mfma_f32_16x16x32_bf16 v[50:53], v[158:161], v[188:191], v[50:53]
	v_mfma_f32_16x16x32_bf16 v[54:57], v[150:153], v[188:191], v[54:57]
	v_mfma_f32_16x16x32_bf16 v[54:57], v[146:149], v[184:187], v[54:57]
	s_barrier
	s_add_i32 s66, s66, 2
	s_add_u32 s6, s6, 0x100
	s_addc_u32 s7, s7, 0
	s_add_u32 s56, s56, 0x100
	s_addc_u32 s57, s57, 0
	s_cmp_gt_u32 s66, 61
	s_cbranch_scc0 .LBB0_1565
	s_setprio 0
	s_and_b64 vcc, exec, s[24:25]
	s_cbranch_vccz .LBB0_1568
	s_barrier

.LBB0_2229:
	s_add_i32 s35, s35, 1
	s_lshl_b32 s7, s35, 5
	s_add_i32 s7, s7, s3
	s_ashr_i32 s19, s7, 2
	s_cmp_lt_i32 s19, 16
	s_mov_b64 s[24:25], s[8:9]
	s_cselect_b64 s[8:9], -1, 0
	s_cmp_lt_i32 s7, 64
	s_mov_b64 s[22:23], s[10:11]
	s_cselect_b64 s[10:11], -1, 0
	s_and_b64 s[20:21], s[10:11], exec
	s_mov_b32 s43, s18
	s_cselect_b32 s18, s29, s18
	s_mov_b32 s42, s6
	s_cselect_b32 s6, s19, s6
	s_ashr_i32 s19, s18, 31
	s_and_b64 s[20:21], s[10:11], s[8:9]
	s_lshl_b64 s[8:9], s[18:19], 21
	v_readlane_b32 s0, v250, 46
	v_readlane_b32 s1, v250, 47
	s_add_u32 s10, s0, s8
	s_addc_u32 s11, s1, s9
	s_and_b64 s[8:9], s[20:21], exec
	s_cselect_b32 s19, s11, s23
	s_cselect_b32 s44, s10, s22
	s_ashr_i32 s7, s6, 31
	s_lshl_b64 s[8:9], s[6:7], 21
	v_readlane_b32 s0, v250, 44
	v_readlane_b32 s1, v250, 45
	s_add_u32 s8, s0, s8
	s_addc_u32 s9, s1, s9
	s_and_b64 s[26:27], s[20:21], exec
	s_cselect_b32 s7, s9, s25
	s_cselect_b32 s45, s8, s24
	s_add_u32 s22, s22, 0x100080
	s_addc_u32 s23, s23, 0
	s_add_u32 s46, s24, 0x100
	s_addc_u32 s47, s25, 0
	s_mov_b32 s48, -2
	s_and_b64 vcc, exec, s[12:13]
	s_cbranch_vccz .Lsp_5
	s_setprio 1
.Lsp_5:
	s_waitcnt lgkmcnt(0)
	ds_read_b128 v[142:145], v154
	ds_read_b128 v[158:161], v154 offset:1024
	ds_read_b128 v[168:171], v154 offset:2048
	ds_read_b128 v[176:179], v154 offset:3072
	ds_read_b128 v[180:183], v155
	ds_read_b128 v[184:187], v155 offset:1024
	ds_read_b128 v[188:191], v155 offset:2048
	ds_read_b128 v[192:195], v155 offset:3072
	s_add_u32 s24, s22, 0xfff00080
	s_addc_u32 s25, s23, -1
	s_cmp_eq_u32 s48, 60
	s_cselect_b32 s27, s19, s25
	s_cselect_b32 s26, s44, s24
	s_cselect_b32 s25, s7, s47
	s_cselect_b32 s24, s45, s46
	s_mov_b32 m0, s40
	ds_read_b128 v[204:207], v156
	ds_read_b128 v[208:211], v156 offset:1024
	ds_read_b128 v[212:215], v156 offset:2048
	ds_read_b128 v[216:219], v156 offset:3072
	ds_read_b128 v[220:223], v156 offset:4096
	ds_read_b128 v[224:227], v156 offset:5120
	ds_read_b128 v[228:231], v156 offset:6144
	ds_read_b128 v[232:235], v156 offset:7168
	global_load_lds_dwordx4 v138, s[22:23]
	s_mov_b32 m0, s41
	s_nop 0
	global_load_lds_dwordx4 v140, s[22:23]
	s_waitcnt vmcnt(8)
	s_waitcnt lgkmcnt(0)
	s_barrier
	v_mfma_f32_16x16x32_bf16 v[126:129], v[142:145], v[204:207], 0
	v_mfma_f32_16x16x32_bf16 v[126:129], v[158:161], v[208:211], v[126:129]
	v_mfma_f32_16x16x32_bf16 v[122:125], v[176:179], v[208:211], 0
	v_mfma_f32_16x16x32_bf16 v[122:125], v[168:171], v[204:207], v[122:125]
	v_mfma_f32_16x16x32_bf16 v[106:109], v[168:171], v[212:215], 0
	v_mfma_f32_16x16x32_bf16 v[106:109], v[176:179], v[216:219], v[106:109]
	v_mfma_f32_16x16x32_bf16 v[110:113], v[158:161], v[216:219], 0
	v_mfma_f32_16x16x32_bf16 v[110:113], v[142:145], v[212:215], v[110:113]
	v_mfma_f32_16x16x32_bf16 v[94:97], v[142:145], v[220:223], 0
	v_mfma_f32_16x16x32_bf16 v[94:97], v[158:161], v[224:227], v[94:97]
	v_mfma_f32_16x16x32_bf16 v[90:93], v[176:179], v[224:227], 0
	v_mfma_f32_16x16x32_bf16 v[90:93], v[168:171], v[220:223], v[90:93]
	v_mfma_f32_16x16x32_bf16 v[74:77], v[168:171], v[228:231], 0
	v_mfma_f32_16x16x32_bf16 v[74:77], v[176:179], v[232:235], v[74:77]
	v_mfma_f32_16x16x32_bf16 v[78:81], v[158:161], v[232:235], 0
	v_mfma_f32_16x16x32_bf16 v[78:81], v[142:145], v[228:231], v[78:81]
	v_mfma_f32_16x16x32_bf16 v[70:73], v[180:183], v[228:231], 0
	v_mfma_f32_16x16x32_bf16 v[70:73], v[184:187], v[232:235], v[70:73]
	v_mfma_f32_16x16x32_bf16 v[66:69], v[192:195], v[232:235], 0
	v_mfma_f32_16x16x32_bf16 v[66:69], v[188:191], v[228:231], v[66:69]
	v_mfma_f32_16x16x32_bf16 v[82:85], v[188:191], v[220:223], 0
	v_mfma_f32_16x16x32_bf16 v[82:85], v[192:195], v[224:227], v[82:85]
	v_mfma_f32_16x16x32_bf16 v[86:89], v[184:187], v[224:227], 0
	v_mfma_f32_16x16x32_bf16 v[86:89], v[180:183], v[220:223], v[86:89]
	v_mfma_f32_16x16x32_bf16 v[102:105], v[180:183], v[212:215], 0
	v_mfma_f32_16x16x32_bf16 v[102:105], v[184:187], v[216:219], v[102:105]
	v_mfma_f32_16x16x32_bf16 v[98:101], v[192:195], v[216:219], 0
	v_mfma_f32_16x16x32_bf16 v[98:101], v[188:191], v[212:215], v[98:101]
	v_mfma_f32_16x16x32_bf16 v[114:117], v[188:191], v[204:207], 0
	v_mfma_f32_16x16x32_bf16 v[114:117], v[192:195], v[208:211], v[114:117]
	v_mfma_f32_16x16x32_bf16 v[118:121], v[184:187], v[208:211], 0
	v_mfma_f32_16x16x32_bf16 v[118:121], v[180:183], v[204:207], v[118:121]
	s_barrier
	s_add_i32 s49, s38, s28
	s_mov_b32 m0, s49
	ds_read_b128 v[204:207], v156 offset:16384
	ds_read_b128 v[208:211], v156 offset:17408
	ds_read_b128 v[212:215], v156 offset:18432
	ds_read_b128 v[216:219], v156 offset:19456
	ds_read_b128 v[220:223], v156 offset:20480
	ds_read_b128 v[224:227], v156 offset:21504
	ds_read_b128 v[228:231], v156 offset:22528
	ds_read_b128 v[232:235], v156 offset:23552
	global_load_lds_dwordx4 v132, s[24:25]
	s_add_i32 m0, s49, 0x2000
	s_add_u32 s50, s24, 0x100000
	s_addc_u32 s51, s25, 0
	s_add_i32 s49, s39, s28
	global_load_lds_dwordx4 v136, s[24:25]
	s_mov_b32 m0, s49
	s_nop 0
	global_load_lds_dwordx4 v132, s[50:51]
	s_add_i32 m0, s49, 0x2000
	s_nop 0
	global_load_lds_dwordx4 v136, s[50:51]
	s_mov_b32 m0, s30
	s_nop 0
	global_load_lds_dwordx4 v130, s[26:27]
	s_mov_b32 m0, s31
	s_nop 0
	global_load_lds_dwordx4 v134, s[26:27]
	s_waitcnt vmcnt(8)
	s_waitcnt lgkmcnt(0)
	s_barrier
	v_mfma_f32_16x16x32_bf16 v[62:65], v[142:145], v[204:207], 0
	v_mfma_f32_16x16x32_bf16 v[62:65], v[158:161], v[208:211], v[62:65]
	v_mfma_f32_16x16x32_bf16 v[58:61], v[176:179], v[208:211], 0
	v_mfma_f32_16x16x32_bf16 v[58:61], v[168:171], v[204:207], v[58:61]
	v_mfma_f32_16x16x32_bf16 v[42:45], v[168:171], v[212:215], 0
	v_mfma_f32_16x16x32_bf16 v[42:45], v[176:179], v[216:219], v[42:45]
	v_mfma_f32_16x16x32_bf16 v[46:49], v[158:161], v[216:219], 0
	v_mfma_f32_16x16x32_bf16 v[46:49], v[142:145], v[212:215], v[46:49]
	v_mfma_f32_16x16x32_bf16 v[30:33], v[142:145], v[220:223], 0
	v_mfma_f32_16x16x32_bf16 v[30:33], v[158:161], v[224:227], v[30:33]
	v_mfma_f32_16x16x32_bf16 v[26:29], v[176:179], v[224:227], 0
	v_mfma_f32_16x16x32_bf16 v[26:29], v[168:171], v[220:223], v[26:29]
	v_mfma_f32_16x16x32_bf16 v[10:13], v[168:171], v[228:231], 0
	v_mfma_f32_16x16x32_bf16 v[10:13], v[176:179], v[232:235], v[10:13]
	v_mfma_f32_16x16x32_bf16 v[14:17], v[158:161], v[232:235], 0
	v_mfma_f32_16x16x32_bf16 v[14:17], v[142:145], v[228:231], v[14:17]
	v_mfma_f32_16x16x32_bf16 v[6:9], v[180:183], v[228:231], 0
	v_mfma_f32_16x16x32_bf16 v[6:9], v[184:187], v[232:235], v[6:9]
	v_mfma_f32_16x16x32_bf16 v[2:5], v[192:195], v[232:235], 0
	v_mfma_f32_16x16x32_bf16 v[2:5], v[188:191], v[228:231], v[2:5]
	v_mfma_f32_16x16x32_bf16 v[18:21], v[188:191], v[220:223], 0
	v_mfma_f32_16x16x32_bf16 v[18:21], v[192:195], v[224:227], v[18:21]
	v_mfma_f32_16x16x32_bf16 v[22:25], v[184:187], v[224:227], 0
	v_mfma_f32_16x16x32_bf16 v[22:25], v[180:183], v[220:223], v[22:25]
	v_mfma_f32_16x16x32_bf16 v[38:41], v[180:183], v[212:215], 0
	v_mfma_f32_16x16x32_bf16 v[38:41], v[184:187], v[216:219], v[38:41]
	v_mfma_f32_16x16x32_bf16 v[34:37], v[192:195], v[216:219], 0
	v_mfma_f32_16x16x32_bf16 v[34:37], v[188:191], v[212:215], v[34:37]
	v_mfma_f32_16x16x32_bf16 v[50:53], v[188:191], v[204:207], 0
	v_mfma_f32_16x16x32_bf16 v[50:53], v[192:195], v[208:211], v[50:53]
	v_mfma_f32_16x16x32_bf16 v[54:57], v[184:187], v[208:211], 0
	v_mfma_f32_16x16x32_bf16 v[54:57], v[180:183], v[204:207], v[54:57]
	s_barrier
	s_add_i32 s49, 0, 0x18000
	v_add_u32_e32 v157, s49, v152
	s_add_i32 s50, 0, 0x1c000
	ds_read_b128 v[142:145], v157
	ds_read_b128 v[158:161], v157 offset:1024
	ds_read_b128 v[168:171], v157 offset:2048
	ds_read_b128 v[176:179], v157 offset:3072
	v_add_u32_e32 v157, s50, v152
	ds_read_b128 v[180:183], v157
	ds_read_b128 v[184:187], v157 offset:1024
	ds_read_b128 v[188:191], v157 offset:2048
	ds_read_b128 v[192:195], v157 offset:3072
	s_add_u32 s26, s26, 0x100000
	s_addc_u32 s27, s27, 0
	s_mov_b32 m0, s33
	ds_read_b128 v[204:207], v156 offset:32768
	ds_read_b128 v[208:211], v156 offset:33792
	ds_read_b128 v[212:215], v156 offset:34816
	ds_read_b128 v[216:219], v156 offset:35840
	ds_read_b128 v[220:223], v156 offset:36864
	ds_read_b128 v[224:227], v156 offset:37888
	ds_read_b128 v[228:231], v156 offset:38912
	ds_read_b128 v[232:235], v156 offset:39936
	global_load_lds_dwordx4 v130, s[26:27]
	s_mov_b32 m0, s34
	s_nop 0
	global_load_lds_dwordx4 v134, s[26:27]
	s_waitcnt vmcnt(8)
	s_waitcnt lgkmcnt(0)
	s_barrier
	v_mfma_f32_16x16x32_bf16 v[126:129], v[142:145], v[204:207], v[126:129]
	v_mfma_f32_16x16x32_bf16 v[126:129], v[158:161], v[208:211], v[126:129]
	v_mfma_f32_16x16x32_bf16 v[122:125], v[176:179], v[208:211], v[122:125]
	v_mfma_f32_16x16x32_bf16 v[122:125], v[168:171], v[204:207], v[122:125]
	v_mfma_f32_16x16x32_bf16 v[106:109], v[168:171], v[212:215], v[106:109]
	v_mfma_f32_16x16x32_bf16 v[106:109], v[176:179], v[216:219], v[106:109]
	v_mfma_f32_16x16x32_bf16 v[110:113], v[158:161], v[216:219], v[110:113]
	v_mfma_f32_16x16x32_bf16 v[110:113], v[142:145], v[212:215], v[110:113]
	v_mfma_f32_16x16x32_bf16 v[94:97], v[142:145], v[220:223], v[94:97]
	v_mfma_f32_16x16x32_bf16 v[94:97], v[158:161], v[224:227], v[94:97]
	v_mfma_f32_16x16x32_bf16 v[90:93], v[176:179], v[224:227], v[90:93]
	v_mfma_f32_16x16x32_bf16 v[90:93], v[168:171], v[220:223], v[90:93]
	v_mfma_f32_16x16x32_bf16 v[74:77], v[168:171], v[228:231], v[74:77]
	v_mfma_f32_16x16x32_bf16 v[74:77], v[176:179], v[232:235], v[74:77]
	v_mfma_f32_16x16x32_bf16 v[78:81], v[158:161], v[232:235], v[78:81]
	v_mfma_f32_16x16x32_bf16 v[78:81], v[142:145], v[228:231], v[78:81]
	v_mfma_f32_16x16x32_bf16 v[70:73], v[180:183], v[228:231], v[70:73]
	v_mfma_f32_16x16x32_bf16 v[70:73], v[184:187], v[232:235], v[70:73]
	v_mfma_f32_16x16x32_bf16 v[66:69], v[192:195], v[232:235], v[66:69]
	v_mfma_f32_16x16x32_bf16 v[66:69], v[188:191], v[228:231], v[66:69]
	v_mfma_f32_16x16x32_bf16 v[82:85], v[188:191], v[220:223], v[82:85]
	v_mfma_f32_16x16x32_bf16 v[82:85], v[192:195], v[224:227], v[82:85]
	v_mfma_f32_16x16x32_bf16 v[86:89], v[184:187], v[224:227], v[86:89]
	v_mfma_f32_16x16x32_bf16 v[86:89], v[180:183], v[220:223], v[86:89]
	v_mfma_f32_16x16x32_bf16 v[102:105], v[180:183], v[212:215], v[102:105]
	v_mfma_f32_16x16x32_bf16 v[102:105], v[184:187], v[216:219], v[102:105]
	v_mfma_f32_16x16x32_bf16 v[98:101], v[192:195], v[216:219], v[98:101]
	v_mfma_f32_16x16x32_bf16 v[98:101], v[188:191], v[212:215], v[98:101]
	v_mfma_f32_16x16x32_bf16 v[114:117], v[188:191], v[204:207], v[114:117]
	v_mfma_f32_16x16x32_bf16 v[114:117], v[192:195], v[208:211], v[114:117]
	v_mfma_f32_16x16x32_bf16 v[118:121], v[184:187], v[208:211], v[118:121]
	v_mfma_f32_16x16x32_bf16 v[118:121], v[180:183], v[204:207], v[118:121]
	s_barrier
	s_add_u32 s98, s26, 0xfff00080
	s_addc_u32 s99, s27, -1
	s_add_u32 s24, s24, 0x80
	s_addc_u32 s25, s25, 0
	s_add_i32 s26, s49, s28
	s_mov_b32 m0, s26
	ds_read_b128 v[204:207], v156 offset:49152
	ds_read_b128 v[208:211], v156 offset:50176
	ds_read_b128 v[212:215], v156 offset:51200
	ds_read_b128 v[216:219], v156 offset:52224
	ds_read_b128 v[220:223], v156 offset:53248
	ds_read_b128 v[224:227], v156 offset:54272
	ds_read_b128 v[228:231], v156 offset:55296
	ds_read_b128 v[232:235], v156 offset:56320
	global_load_lds_dwordx4 v132, s[24:25]
	s_add_i32 m0, s26, 0x2000
	s_add_i32 s26, s50, s28
	global_load_lds_dwordx4 v136, s[24:25]
	s_add_u32 s24, s24, 0x100000
	s_addc_u32 s25, s25, 0
	s_mov_b32 m0, s26
	s_nop 0
	global_load_lds_dwordx4 v132, s[24:25]
	s_add_i32 m0, s26, 0x2000
	s_nop 0
	global_load_lds_dwordx4 v136, s[24:25]
	s_mov_b32 m0, s36
	s_nop 0
	global_load_lds_dwordx4 v130, s[98:99]
	s_mov_b32 m0, s37
	s_nop 0
	global_load_lds_dwordx4 v134, s[98:99]
	s_waitcnt vmcnt(8)
	s_waitcnt lgkmcnt(0)
	s_barrier
	v_mfma_f32_16x16x32_bf16 v[62:65], v[142:145], v[204:207], v[62:65]
	v_mfma_f32_16x16x32_bf16 v[62:65], v[158:161], v[208:211], v[62:65]
	v_mfma_f32_16x16x32_bf16 v[58:61], v[176:179], v[208:211], v[58:61]
	v_mfma_f32_16x16x32_bf16 v[58:61], v[168:171], v[204:207], v[58:61]
	v_mfma_f32_16x16x32_bf16 v[42:45], v[168:171], v[212:215], v[42:45]
	v_mfma_f32_16x16x32_bf16 v[42:45], v[176:179], v[216:219], v[42:45]
	v_mfma_f32_16x16x32_bf16 v[46:49], v[158:161], v[216:219], v[46:49]
	v_mfma_f32_16x16x32_bf16 v[46:49], v[142:145], v[212:215], v[46:49]
	v_mfma_f32_16x16x32_bf16 v[30:33], v[142:145], v[220:223], v[30:33]
	v_mfma_f32_16x16x32_bf16 v[30:33], v[158:161], v[224:227], v[30:33]
	v_mfma_f32_16x16x32_bf16 v[26:29], v[176:179], v[224:227], v[26:29]
	v_mfma_f32_16x16x32_bf16 v[26:29], v[168:171], v[220:223], v[26:29]
	v_mfma_f32_16x16x32_bf16 v[10:13], v[168:171], v[228:231], v[10:13]
	v_mfma_f32_16x16x32_bf16 v[10:13], v[176:179], v[232:235], v[10:13]
	v_mfma_f32_16x16x32_bf16 v[14:17], v[158:161], v[232:235], v[14:17]
	v_mfma_f32_16x16x32_bf16 v[14:17], v[142:145], v[228:231], v[14:17]
	v_mfma_f32_16x16x32_bf16 v[6:9], v[180:183], v[228:231], v[6:9]
	v_mfma_f32_16x16x32_bf16 v[6:9], v[184:187], v[232:235], v[6:9]
	v_mfma_f32_16x16x32_bf16 v[2:5], v[192:195], v[232:235], v[2:5]
	v_mfma_f32_16x16x32_bf16 v[2:5], v[188:191], v[228:231], v[2:5]
	v_mfma_f32_16x16x32_bf16 v[18:21], v[188:191], v[220:223], v[18:21]
	v_mfma_f32_16x16x32_bf16 v[18:21], v[192:195], v[224:227], v[18:21]
	v_mfma_f32_16x16x32_bf16 v[22:25], v[184:187], v[224:227], v[22:25]
	v_mfma_f32_16x16x32_bf16 v[22:25], v[180:183], v[220:223], v[22:25]
	v_mfma_f32_16x16x32_bf16 v[38:41], v[180:183], v[212:215], v[38:41]
	v_mfma_f32_16x16x32_bf16 v[38:41], v[184:187], v[216:219], v[38:41]
	v_mfma_f32_16x16x32_bf16 v[34:37], v[192:195], v[216:219], v[34:37]
	v_mfma_f32_16x16x32_bf16 v[34:37], v[188:191], v[212:215], v[34:37]
	v_mfma_f32_16x16x32_bf16 v[50:53], v[188:191], v[204:207], v[50:53]
	v_mfma_f32_16x16x32_bf16 v[50:53], v[192:195], v[208:211], v[50:53]
	v_mfma_f32_16x16x32_bf16 v[54:57], v[184:187], v[208:211], v[54:57]
	v_mfma_f32_16x16x32_bf16 v[54:57], v[180:183], v[204:207], v[54:57]
	s_barrier
	s_add_i32 s48, s48, 2
	s_add_u32 s22, s22, 0x100
	s_addc_u32 s23, s23, 0
	s_add_u32 s46, s46, 0x100
	s_addc_u32 s47, s47, 0
.LBB0_2230:
	ds_read_b128 v[142:145], v154
	ds_read_b128 v[158:161], v154 offset:1024
	ds_read_b128 v[168:171], v154 offset:2048
	ds_read_b128 v[176:179], v154 offset:3072
	ds_read_b128 v[180:183], v155
	ds_read_b128 v[184:187], v155 offset:1024
	ds_read_b128 v[188:191], v155 offset:2048
	ds_read_b128 v[192:195], v155 offset:3072
	s_add_u32 s24, s22, 0xfff00080
	s_addc_u32 s25, s23, -1
	s_cmp_eq_u32 s48, 60
	s_cselect_b32 s27, s19, s25
	s_cselect_b32 s26, s44, s24
	s_cselect_b32 s25, s7, s47
	s_cselect_b32 s24, s45, s46
	s_mov_b32 m0, s40
	ds_read_b128 v[204:207], v156
	ds_read_b128 v[208:211], v156 offset:1024
	ds_read_b128 v[212:215], v156 offset:2048
	ds_read_b128 v[216:219], v156 offset:3072
	ds_read_b128 v[220:223], v156 offset:4096
	ds_read_b128 v[224:227], v156 offset:5120
	ds_read_b128 v[228:231], v156 offset:6144
	ds_read_b128 v[232:235], v156 offset:7168
	global_load_lds_dwordx4 v138, s[22:23]
	s_mov_b32 m0, s41
	s_nop 0
	global_load_lds_dwordx4 v140, s[22:23]
	s_waitcnt vmcnt(8)
	s_waitcnt lgkmcnt(0)
	s_barrier
	v_mfma_f32_16x16x32_bf16 v[126:129], v[142:145], v[204:207], v[126:129]
	v_mfma_f32_16x16x32_bf16 v[126:129], v[158:161], v[208:211], v[126:129]
	v_mfma_f32_16x16x32_bf16 v[122:125], v[176:179], v[208:211], v[122:125]
	v_mfma_f32_16x16x32_bf16 v[122:125], v[168:171], v[204:207], v[122:125]
	v_mfma_f32_16x16x32_bf16 v[106:109], v[168:171], v[212:215], v[106:109]
	v_mfma_f32_16x16x32_bf16 v[106:109], v[176:179], v[216:219], v[106:109]
	v_mfma_f32_16x16x32_bf16 v[110:113], v[158:161], v[216:219], v[110:113]
	v_mfma_f32_16x16x32_bf16 v[110:113], v[142:145], v[212:215], v[110:113]
	v_mfma_f32_16x16x32_bf16 v[94:97], v[142:145], v[220:223], v[94:97]
	v_mfma_f32_16x16x32_bf16 v[94:97], v[158:161], v[224:227], v[94:97]
	v_mfma_f32_16x16x32_bf16 v[90:93], v[176:179], v[224:227], v[90:93]
	v_mfma_f32_16x16x32_bf16 v[90:93], v[168:171], v[220:223], v[90:93]
	v_mfma_f32_16x16x32_bf16 v[74:77], v[168:171], v[228:231], v[74:77]
	v_mfma_f32_16x16x32_bf16 v[74:77], v[176:179], v[232:235], v[74:77]
	v_mfma_f32_16x16x32_bf16 v[78:81], v[158:161], v[232:235], v[78:81]
	v_mfma_f32_16x16x32_bf16 v[78:81], v[142:145], v[228:231], v[78:81]
	v_mfma_f32_16x16x32_bf16 v[70:73], v[180:183], v[228:231], v[70:73]
	v_mfma_f32_16x16x32_bf16 v[70:73], v[184:187], v[232:235], v[70:73]
	v_mfma_f32_16x16x32_bf16 v[66:69], v[192:195], v[232:235], v[66:69]
	v_mfma_f32_16x16x32_bf16 v[66:69], v[188:191], v[228:231], v[66:69]
	v_mfma_f32_16x16x32_bf16 v[82:85], v[188:191], v[220:223], v[82:85]
	v_mfma_f32_16x16x32_bf16 v[82:85], v[192:195], v[224:227], v[82:85]
	v_mfma_f32_16x16x32_bf16 v[86:89], v[184:187], v[224:227], v[86:89]
	v_mfma_f32_16x16x32_bf16 v[86:89], v[180:183], v[220:223], v[86:89]
	v_mfma_f32_16x16x32_bf16 v[102:105], v[180:183], v[212:215], v[102:105]
	v_mfma_f32_16x16x32_bf16 v[102:105], v[184:187], v[216:219], v[102:105]
	v_mfma_f32_16x16x32_bf16 v[98:101], v[192:195], v[216:219], v[98:101]
	v_mfma_f32_16x16x32_bf16 v[98:101], v[188:191], v[212:215], v[98:101]
	v_mfma_f32_16x16x32_bf16 v[114:117], v[188:191], v[204:207], v[114:117]
	v_mfma_f32_16x16x32_bf16 v[114:117], v[192:195], v[208:211], v[114:117]
	v_mfma_f32_16x16x32_bf16 v[118:121], v[184:187], v[208:211], v[118:121]
	v_mfma_f32_16x16x32_bf16 v[118:121], v[180:183], v[204:207], v[118:121]
	s_barrier
	s_add_i32 s49, s38, s28
	s_mov_b32 m0, s49
	ds_read_b128 v[204:207], v156 offset:16384
	ds_read_b128 v[208:211], v156 offset:17408
	ds_read_b128 v[212:215], v156 offset:18432
	ds_read_b128 v[216:219], v156 offset:19456
	ds_read_b128 v[220:223], v156 offset:20480
	ds_read_b128 v[224:227], v156 offset:21504
	ds_read_b128 v[228:231], v156 offset:22528
	ds_read_b128 v[232:235], v156 offset:23552
	global_load_lds_dwordx4 v132, s[24:25]
	s_add_i32 m0, s49, 0x2000
	s_add_u32 s50, s24, 0x100000
	s_addc_u32 s51, s25, 0
	s_add_i32 s49, s39, s28
	global_load_lds_dwordx4 v136, s[24:25]
	s_mov_b32 m0, s49
	s_nop 0
	global_load_lds_dwordx4 v132, s[50:51]
	s_add_i32 m0, s49, 0x2000
	s_nop 0
	global_load_lds_dwordx4 v136, s[50:51]
	s_mov_b32 m0, s30
	s_nop 0
	global_load_lds_dwordx4 v130, s[26:27]
	s_mov_b32 m0, s31
	s_nop 0
	global_load_lds_dwordx4 v134, s[26:27]
	s_waitcnt vmcnt(8)
	s_waitcnt lgkmcnt(0)
	s_barrier
	v_mfma_f32_16x16x32_bf16 v[62:65], v[142:145], v[204:207], v[62:65]
	v_mfma_f32_16x16x32_bf16 v[62:65], v[158:161], v[208:211], v[62:65]
	v_mfma_f32_16x16x32_bf16 v[58:61], v[176:179], v[208:211], v[58:61]
	v_mfma_f32_16x16x32_bf16 v[58:61], v[168:171], v[204:207], v[58:61]
	v_mfma_f32_16x16x32_bf16 v[42:45], v[168:171], v[212:215], v[42:45]
	v_mfma_f32_16x16x32_bf16 v[42:45], v[176:179], v[216:219], v[42:45]
	v_mfma_f32_16x16x32_bf16 v[46:49], v[158:161], v[216:219], v[46:49]
	v_mfma_f32_16x16x32_bf16 v[46:49], v[142:145], v[212:215], v[46:49]
	v_mfma_f32_16x16x32_bf16 v[30:33], v[142:145], v[220:223], v[30:33]
	v_mfma_f32_16x16x32_bf16 v[30:33], v[158:161], v[224:227], v[30:33]
	v_mfma_f32_16x16x32_bf16 v[26:29], v[176:179], v[224:227], v[26:29]
	v_mfma_f32_16x16x32_bf16 v[26:29], v[168:171], v[220:223], v[26:29]
	v_mfma_f32_16x16x32_bf16 v[10:13], v[168:171], v[228:231], v[10:13]
	v_mfma_f32_16x16x32_bf16 v[10:13], v[176:179], v[232:235], v[10:13]
	v_mfma_f32_16x16x32_bf16 v[14:17], v[158:161], v[232:235], v[14:17]
	v_mfma_f32_16x16x32_bf16 v[14:17], v[142:145], v[228:231], v[14:17]
	v_mfma_f32_16x16x32_bf16 v[6:9], v[180:183], v[228:231], v[6:9]
	v_mfma_f32_16x16x32_bf16 v[6:9], v[184:187], v[232:235], v[6:9]
	v_mfma_f32_16x16x32_bf16 v[2:5], v[192:195], v[232:235], v[2:5]
	v_mfma_f32_16x16x32_bf16 v[2:5], v[188:191], v[228:231], v[2:5]
	v_mfma_f32_16x16x32_bf16 v[18:21], v[188:191], v[220:223], v[18:21]
	v_mfma_f32_16x16x32_bf16 v[18:21], v[192:195], v[224:227], v[18:21]
	v_mfma_f32_16x16x32_bf16 v[22:25], v[184:187], v[224:227], v[22:25]
	v_mfma_f32_16x16x32_bf16 v[22:25], v[180:183], v[220:223], v[22:25]
	v_mfma_f32_16x16x32_bf16 v[38:41], v[180:183], v[212:215], v[38:41]
	v_mfma_f32_16x16x32_bf16 v[38:41], v[184:187], v[216:219], v[38:41]
	v_mfma_f32_16x16x32_bf16 v[34:37], v[192:195], v[216:219], v[34:37]
	v_mfma_f32_16x16x32_bf16 v[34:37], v[188:191], v[212:215], v[34:37]
	v_mfma_f32_16x16x32_bf16 v[50:53], v[188:191], v[204:207], v[50:53]
	v_mfma_f32_16x16x32_bf16 v[50:53], v[192:195], v[208:211], v[50:53]
	v_mfma_f32_16x16x32_bf16 v[54:57], v[184:187], v[208:211], v[54:57]
	v_mfma_f32_16x16x32_bf16 v[54:57], v[180:183], v[204:207], v[54:57]
	s_barrier
	s_add_i32 s49, 0, 0x18000
	v_add_u32_e32 v157, s49, v152
	s_add_i32 s50, 0, 0x1c000
	ds_read_b128 v[142:145], v157
	ds_read_b128 v[158:161], v157 offset:1024
	ds_read_b128 v[168:171], v157 offset:2048
	ds_read_b128 v[176:179], v157 offset:3072
	v_add_u32_e32 v157, s50, v152
	ds_read_b128 v[180:183], v157
	ds_read_b128 v[184:187], v157 offset:1024
	ds_read_b128 v[188:191], v157 offset:2048
	ds_read_b128 v[192:195], v157 offset:3072
	s_add_u32 s26, s26, 0x100000
	s_addc_u32 s27, s27, 0
	s_mov_b32 m0, s33
	ds_read_b128 v[204:207], v156 offset:32768
	ds_read_b128 v[208:211], v156 offset:33792
	ds_read_b128 v[212:215], v156 offset:34816
	ds_read_b128 v[216:219], v156 offset:35840
	ds_read_b128 v[220:223], v156 offset:36864
	ds_read_b128 v[224:227], v156 offset:37888
	ds_read_b128 v[228:231], v156 offset:38912
	ds_read_b128 v[232:235], v156 offset:39936
	global_load_lds_dwordx4 v130, s[26:27]
	s_mov_b32 m0, s34
	s_nop 0
	global_load_lds_dwordx4 v134, s[26:27]
	s_waitcnt vmcnt(8)
	s_waitcnt lgkmcnt(0)
	s_barrier
	v_mfma_f32_16x16x32_bf16 v[126:129], v[142:145], v[204:207], v[126:129]
	v_mfma_f32_16x16x32_bf16 v[126:129], v[158:161], v[208:211], v[126:129]
	v_mfma_f32_16x16x32_bf16 v[122:125], v[176:179], v[208:211], v[122:125]
	v_mfma_f32_16x16x32_bf16 v[122:125], v[168:171], v[204:207], v[122:125]
	v_mfma_f32_16x16x32_bf16 v[106:109], v[168:171], v[212:215], v[106:109]
	v_mfma_f32_16x16x32_bf16 v[106:109], v[176:179], v[216:219], v[106:109]
	v_mfma_f32_16x16x32_bf16 v[110:113], v[158:161], v[216:219], v[110:113]
	v_mfma_f32_16x16x32_bf16 v[110:113], v[142:145], v[212:215], v[110:113]
	v_mfma_f32_16x16x32_bf16 v[94:97], v[142:145], v[220:223], v[94:97]
	v_mfma_f32_16x16x32_bf16 v[94:97], v[158:161], v[224:227], v[94:97]
	v_mfma_f32_16x16x32_bf16 v[90:93], v[176:179], v[224:227], v[90:93]
	v_mfma_f32_16x16x32_bf16 v[90:93], v[168:171], v[220:223], v[90:93]
	v_mfma_f32_16x16x32_bf16 v[74:77], v[168:171], v[228:231], v[74:77]
	v_mfma_f32_16x16x32_bf16 v[74:77], v[176:179], v[232:235], v[74:77]
	v_mfma_f32_16x16x32_bf16 v[78:81], v[158:161], v[232:235], v[78:81]
	v_mfma_f32_16x16x32_bf16 v[78:81], v[142:145], v[228:231], v[78:81]
	v_mfma_f32_16x16x32_bf16 v[70:73], v[180:183], v[228:231], v[70:73]
	v_mfma_f32_16x16x32_bf16 v[70:73], v[184:187], v[232:235], v[70:73]
	v_mfma_f32_16x16x32_bf16 v[66:69], v[192:195], v[232:235], v[66:69]
	v_mfma_f32_16x16x32_bf16 v[66:69], v[188:191], v[228:231], v[66:69]
	v_mfma_f32_16x16x32_bf16 v[82:85], v[188:191], v[220:223], v[82:85]
	v_mfma_f32_16x16x32_bf16 v[82:85], v[192:195], v[224:227], v[82:85]
	v_mfma_f32_16x16x32_bf16 v[86:89], v[184:187], v[224:227], v[86:89]
	v_mfma_f32_16x16x32_bf16 v[86:89], v[180:183], v[220:223], v[86:89]
	v_mfma_f32_16x16x32_bf16 v[102:105], v[180:183], v[212:215], v[102:105]
	v_mfma_f32_16x16x32_bf16 v[102:105], v[184:187], v[216:219], v[102:105]
	v_mfma_f32_16x16x32_bf16 v[98:101], v[192:195], v[216:219], v[98:101]
	v_mfma_f32_16x16x32_bf16 v[98:101], v[188:191], v[212:215], v[98:101]
	v_mfma_f32_16x16x32_bf16 v[114:117], v[188:191], v[204:207], v[114:117]
	v_mfma_f32_16x16x32_bf16 v[114:117], v[192:195], v[208:211], v[114:117]
	v_mfma_f32_16x16x32_bf16 v[118:121], v[184:187], v[208:211], v[118:121]
	v_mfma_f32_16x16x32_bf16 v[118:121], v[180:183], v[204:207], v[118:121]
	s_barrier
	s_add_u32 s98, s26, 0xfff00080
	s_addc_u32 s99, s27, -1
	s_add_u32 s24, s24, 0x80
	s_addc_u32 s25, s25, 0
	s_add_i32 s26, s49, s28
	s_mov_b32 m0, s26
	ds_read_b128 v[204:207], v156 offset:49152
	ds_read_b128 v[208:211], v156 offset:50176
	ds_read_b128 v[212:215], v156 offset:51200
	ds_read_b128 v[216:219], v156 offset:52224
	ds_read_b128 v[220:223], v156 offset:53248
	ds_read_b128 v[224:227], v156 offset:54272
	ds_read_b128 v[228:231], v156 offset:55296
	ds_read_b128 v[232:235], v156 offset:56320
	global_load_lds_dwordx4 v132, s[24:25]
	s_add_i32 m0, s26, 0x2000
	s_add_i32 s26, s50, s28
	global_load_lds_dwordx4 v136, s[24:25]
	s_add_u32 s24, s24, 0x100000
	s_addc_u32 s25, s25, 0
	s_mov_b32 m0, s26
	s_nop 0
	global_load_lds_dwordx4 v132, s[24:25]
	s_add_i32 m0, s26, 0x2000
	s_nop 0
	global_load_lds_dwordx4 v136, s[24:25]
	s_mov_b32 m0, s36
	s_nop 0
	global_load_lds_dwordx4 v130, s[98:99]
	s_mov_b32 m0, s37
	s_nop 0
	global_load_lds_dwordx4 v134, s[98:99]
	s_waitcnt vmcnt(8)
	s_waitcnt lgkmcnt(0)
	s_barrier
	v_mfma_f32_16x16x32_bf16 v[62:65], v[142:145], v[204:207], v[62:65]
	v_mfma_f32_16x16x32_bf16 v[62:65], v[158:161], v[208:211], v[62:65]
	v_mfma_f32_16x16x32_bf16 v[58:61], v[176:179], v[208:211], v[58:61]
	v_mfma_f32_16x16x32_bf16 v[58:61], v[168:171], v[204:207], v[58:61]
	v_mfma_f32_16x16x32_bf16 v[42:45], v[168:171], v[212:215], v[42:45]
	v_mfma_f32_16x16x32_bf16 v[42:45], v[176:179], v[216:219], v[42:45]
	v_mfma_f32_16x16x32_bf16 v[46:49], v[158:161], v[216:219], v[46:49]
	v_mfma_f32_16x16x32_bf16 v[46:49], v[142:145], v[212:215], v[46:49]
	v_mfma_f32_16x16x32_bf16 v[30:33], v[142:145], v[220:223], v[30:33]
	v_mfma_f32_16x16x32_bf16 v[30:33], v[158:161], v[224:227], v[30:33]
	v_mfma_f32_16x16x32_bf16 v[26:29], v[176:179], v[224:227], v[26:29]
	v_mfma_f32_16x16x32_bf16 v[26:29], v[168:171], v[220:223], v[26:29]
	v_mfma_f32_16x16x32_bf16 v[10:13], v[168:171], v[228:231], v[10:13]
	v_mfma_f32_16x16x32_bf16 v[10:13], v[176:179], v[232:235], v[10:13]
	v_mfma_f32_16x16x32_bf16 v[14:17], v[158:161], v[232:235], v[14:17]
	v_mfma_f32_16x16x32_bf16 v[14:17], v[142:145], v[228:231], v[14:17]
	v_mfma_f32_16x16x32_bf16 v[6:9], v[180:183], v[228:231], v[6:9]
	v_mfma_f32_16x16x32_bf16 v[6:9], v[184:187], v[232:235], v[6:9]
	v_mfma_f32_16x16x32_bf16 v[2:5], v[192:195], v[232:235], v[2:5]
	v_mfma_f32_16x16x32_bf16 v[2:5], v[188:191], v[228:231], v[2:5]
	v_mfma_f32_16x16x32_bf16 v[18:21], v[188:191], v[220:223], v[18:21]
	v_mfma_f32_16x16x32_bf16 v[18:21], v[192:195], v[224:227], v[18:21]
	v_mfma_f32_16x16x32_bf16 v[22:25], v[184:187], v[224:227], v[22:25]
	v_mfma_f32_16x16x32_bf16 v[22:25], v[180:183], v[220:223], v[22:25]
	v_mfma_f32_16x16x32_bf16 v[38:41], v[180:183], v[212:215], v[38:41]
	v_mfma_f32_16x16x32_bf16 v[38:41], v[184:187], v[216:219], v[38:41]
	v_mfma_f32_16x16x32_bf16 v[34:37], v[192:195], v[216:219], v[34:37]
	v_mfma_f32_16x16x32_bf16 v[34:37], v[188:191], v[212:215], v[34:37]
	v_mfma_f32_16x16x32_bf16 v[50:53], v[188:191], v[204:207], v[50:53]
	v_mfma_f32_16x16x32_bf16 v[50:53], v[192:195], v[208:211], v[50:53]
	v_mfma_f32_16x16x32_bf16 v[54:57], v[184:187], v[208:211], v[54:57]
	v_mfma_f32_16x16x32_bf16 v[54:57], v[180:183], v[204:207], v[54:57]
	s_barrier
	s_add_i32 s48, s48, 2
	s_add_u32 s22, s22, 0x100
	s_addc_u32 s23, s23, 0
	s_add_u32 s46, s46, 0x100
	s_addc_u32 s47, s47, 0
	s_cmp_gt_u32 s48, 61
	s_cbranch_scc0 .LBB0_2230
	s_setprio 0
	s_and_b64 vcc, exec, s[16:17]
	s_cbranch_vccz .LBB0_2233
	s_barrier

.LBB0_2372:
	s_add_i32 s34, s34, 1
	s_mov_b32 s50, s6
	s_lshl_b32 s6, s34, 5
	s_add_i32 s6, s6, s3
	s_mov_b64 s[22:23], s[8:9]
	s_lshl_b32 s8, s6, 3
	s_ashr_i32 s7, s6, 2
	s_add_i32 s8, s8, s37
	s_cmpk_lt_i32 s6, 0x158
	s_cselect_b32 s6, s7, s8
	s_mov_b32 s51, s26
	s_cselect_b32 s26, s38, 32
	s_cmpk_lt_i32 s6, 0x56
	s_cselect_b64 s[18:19], -1, 0
	s_lshl_b32 s7, s26, 21
	v_readlane_b32 s0, v250, 46
	s_mov_b64 s[20:21], s[10:11]
	v_readlane_b32 s1, v250, 47
	s_add_u32 s10, s0, s7
	s_addc_u32 s11, s1, 0
	s_and_b64 s[8:9], s[18:19], exec
	s_cselect_b32 s52, s11, s21
	s_cselect_b32 s53, s10, s20
	s_ashr_i32 s7, s6, 31
	s_lshl_b64 s[8:9], s[6:7], 21
	s_add_u32 s8, s27, s8
	s_addc_u32 s9, s28, s9
	s_and_b64 s[24:25], s[18:19], exec
	s_cselect_b32 s7, s9, s23
	s_cselect_b32 s54, s8, s22
	s_add_u32 s20, s20, 0x100080
	s_addc_u32 s21, s21, 0
	s_add_u32 s55, s22, 0x100
	s_addc_u32 s56, s23, 0
	s_mov_b32 s57, -2
	s_and_b64 vcc, exec, s[12:13]
	s_cbranch_vccz .Lsp_6
	s_setprio 1
.Lsp_6:
	s_waitcnt lgkmcnt(0)
	s_add_u32 s60, s20, 0xfff00000
	s_addc_u32 s61, s21, -1
	s_mov_b32 m0, s35
	ds_read_b128 v[142:145], v148
	global_load_lds_dwordx4 v130, s[60:61]
	s_mov_b32 m0, s36
	ds_read_b128 v[154:157], v148 offset:1024
	global_load_lds_dwordx4 v134, s[60:61]
	s_mov_b32 m0, s40
	ds_read_b128 v[158:161], v148 offset:2048
	global_load_lds_dwordx4 v138, s[20:21]
	s_mov_b32 m0, s41
	ds_read_b128 v[168:171], v148 offset:3072
	global_load_lds_dwordx4 v140, s[20:21]
	ds_read_b128 v[176:179], v149
	ds_read_b128 v[180:183], v149 offset:1024
	ds_read_b128 v[184:187], v149 offset:2048
	ds_read_b128 v[188:191], v149 offset:3072
	s_add_u32 s22, s20, 0xfff00080
	s_addc_u32 s23, s21, -1
	s_cmp_eq_u32 s57, 60
	s_cselect_b32 s25, s52, s23
	s_cselect_b32 s24, s53, s22
	s_cselect_b32 s23, s7, s56
	s_cselect_b32 s22, s54, s55
	ds_read_b128 v[192:195], v150
	ds_read_b128 v[204:207], v150 offset:1024
	ds_read_b128 v[208:211], v150 offset:2048
	ds_read_b128 v[212:215], v150 offset:3072
	ds_read_b128 v[216:219], v150 offset:4096
	ds_read_b128 v[220:223], v150 offset:5120
	ds_read_b128 v[224:227], v150 offset:6144
	ds_read_b128 v[228:231], v150 offset:7168
	s_waitcnt vmcnt(8)
	s_waitcnt lgkmcnt(0)
	s_barrier
	v_mfma_f32_16x16x32_bf16 v[126:129], v[142:145], v[192:195], 0
	v_mfma_f32_16x16x32_bf16 v[126:129], v[154:157], v[204:207], v[126:129]
	v_mfma_f32_16x16x32_bf16 v[122:125], v[168:171], v[204:207], 0
	v_mfma_f32_16x16x32_bf16 v[122:125], v[158:161], v[192:195], v[122:125]
	v_mfma_f32_16x16x32_bf16 v[106:109], v[158:161], v[208:211], 0
	v_mfma_f32_16x16x32_bf16 v[106:109], v[168:171], v[212:215], v[106:109]
	v_mfma_f32_16x16x32_bf16 v[110:113], v[154:157], v[212:215], 0
	v_mfma_f32_16x16x32_bf16 v[110:113], v[142:145], v[208:211], v[110:113]
	v_mfma_f32_16x16x32_bf16 v[94:97], v[142:145], v[216:219], 0
	v_mfma_f32_16x16x32_bf16 v[94:97], v[154:157], v[220:223], v[94:97]
	v_mfma_f32_16x16x32_bf16 v[90:93], v[168:171], v[220:223], 0
	v_mfma_f32_16x16x32_bf16 v[90:93], v[158:161], v[216:219], v[90:93]
	v_mfma_f32_16x16x32_bf16 v[74:77], v[158:161], v[224:227], 0
	v_mfma_f32_16x16x32_bf16 v[74:77], v[168:171], v[228:231], v[74:77]
	v_mfma_f32_16x16x32_bf16 v[78:81], v[154:157], v[228:231], 0
	v_mfma_f32_16x16x32_bf16 v[78:81], v[142:145], v[224:227], v[78:81]
	v_mfma_f32_16x16x32_bf16 v[70:73], v[176:179], v[224:227], 0
	v_mfma_f32_16x16x32_bf16 v[70:73], v[180:183], v[228:231], v[70:73]
	v_mfma_f32_16x16x32_bf16 v[66:69], v[188:191], v[228:231], 0
	v_mfma_f32_16x16x32_bf16 v[66:69], v[184:187], v[224:227], v[66:69]
	v_mfma_f32_16x16x32_bf16 v[82:85], v[184:187], v[216:219], 0
	v_mfma_f32_16x16x32_bf16 v[82:85], v[188:191], v[220:223], v[82:85]
	v_mfma_f32_16x16x32_bf16 v[86:89], v[180:183], v[220:223], 0
	v_mfma_f32_16x16x32_bf16 v[86:89], v[176:179], v[216:219], v[86:89]
	v_mfma_f32_16x16x32_bf16 v[102:105], v[176:179], v[208:211], 0
	v_mfma_f32_16x16x32_bf16 v[102:105], v[180:183], v[212:215], v[102:105]
	v_mfma_f32_16x16x32_bf16 v[98:101], v[188:191], v[212:215], 0
	v_mfma_f32_16x16x32_bf16 v[98:101], v[184:187], v[208:211], v[98:101]
	v_mfma_f32_16x16x32_bf16 v[114:117], v[184:187], v[192:195], 0
	v_mfma_f32_16x16x32_bf16 v[114:117], v[188:191], v[204:207], v[114:117]
	v_mfma_f32_16x16x32_bf16 v[118:121], v[180:183], v[204:207], 0
	v_mfma_f32_16x16x32_bf16 v[118:121], v[176:179], v[192:195], v[118:121]
	s_barrier
	s_mov_b32 m0, s42
	s_add_u32 s60, s22, 0x100000
	global_load_lds_dwordx4 v132, s[22:23]
	s_mov_b32 m0, s43
	s_addc_u32 s61, s23, 0
	global_load_lds_dwordx4 v136, s[22:23]
	s_mov_b32 m0, s44
	ds_read_b128 v[192:195], v150 offset:16384
	global_load_lds_dwordx4 v132, s[60:61]
	s_mov_b32 m0, s45
	ds_read_b128 v[204:207], v150 offset:17408
	global_load_lds_dwordx4 v136, s[60:61]
	ds_read_b128 v[208:211], v150 offset:18432
	ds_read_b128 v[212:215], v150 offset:19456
	ds_read_b128 v[216:219], v150 offset:20480
	ds_read_b128 v[220:223], v150 offset:21504
	ds_read_b128 v[224:227], v150 offset:22528
	ds_read_b128 v[228:231], v150 offset:23552
	s_waitcnt vmcnt(6)
	s_waitcnt lgkmcnt(0)
	s_barrier
	v_mfma_f32_16x16x32_bf16 v[62:65], v[142:145], v[192:195], 0
	v_mfma_f32_16x16x32_bf16 v[62:65], v[154:157], v[204:207], v[62:65]
	v_mfma_f32_16x16x32_bf16 v[58:61], v[168:171], v[204:207], 0
	v_mfma_f32_16x16x32_bf16 v[58:61], v[158:161], v[192:195], v[58:61]
	v_mfma_f32_16x16x32_bf16 v[42:45], v[158:161], v[208:211], 0
	v_mfma_f32_16x16x32_bf16 v[42:45], v[168:171], v[212:215], v[42:45]
	v_mfma_f32_16x16x32_bf16 v[46:49], v[154:157], v[212:215], 0
	v_mfma_f32_16x16x32_bf16 v[46:49], v[142:145], v[208:211], v[46:49]
	v_mfma_f32_16x16x32_bf16 v[30:33], v[142:145], v[216:219], 0
	v_mfma_f32_16x16x32_bf16 v[30:33], v[154:157], v[220:223], v[30:33]
	v_mfma_f32_16x16x32_bf16 v[26:29], v[168:171], v[220:223], 0
	v_mfma_f32_16x16x32_bf16 v[26:29], v[158:161], v[216:219], v[26:29]
	v_mfma_f32_16x16x32_bf16 v[10:13], v[158:161], v[224:227], 0
	v_mfma_f32_16x16x32_bf16 v[10:13], v[168:171], v[228:231], v[10:13]
	v_mfma_f32_16x16x32_bf16 v[14:17], v[154:157], v[228:231], 0
	v_mfma_f32_16x16x32_bf16 v[14:17], v[142:145], v[224:227], v[14:17]
	v_mfma_f32_16x16x32_bf16 v[6:9], v[176:179], v[224:227], 0
	v_mfma_f32_16x16x32_bf16 v[6:9], v[180:183], v[228:231], v[6:9]
	v_mfma_f32_16x16x32_bf16 v[2:5], v[188:191], v[228:231], 0
	v_mfma_f32_16x16x32_bf16 v[2:5], v[184:187], v[224:227], v[2:5]
	v_mfma_f32_16x16x32_bf16 v[18:21], v[184:187], v[216:219], 0
	v_mfma_f32_16x16x32_bf16 v[18:21], v[188:191], v[220:223], v[18:21]
	v_mfma_f32_16x16x32_bf16 v[22:25], v[180:183], v[220:223], 0
	v_mfma_f32_16x16x32_bf16 v[22:25], v[176:179], v[216:219], v[22:25]
	v_mfma_f32_16x16x32_bf16 v[38:41], v[176:179], v[208:211], 0
	v_mfma_f32_16x16x32_bf16 v[38:41], v[180:183], v[212:215], v[38:41]
	v_mfma_f32_16x16x32_bf16 v[34:37], v[188:191], v[212:215], 0
	v_mfma_f32_16x16x32_bf16 v[34:37], v[184:187], v[208:211], v[34:37]
	v_mfma_f32_16x16x32_bf16 v[50:53], v[184:187], v[192:195], 0
	v_mfma_f32_16x16x32_bf16 v[50:53], v[188:191], v[204:207], v[50:53]
	v_mfma_f32_16x16x32_bf16 v[54:57], v[180:183], v[204:207], 0
	v_mfma_f32_16x16x32_bf16 v[54:57], v[176:179], v[192:195], v[54:57]
	s_barrier
	s_mov_b32 m0, s29
	ds_read_b128 v[142:145], v151
	global_load_lds_dwordx4 v130, s[24:25]
	s_mov_b32 m0, s30
	ds_read_b128 v[154:157], v151 offset:1024
	global_load_lds_dwordx4 v134, s[24:25]
	s_add_u32 s24, s24, 0x100000
	s_addc_u32 s25, s25, 0
	s_mov_b32 m0, s31
	ds_read_b128 v[158:161], v151 offset:2048
	global_load_lds_dwordx4 v130, s[24:25]
	s_mov_b32 m0, s33
	ds_read_b128 v[168:171], v151 offset:3072
	global_load_lds_dwordx4 v134, s[24:25]
	ds_read_b128 v[176:179], v152
	ds_read_b128 v[180:183], v152 offset:1024
	ds_read_b128 v[184:187], v152 offset:2048
	ds_read_b128 v[188:191], v152 offset:3072
	ds_read_b128 v[192:195], v150 offset:32768
	ds_read_b128 v[204:207], v150 offset:33792
	ds_read_b128 v[208:211], v150 offset:34816
	ds_read_b128 v[212:215], v150 offset:35840
	ds_read_b128 v[216:219], v150 offset:36864
	ds_read_b128 v[220:223], v150 offset:37888
	ds_read_b128 v[224:227], v150 offset:38912
	ds_read_b128 v[228:231], v150 offset:39936
	s_waitcnt vmcnt(8)
	s_waitcnt lgkmcnt(0)
	s_barrier
	v_mfma_f32_16x16x32_bf16 v[126:129], v[142:145], v[192:195], v[126:129]
	v_mfma_f32_16x16x32_bf16 v[126:129], v[154:157], v[204:207], v[126:129]
	v_mfma_f32_16x16x32_bf16 v[122:125], v[168:171], v[204:207], v[122:125]
	v_mfma_f32_16x16x32_bf16 v[122:125], v[158:161], v[192:195], v[122:125]
	v_mfma_f32_16x16x32_bf16 v[106:109], v[158:161], v[208:211], v[106:109]
	v_mfma_f32_16x16x32_bf16 v[106:109], v[168:171], v[212:215], v[106:109]
	v_mfma_f32_16x16x32_bf16 v[110:113], v[154:157], v[212:215], v[110:113]
	v_mfma_f32_16x16x32_bf16 v[110:113], v[142:145], v[208:211], v[110:113]
	v_mfma_f32_16x16x32_bf16 v[94:97], v[142:145], v[216:219], v[94:97]
	v_mfma_f32_16x16x32_bf16 v[94:97], v[154:157], v[220:223], v[94:97]
	v_mfma_f32_16x16x32_bf16 v[90:93], v[168:171], v[220:223], v[90:93]
	v_mfma_f32_16x16x32_bf16 v[90:93], v[158:161], v[216:219], v[90:93]
	v_mfma_f32_16x16x32_bf16 v[74:77], v[158:161], v[224:227], v[74:77]
	v_mfma_f32_16x16x32_bf16 v[74:77], v[168:171], v[228:231], v[74:77]
	v_mfma_f32_16x16x32_bf16 v[78:81], v[154:157], v[228:231], v[78:81]
	v_mfma_f32_16x16x32_bf16 v[78:81], v[142:145], v[224:227], v[78:81]
	v_mfma_f32_16x16x32_bf16 v[70:73], v[176:179], v[224:227], v[70:73]
	v_mfma_f32_16x16x32_bf16 v[70:73], v[180:183], v[228:231], v[70:73]
	v_mfma_f32_16x16x32_bf16 v[66:69], v[188:191], v[228:231], v[66:69]
	v_mfma_f32_16x16x32_bf16 v[66:69], v[184:187], v[224:227], v[66:69]
	v_mfma_f32_16x16x32_bf16 v[82:85], v[184:187], v[216:219], v[82:85]
	v_mfma_f32_16x16x32_bf16 v[82:85], v[188:191], v[220:223], v[82:85]
	v_mfma_f32_16x16x32_bf16 v[86:89], v[180:183], v[220:223], v[86:89]
	v_mfma_f32_16x16x32_bf16 v[86:89], v[176:179], v[216:219], v[86:89]
	v_mfma_f32_16x16x32_bf16 v[102:105], v[176:179], v[208:211], v[102:105]
	v_mfma_f32_16x16x32_bf16 v[102:105], v[180:183], v[212:215], v[102:105]
	v_mfma_f32_16x16x32_bf16 v[98:101], v[188:191], v[212:215], v[98:101]
	v_mfma_f32_16x16x32_bf16 v[98:101], v[184:187], v[208:211], v[98:101]
	v_mfma_f32_16x16x32_bf16 v[114:117], v[184:187], v[192:195], v[114:117]
	v_mfma_f32_16x16x32_bf16 v[114:117], v[188:191], v[204:207], v[114:117]
	v_mfma_f32_16x16x32_bf16 v[118:121], v[180:183], v[204:207], v[118:121]
	v_mfma_f32_16x16x32_bf16 v[118:121], v[176:179], v[192:195], v[118:121]
	s_barrier
	s_mov_b32 m0, s46
	s_add_u32 s22, s22, 0x80
	s_addc_u32 s23, s23, 0
	global_load_lds_dwordx4 v132, s[22:23]
	s_mov_b32 m0, s47
	ds_read_b128 v[192:195], v150 offset:49152
	global_load_lds_dwordx4 v136, s[22:23]
	s_mov_b32 m0, s48
	s_add_u32 s22, s22, 0x100000
	s_addc_u32 s23, s23, 0
	global_load_lds_dwordx4 v132, s[22:23]
	s_mov_b32 m0, s49
	ds_read_b128 v[204:207], v150 offset:50176
	global_load_lds_dwordx4 v136, s[22:23]
	ds_read_b128 v[208:211], v150 offset:51200
	ds_read_b128 v[212:215], v150 offset:52224
	ds_read_b128 v[216:219], v150 offset:53248
	ds_read_b128 v[220:223], v150 offset:54272
	ds_read_b128 v[224:227], v150 offset:55296
	ds_read_b128 v[228:231], v150 offset:56320
	s_waitcnt vmcnt(6)
	s_waitcnt lgkmcnt(0)
	s_barrier
	v_mfma_f32_16x16x32_bf16 v[62:65], v[142:145], v[192:195], v[62:65]
	v_mfma_f32_16x16x32_bf16 v[62:65], v[154:157], v[204:207], v[62:65]
	v_mfma_f32_16x16x32_bf16 v[58:61], v[168:171], v[204:207], v[58:61]
	v_mfma_f32_16x16x32_bf16 v[58:61], v[158:161], v[192:195], v[58:61]
	v_mfma_f32_16x16x32_bf16 v[42:45], v[158:161], v[208:211], v[42:45]
	v_mfma_f32_16x16x32_bf16 v[42:45], v[168:171], v[212:215], v[42:45]
	v_mfma_f32_16x16x32_bf16 v[46:49], v[154:157], v[212:215], v[46:49]
	v_mfma_f32_16x16x32_bf16 v[46:49], v[142:145], v[208:211], v[46:49]
	v_mfma_f32_16x16x32_bf16 v[30:33], v[142:145], v[216:219], v[30:33]
	v_mfma_f32_16x16x32_bf16 v[30:33], v[154:157], v[220:223], v[30:33]
	v_mfma_f32_16x16x32_bf16 v[26:29], v[168:171], v[220:223], v[26:29]
	v_mfma_f32_16x16x32_bf16 v[26:29], v[158:161], v[216:219], v[26:29]
	v_mfma_f32_16x16x32_bf16 v[10:13], v[158:161], v[224:227], v[10:13]
	v_mfma_f32_16x16x32_bf16 v[10:13], v[168:171], v[228:231], v[10:13]
	v_mfma_f32_16x16x32_bf16 v[14:17], v[154:157], v[228:231], v[14:17]
	v_mfma_f32_16x16x32_bf16 v[14:17], v[142:145], v[224:227], v[14:17]
	v_mfma_f32_16x16x32_bf16 v[6:9], v[176:179], v[224:227], v[6:9]
	v_mfma_f32_16x16x32_bf16 v[6:9], v[180:183], v[228:231], v[6:9]
	v_mfma_f32_16x16x32_bf16 v[2:5], v[188:191], v[228:231], v[2:5]
	v_mfma_f32_16x16x32_bf16 v[2:5], v[184:187], v[224:227], v[2:5]
	v_mfma_f32_16x16x32_bf16 v[18:21], v[184:187], v[216:219], v[18:21]
	v_mfma_f32_16x16x32_bf16 v[18:21], v[188:191], v[220:223], v[18:21]
	v_mfma_f32_16x16x32_bf16 v[22:25], v[180:183], v[220:223], v[22:25]
	v_mfma_f32_16x16x32_bf16 v[22:25], v[176:179], v[216:219], v[22:25]
	v_mfma_f32_16x16x32_bf16 v[38:41], v[176:179], v[208:211], v[38:41]
	v_mfma_f32_16x16x32_bf16 v[38:41], v[180:183], v[212:215], v[38:41]
	v_mfma_f32_16x16x32_bf16 v[34:37], v[188:191], v[212:215], v[34:37]
	v_mfma_f32_16x16x32_bf16 v[34:37], v[184:187], v[208:211], v[34:37]
	v_mfma_f32_16x16x32_bf16 v[50:53], v[184:187], v[192:195], v[50:53]
	v_mfma_f32_16x16x32_bf16 v[50:53], v[188:191], v[204:207], v[50:53]
	v_mfma_f32_16x16x32_bf16 v[54:57], v[180:183], v[204:207], v[54:57]
	v_mfma_f32_16x16x32_bf16 v[54:57], v[176:179], v[192:195], v[54:57]
	s_barrier
	s_add_i32 s57, s57, 2
	s_add_u32 s20, s20, 0x100
	s_addc_u32 s21, s21, 0
	s_add_u32 s55, s55, 0x100
	s_addc_u32 s56, s56, 0
.LBB0_2373:
	s_add_u32 s60, s20, 0xfff00000
	s_addc_u32 s61, s21, -1
	s_mov_b32 m0, s35
	ds_read_b128 v[142:145], v148
	global_load_lds_dwordx4 v130, s[60:61]
	s_mov_b32 m0, s36
	ds_read_b128 v[154:157], v148 offset:1024
	global_load_lds_dwordx4 v134, s[60:61]
	s_mov_b32 m0, s40
	ds_read_b128 v[158:161], v148 offset:2048
	global_load_lds_dwordx4 v138, s[20:21]
	s_mov_b32 m0, s41
	ds_read_b128 v[168:171], v148 offset:3072
	global_load_lds_dwordx4 v140, s[20:21]
	ds_read_b128 v[176:179], v149
	ds_read_b128 v[180:183], v149 offset:1024
	ds_read_b128 v[184:187], v149 offset:2048
	ds_read_b128 v[188:191], v149 offset:3072
	s_add_u32 s22, s20, 0xfff00080
	s_addc_u32 s23, s21, -1
	s_cmp_eq_u32 s57, 60
	s_cselect_b32 s25, s52, s23
	s_cselect_b32 s24, s53, s22
	s_cselect_b32 s23, s7, s56
	s_cselect_b32 s22, s54, s55
	ds_read_b128 v[192:195], v150
	ds_read_b128 v[204:207], v150 offset:1024
	ds_read_b128 v[208:211], v150 offset:2048
	ds_read_b128 v[212:215], v150 offset:3072
	ds_read_b128 v[216:219], v150 offset:4096
	ds_read_b128 v[220:223], v150 offset:5120
	ds_read_b128 v[224:227], v150 offset:6144
	ds_read_b128 v[228:231], v150 offset:7168
	s_waitcnt vmcnt(8)
	s_waitcnt lgkmcnt(0)
	s_barrier
	v_mfma_f32_16x16x32_bf16 v[126:129], v[142:145], v[192:195], v[126:129]
	v_mfma_f32_16x16x32_bf16 v[126:129], v[154:157], v[204:207], v[126:129]
	v_mfma_f32_16x16x32_bf16 v[122:125], v[168:171], v[204:207], v[122:125]
	v_mfma_f32_16x16x32_bf16 v[122:125], v[158:161], v[192:195], v[122:125]
	v_mfma_f32_16x16x32_bf16 v[106:109], v[158:161], v[208:211], v[106:109]
	v_mfma_f32_16x16x32_bf16 v[106:109], v[168:171], v[212:215], v[106:109]
	v_mfma_f32_16x16x32_bf16 v[110:113], v[154:157], v[212:215], v[110:113]
	v_mfma_f32_16x16x32_bf16 v[110:113], v[142:145], v[208:211], v[110:113]
	v_mfma_f32_16x16x32_bf16 v[94:97], v[142:145], v[216:219], v[94:97]
	v_mfma_f32_16x16x32_bf16 v[94:97], v[154:157], v[220:223], v[94:97]
	v_mfma_f32_16x16x32_bf16 v[90:93], v[168:171], v[220:223], v[90:93]
	v_mfma_f32_16x16x32_bf16 v[90:93], v[158:161], v[216:219], v[90:93]
	v_mfma_f32_16x16x32_bf16 v[74:77], v[158:161], v[224:227], v[74:77]
	v_mfma_f32_16x16x32_bf16 v[74:77], v[168:171], v[228:231], v[74:77]
	v_mfma_f32_16x16x32_bf16 v[78:81], v[154:157], v[228:231], v[78:81]
	v_mfma_f32_16x16x32_bf16 v[78:81], v[142:145], v[224:227], v[78:81]
	v_mfma_f32_16x16x32_bf16 v[70:73], v[176:179], v[224:227], v[70:73]
	v_mfma_f32_16x16x32_bf16 v[70:73], v[180:183], v[228:231], v[70:73]
	v_mfma_f32_16x16x32_bf16 v[66:69], v[188:191], v[228:231], v[66:69]
	v_mfma_f32_16x16x32_bf16 v[66:69], v[184:187], v[224:227], v[66:69]
	v_mfma_f32_16x16x32_bf16 v[82:85], v[184:187], v[216:219], v[82:85]
	v_mfma_f32_16x16x32_bf16 v[82:85], v[188:191], v[220:223], v[82:85]
	v_mfma_f32_16x16x32_bf16 v[86:89], v[180:183], v[220:223], v[86:89]
	v_mfma_f32_16x16x32_bf16 v[86:89], v[176:179], v[216:219], v[86:89]
	v_mfma_f32_16x16x32_bf16 v[102:105], v[176:179], v[208:211], v[102:105]
	v_mfma_f32_16x16x32_bf16 v[102:105], v[180:183], v[212:215], v[102:105]
	v_mfma_f32_16x16x32_bf16 v[98:101], v[188:191], v[212:215], v[98:101]
	v_mfma_f32_16x16x32_bf16 v[98:101], v[184:187], v[208:211], v[98:101]
	v_mfma_f32_16x16x32_bf16 v[114:117], v[184:187], v[192:195], v[114:117]
	v_mfma_f32_16x16x32_bf16 v[114:117], v[188:191], v[204:207], v[114:117]
	v_mfma_f32_16x16x32_bf16 v[118:121], v[180:183], v[204:207], v[118:121]
	v_mfma_f32_16x16x32_bf16 v[118:121], v[176:179], v[192:195], v[118:121]
	s_barrier
	s_mov_b32 m0, s42
	s_add_u32 s60, s22, 0x100000
	global_load_lds_dwordx4 v132, s[22:23]
	s_mov_b32 m0, s43
	s_addc_u32 s61, s23, 0
	global_load_lds_dwordx4 v136, s[22:23]
	s_mov_b32 m0, s44
	ds_read_b128 v[192:195], v150 offset:16384
	global_load_lds_dwordx4 v132, s[60:61]
	s_mov_b32 m0, s45
	ds_read_b128 v[204:207], v150 offset:17408
	global_load_lds_dwordx4 v136, s[60:61]
	ds_read_b128 v[208:211], v150 offset:18432
	ds_read_b128 v[212:215], v150 offset:19456
	ds_read_b128 v[216:219], v150 offset:20480
	ds_read_b128 v[220:223], v150 offset:21504
	ds_read_b128 v[224:227], v150 offset:22528
	ds_read_b128 v[228:231], v150 offset:23552
	s_waitcnt vmcnt(6)
	s_waitcnt lgkmcnt(0)
	s_barrier
	v_mfma_f32_16x16x32_bf16 v[62:65], v[142:145], v[192:195], v[62:65]
	v_mfma_f32_16x16x32_bf16 v[62:65], v[154:157], v[204:207], v[62:65]
	v_mfma_f32_16x16x32_bf16 v[58:61], v[168:171], v[204:207], v[58:61]
	v_mfma_f32_16x16x32_bf16 v[58:61], v[158:161], v[192:195], v[58:61]
	v_mfma_f32_16x16x32_bf16 v[42:45], v[158:161], v[208:211], v[42:45]
	v_mfma_f32_16x16x32_bf16 v[42:45], v[168:171], v[212:215], v[42:45]
	v_mfma_f32_16x16x32_bf16 v[46:49], v[154:157], v[212:215], v[46:49]
	v_mfma_f32_16x16x32_bf16 v[46:49], v[142:145], v[208:211], v[46:49]
	v_mfma_f32_16x16x32_bf16 v[30:33], v[142:145], v[216:219], v[30:33]
	v_mfma_f32_16x16x32_bf16 v[30:33], v[154:157], v[220:223], v[30:33]
	v_mfma_f32_16x16x32_bf16 v[26:29], v[168:171], v[220:223], v[26:29]
	v_mfma_f32_16x16x32_bf16 v[26:29], v[158:161], v[216:219], v[26:29]
	v_mfma_f32_16x16x32_bf16 v[10:13], v[158:161], v[224:227], v[10:13]
	v_mfma_f32_16x16x32_bf16 v[10:13], v[168:171], v[228:231], v[10:13]
	v_mfma_f32_16x16x32_bf16 v[14:17], v[154:157], v[228:231], v[14:17]
	v_mfma_f32_16x16x32_bf16 v[14:17], v[142:145], v[224:227], v[14:17]
	v_mfma_f32_16x16x32_bf16 v[6:9], v[176:179], v[224:227], v[6:9]
	v_mfma_f32_16x16x32_bf16 v[6:9], v[180:183], v[228:231], v[6:9]
	v_mfma_f32_16x16x32_bf16 v[2:5], v[188:191], v[228:231], v[2:5]
	v_mfma_f32_16x16x32_bf16 v[2:5], v[184:187], v[224:227], v[2:5]
	v_mfma_f32_16x16x32_bf16 v[18:21], v[184:187], v[216:219], v[18:21]
	v_mfma_f32_16x16x32_bf16 v[18:21], v[188:191], v[220:223], v[18:21]
	v_mfma_f32_16x16x32_bf16 v[22:25], v[180:183], v[220:223], v[22:25]
	v_mfma_f32_16x16x32_bf16 v[22:25], v[176:179], v[216:219], v[22:25]
	v_mfma_f32_16x16x32_bf16 v[38:41], v[176:179], v[208:211], v[38:41]
	v_mfma_f32_16x16x32_bf16 v[38:41], v[180:183], v[212:215], v[38:41]
	v_mfma_f32_16x16x32_bf16 v[34:37], v[188:191], v[212:215], v[34:37]
	v_mfma_f32_16x16x32_bf16 v[34:37], v[184:187], v[208:211], v[34:37]
	v_mfma_f32_16x16x32_bf16 v[50:53], v[184:187], v[192:195], v[50:53]
	v_mfma_f32_16x16x32_bf16 v[50:53], v[188:191], v[204:207], v[50:53]
	v_mfma_f32_16x16x32_bf16 v[54:57], v[180:183], v[204:207], v[54:57]
	v_mfma_f32_16x16x32_bf16 v[54:57], v[176:179], v[192:195], v[54:57]
	s_barrier
	s_mov_b32 m0, s29
	ds_read_b128 v[142:145], v151
	global_load_lds_dwordx4 v130, s[24:25]
	s_mov_b32 m0, s30
	ds_read_b128 v[154:157], v151 offset:1024
	global_load_lds_dwordx4 v134, s[24:25]
	s_add_u32 s24, s24, 0x100000
	s_addc_u32 s25, s25, 0
	s_mov_b32 m0, s31
	ds_read_b128 v[158:161], v151 offset:2048
	global_load_lds_dwordx4 v130, s[24:25]
	s_mov_b32 m0, s33
	ds_read_b128 v[168:171], v151 offset:3072
	global_load_lds_dwordx4 v134, s[24:25]
	ds_read_b128 v[176:179], v152
	ds_read_b128 v[180:183], v152 offset:1024
	ds_read_b128 v[184:187], v152 offset:2048
	ds_read_b128 v[188:191], v152 offset:3072
	ds_read_b128 v[192:195], v150 offset:32768
	ds_read_b128 v[204:207], v150 offset:33792
	ds_read_b128 v[208:211], v150 offset:34816
	ds_read_b128 v[212:215], v150 offset:35840
	ds_read_b128 v[216:219], v150 offset:36864
	ds_read_b128 v[220:223], v150 offset:37888
	ds_read_b128 v[224:227], v150 offset:38912
	ds_read_b128 v[228:231], v150 offset:39936
	s_waitcnt vmcnt(8)
	s_waitcnt lgkmcnt(0)
	s_barrier
	v_mfma_f32_16x16x32_bf16 v[126:129], v[142:145], v[192:195], v[126:129]
	v_mfma_f32_16x16x32_bf16 v[126:129], v[154:157], v[204:207], v[126:129]
	v_mfma_f32_16x16x32_bf16 v[122:125], v[168:171], v[204:207], v[122:125]
	v_mfma_f32_16x16x32_bf16 v[122:125], v[158:161], v[192:195], v[122:125]
	v_mfma_f32_16x16x32_bf16 v[106:109], v[158:161], v[208:211], v[106:109]
	v_mfma_f32_16x16x32_bf16 v[106:109], v[168:171], v[212:215], v[106:109]
	v_mfma_f32_16x16x32_bf16 v[110:113], v[154:157], v[212:215], v[110:113]
	v_mfma_f32_16x16x32_bf16 v[110:113], v[142:145], v[208:211], v[110:113]
	v_mfma_f32_16x16x32_bf16 v[94:97], v[142:145], v[216:219], v[94:97]
	v_mfma_f32_16x16x32_bf16 v[94:97], v[154:157], v[220:223], v[94:97]
	v_mfma_f32_16x16x32_bf16 v[90:93], v[168:171], v[220:223], v[90:93]
	v_mfma_f32_16x16x32_bf16 v[90:93], v[158:161], v[216:219], v[90:93]
	v_mfma_f32_16x16x32_bf16 v[74:77], v[158:161], v[224:227], v[74:77]
	v_mfma_f32_16x16x32_bf16 v[74:77], v[168:171], v[228:231], v[74:77]
	v_mfma_f32_16x16x32_bf16 v[78:81], v[154:157], v[228:231], v[78:81]
	v_mfma_f32_16x16x32_bf16 v[78:81], v[142:145], v[224:227], v[78:81]
	v_mfma_f32_16x16x32_bf16 v[70:73], v[176:179], v[224:227], v[70:73]
	v_mfma_f32_16x16x32_bf16 v[70:73], v[180:183], v[228:231], v[70:73]
	v_mfma_f32_16x16x32_bf16 v[66:69], v[188:191], v[228:231], v[66:69]
	v_mfma_f32_16x16x32_bf16 v[66:69], v[184:187], v[224:227], v[66:69]
	v_mfma_f32_16x16x32_bf16 v[82:85], v[184:187], v[216:219], v[82:85]
	v_mfma_f32_16x16x32_bf16 v[82:85], v[188:191], v[220:223], v[82:85]
	v_mfma_f32_16x16x32_bf16 v[86:89], v[180:183], v[220:223], v[86:89]
	v_mfma_f32_16x16x32_bf16 v[86:89], v[176:179], v[216:219], v[86:89]
	v_mfma_f32_16x16x32_bf16 v[102:105], v[176:179], v[208:211], v[102:105]
	v_mfma_f32_16x16x32_bf16 v[102:105], v[180:183], v[212:215], v[102:105]
	v_mfma_f32_16x16x32_bf16 v[98:101], v[188:191], v[212:215], v[98:101]
	v_mfma_f32_16x16x32_bf16 v[98:101], v[184:187], v[208:211], v[98:101]
	v_mfma_f32_16x16x32_bf16 v[114:117], v[184:187], v[192:195], v[114:117]
	v_mfma_f32_16x16x32_bf16 v[114:117], v[188:191], v[204:207], v[114:117]
	v_mfma_f32_16x16x32_bf16 v[118:121], v[180:183], v[204:207], v[118:121]
	v_mfma_f32_16x16x32_bf16 v[118:121], v[176:179], v[192:195], v[118:121]
	s_barrier
	s_mov_b32 m0, s46
	s_add_u32 s22, s22, 0x80
	s_addc_u32 s23, s23, 0
	global_load_lds_dwordx4 v132, s[22:23]
	s_mov_b32 m0, s47
	ds_read_b128 v[192:195], v150 offset:49152
	global_load_lds_dwordx4 v136, s[22:23]
	s_mov_b32 m0, s48
	s_add_u32 s22, s22, 0x100000
	s_addc_u32 s23, s23, 0
	global_load_lds_dwordx4 v132, s[22:23]
	s_mov_b32 m0, s49
	ds_read_b128 v[204:207], v150 offset:50176
	global_load_lds_dwordx4 v136, s[22:23]
	ds_read_b128 v[208:211], v150 offset:51200
	ds_read_b128 v[212:215], v150 offset:52224
	ds_read_b128 v[216:219], v150 offset:53248
	ds_read_b128 v[220:223], v150 offset:54272
	ds_read_b128 v[224:227], v150 offset:55296
	ds_read_b128 v[228:231], v150 offset:56320
	s_waitcnt vmcnt(6)
	s_waitcnt lgkmcnt(0)
	s_barrier
	v_mfma_f32_16x16x32_bf16 v[62:65], v[142:145], v[192:195], v[62:65]
	v_mfma_f32_16x16x32_bf16 v[62:65], v[154:157], v[204:207], v[62:65]
	v_mfma_f32_16x16x32_bf16 v[58:61], v[168:171], v[204:207], v[58:61]
	v_mfma_f32_16x16x32_bf16 v[58:61], v[158:161], v[192:195], v[58:61]
	v_mfma_f32_16x16x32_bf16 v[42:45], v[158:161], v[208:211], v[42:45]
	v_mfma_f32_16x16x32_bf16 v[42:45], v[168:171], v[212:215], v[42:45]
	v_mfma_f32_16x16x32_bf16 v[46:49], v[154:157], v[212:215], v[46:49]
	v_mfma_f32_16x16x32_bf16 v[46:49], v[142:145], v[208:211], v[46:49]
	v_mfma_f32_16x16x32_bf16 v[30:33], v[142:145], v[216:219], v[30:33]
	v_mfma_f32_16x16x32_bf16 v[30:33], v[154:157], v[220:223], v[30:33]
	v_mfma_f32_16x16x32_bf16 v[26:29], v[168:171], v[220:223], v[26:29]
	v_mfma_f32_16x16x32_bf16 v[26:29], v[158:161], v[216:219], v[26:29]
	v_mfma_f32_16x16x32_bf16 v[10:13], v[158:161], v[224:227], v[10:13]
	v_mfma_f32_16x16x32_bf16 v[10:13], v[168:171], v[228:231], v[10:13]
	v_mfma_f32_16x16x32_bf16 v[14:17], v[154:157], v[228:231], v[14:17]
	v_mfma_f32_16x16x32_bf16 v[14:17], v[142:145], v[224:227], v[14:17]
	v_mfma_f32_16x16x32_bf16 v[6:9], v[176:179], v[224:227], v[6:9]
	v_mfma_f32_16x16x32_bf16 v[6:9], v[180:183], v[228:231], v[6:9]
	v_mfma_f32_16x16x32_bf16 v[2:5], v[188:191], v[228:231], v[2:5]
	v_mfma_f32_16x16x32_bf16 v[2:5], v[184:187], v[224:227], v[2:5]
	v_mfma_f32_16x16x32_bf16 v[18:21], v[184:187], v[216:219], v[18:21]
	v_mfma_f32_16x16x32_bf16 v[18:21], v[188:191], v[220:223], v[18:21]
	v_mfma_f32_16x16x32_bf16 v[22:25], v[180:183], v[220:223], v[22:25]
	v_mfma_f32_16x16x32_bf16 v[22:25], v[176:179], v[216:219], v[22:25]
	v_mfma_f32_16x16x32_bf16 v[38:41], v[176:179], v[208:211], v[38:41]
	v_mfma_f32_16x16x32_bf16 v[38:41], v[180:183], v[212:215], v[38:41]
	v_mfma_f32_16x16x32_bf16 v[34:37], v[188:191], v[212:215], v[34:37]
	v_mfma_f32_16x16x32_bf16 v[34:37], v[184:187], v[208:211], v[34:37]
	v_mfma_f32_16x16x32_bf16 v[50:53], v[184:187], v[192:195], v[50:53]
	v_mfma_f32_16x16x32_bf16 v[50:53], v[188:191], v[204:207], v[50:53]
	v_mfma_f32_16x16x32_bf16 v[54:57], v[180:183], v[204:207], v[54:57]
	v_mfma_f32_16x16x32_bf16 v[54:57], v[176:179], v[192:195], v[54:57]
	s_barrier
	s_add_i32 s57, s57, 2
	s_add_u32 s20, s20, 0x100
	s_addc_u32 s21, s21, 0
	s_add_u32 s55, s55, 0x100
	s_addc_u32 s56, s56, 0
	s_cmp_gt_u32 s57, 61
	s_cbranch_scc0 .LBB0_2373
	s_setprio 0
	s_and_b64 vcc, exec, s[16:17]
	s_cbranch_vccz .LBB0_2376
	s_barrier

.LBB0_2617:
	s_and_b64 s[24:25], s[24:25], exec
	s_cselect_b32 s25, s7, s29
	s_cselect_b32 s24, s6, s28
	s_add_u32 s28, s28, 0x2b0080
	s_addc_u32 s29, s29, 0
	s_add_u32 s60, s30, 0x100
	s_addc_u32 s61, s31, 0
	s_mov_b32 s62, -2
	s_and_b64 vcc, exec, s[8:9]
	s_cbranch_vccz .Lsp_7
	s_setprio 1
.Lsp_7:
	s_waitcnt lgkmcnt(0)
	s_add_u32 s64, s28, 0xffd50000
	s_addc_u32 s65, s29, -1
	s_mov_b32 m0, s44
	ds_read_b128 v[142:145], v156
	global_load_lds_dwordx4 v130, s[64:65]
	s_mov_b32 m0, s45
	ds_read_b128 v[168:171], v156 offset:1024
	global_load_lds_dwordx4 v134, s[64:65]
	s_mov_b32 m0, s46
	ds_read_b128 v[172:175], v156 offset:2048
	global_load_lds_dwordx4 v138, s[28:29]
	s_mov_b32 m0, s47
	ds_read_b128 v[176:179], v156 offset:3072
	global_load_lds_dwordx4 v140, s[28:29]
	ds_read_b128 v[180:183], v157
	ds_read_b128 v[184:187], v157 offset:1024
	ds_read_b128 v[188:191], v157 offset:2048
	ds_read_b128 v[192:195], v157 offset:3072
	s_add_u32 s30, s28, 0xffd50080
	s_addc_u32 s31, s29, -1
	s_cmpk_eq_i32 s62, 0xa8
	s_cselect_b32 s35, s25, s31
	s_cselect_b32 s34, s24, s30
	s_cselect_b32 s31, s23, s61
	s_cselect_b32 s30, s22, s60
	ds_read_b128 v[196:199], v158
	ds_read_b128 v[200:203], v158 offset:1024
	ds_read_b128 v[204:207], v158 offset:2048
	ds_read_b128 v[208:211], v158 offset:3072
	ds_read_b128 v[212:215], v158 offset:4096
	ds_read_b128 v[216:219], v158 offset:5120
	ds_read_b128 v[220:223], v158 offset:6144
	ds_read_b128 v[224:227], v158 offset:7168
	s_waitcnt vmcnt(8)
	s_waitcnt lgkmcnt(0)
	s_barrier
	v_mfma_f32_16x16x32_bf16 v[126:129], v[142:145], v[196:199], 0
	v_mfma_f32_16x16x32_bf16 v[126:129], v[168:171], v[200:203], v[126:129]
	v_mfma_f32_16x16x32_bf16 v[122:125], v[176:179], v[200:203], 0
	v_mfma_f32_16x16x32_bf16 v[122:125], v[172:175], v[196:199], v[122:125]
	v_mfma_f32_16x16x32_bf16 v[106:109], v[172:175], v[204:207], 0
	v_mfma_f32_16x16x32_bf16 v[106:109], v[176:179], v[208:211], v[106:109]
	v_mfma_f32_16x16x32_bf16 v[110:113], v[168:171], v[208:211], 0
	v_mfma_f32_16x16x32_bf16 v[110:113], v[142:145], v[204:207], v[110:113]
	v_mfma_f32_16x16x32_bf16 v[94:97], v[142:145], v[212:215], 0
	v_mfma_f32_16x16x32_bf16 v[94:97], v[168:171], v[216:219], v[94:97]
	v_mfma_f32_16x16x32_bf16 v[90:93], v[176:179], v[216:219], 0
	v_mfma_f32_16x16x32_bf16 v[90:93], v[172:175], v[212:215], v[90:93]
	v_mfma_f32_16x16x32_bf16 v[74:77], v[172:175], v[220:223], 0
	v_mfma_f32_16x16x32_bf16 v[74:77], v[176:179], v[224:227], v[74:77]
	v_mfma_f32_16x16x32_bf16 v[78:81], v[168:171], v[224:227], 0
	v_mfma_f32_16x16x32_bf16 v[78:81], v[142:145], v[220:223], v[78:81]
	v_mfma_f32_16x16x32_bf16 v[70:73], v[180:183], v[220:223], 0
	v_mfma_f32_16x16x32_bf16 v[70:73], v[184:187], v[224:227], v[70:73]
	v_mfma_f32_16x16x32_bf16 v[66:69], v[192:195], v[224:227], 0
	v_mfma_f32_16x16x32_bf16 v[66:69], v[188:191], v[220:223], v[66:69]
	v_mfma_f32_16x16x32_bf16 v[82:85], v[188:191], v[212:215], 0
	v_mfma_f32_16x16x32_bf16 v[82:85], v[192:195], v[216:219], v[82:85]
	v_mfma_f32_16x16x32_bf16 v[86:89], v[184:187], v[216:219], 0
	v_mfma_f32_16x16x32_bf16 v[86:89], v[180:183], v[212:215], v[86:89]
	v_mfma_f32_16x16x32_bf16 v[102:105], v[180:183], v[204:207], 0
	v_mfma_f32_16x16x32_bf16 v[102:105], v[184:187], v[208:211], v[102:105]
	v_mfma_f32_16x16x32_bf16 v[98:101], v[192:195], v[208:211], 0
	v_mfma_f32_16x16x32_bf16 v[98:101], v[188:191], v[204:207], v[98:101]
	v_mfma_f32_16x16x32_bf16 v[114:117], v[188:191], v[196:199], 0
	v_mfma_f32_16x16x32_bf16 v[114:117], v[192:195], v[200:203], v[114:117]
	v_mfma_f32_16x16x32_bf16 v[118:121], v[184:187], v[200:203], 0
	v_mfma_f32_16x16x32_bf16 v[118:121], v[180:183], v[196:199], v[118:121]
	s_barrier
	s_mov_b32 m0, s48
	s_add_u32 s64, s30, 0x2b0000
	global_load_lds_dwordx4 v132, s[30:31]
	s_mov_b32 m0, s49
	s_addc_u32 s65, s31, 0
	global_load_lds_dwordx4 v136, s[30:31]
	s_mov_b32 m0, s50
	ds_read_b128 v[196:199], v158 offset:16384
	global_load_lds_dwordx4 v132, s[64:65]
	s_mov_b32 m0, s51
	ds_read_b128 v[200:203], v158 offset:17408
	global_load_lds_dwordx4 v136, s[64:65]
	ds_read_b128 v[204:207], v158 offset:18432
	ds_read_b128 v[208:211], v158 offset:19456
	ds_read_b128 v[212:215], v158 offset:20480
	ds_read_b128 v[216:219], v158 offset:21504
	ds_read_b128 v[220:223], v158 offset:22528
	ds_read_b128 v[224:227], v158 offset:23552
	s_waitcnt vmcnt(6)
	s_waitcnt lgkmcnt(0)
	s_barrier
	v_mfma_f32_16x16x32_bf16 v[62:65], v[142:145], v[196:199], 0
	v_mfma_f32_16x16x32_bf16 v[62:65], v[168:171], v[200:203], v[62:65]
	v_mfma_f32_16x16x32_bf16 v[58:61], v[176:179], v[200:203], 0
	v_mfma_f32_16x16x32_bf16 v[58:61], v[172:175], v[196:199], v[58:61]
	v_mfma_f32_16x16x32_bf16 v[42:45], v[172:175], v[204:207], 0
	v_mfma_f32_16x16x32_bf16 v[42:45], v[176:179], v[208:211], v[42:45]
	v_mfma_f32_16x16x32_bf16 v[46:49], v[168:171], v[208:211], 0
	v_mfma_f32_16x16x32_bf16 v[46:49], v[142:145], v[204:207], v[46:49]
	v_mfma_f32_16x16x32_bf16 v[30:33], v[142:145], v[212:215], 0
	v_mfma_f32_16x16x32_bf16 v[30:33], v[168:171], v[216:219], v[30:33]
	v_mfma_f32_16x16x32_bf16 v[26:29], v[176:179], v[216:219], 0
	v_mfma_f32_16x16x32_bf16 v[26:29], v[172:175], v[212:215], v[26:29]
	v_mfma_f32_16x16x32_bf16 v[10:13], v[172:175], v[220:223], 0
	v_mfma_f32_16x16x32_bf16 v[10:13], v[176:179], v[224:227], v[10:13]
	v_mfma_f32_16x16x32_bf16 v[14:17], v[168:171], v[224:227], 0
	v_mfma_f32_16x16x32_bf16 v[14:17], v[142:145], v[220:223], v[14:17]
	v_mfma_f32_16x16x32_bf16 v[6:9], v[180:183], v[220:223], 0
	v_mfma_f32_16x16x32_bf16 v[6:9], v[184:187], v[224:227], v[6:9]
	v_mfma_f32_16x16x32_bf16 v[2:5], v[192:195], v[224:227], 0
	v_mfma_f32_16x16x32_bf16 v[2:5], v[188:191], v[220:223], v[2:5]
	v_mfma_f32_16x16x32_bf16 v[18:21], v[188:191], v[212:215], 0
	v_mfma_f32_16x16x32_bf16 v[18:21], v[192:195], v[216:219], v[18:21]
	v_mfma_f32_16x16x32_bf16 v[22:25], v[184:187], v[216:219], 0
	v_mfma_f32_16x16x32_bf16 v[22:25], v[180:183], v[212:215], v[22:25]
	v_mfma_f32_16x16x32_bf16 v[38:41], v[180:183], v[204:207], 0
	v_mfma_f32_16x16x32_bf16 v[38:41], v[184:187], v[208:211], v[38:41]
	v_mfma_f32_16x16x32_bf16 v[34:37], v[192:195], v[208:211], 0
	v_mfma_f32_16x16x32_bf16 v[34:37], v[188:191], v[204:207], v[34:37]
	v_mfma_f32_16x16x32_bf16 v[50:53], v[188:191], v[196:199], 0
	v_mfma_f32_16x16x32_bf16 v[50:53], v[192:195], v[200:203], v[50:53]
	v_mfma_f32_16x16x32_bf16 v[54:57], v[184:187], v[200:203], 0
	v_mfma_f32_16x16x32_bf16 v[54:57], v[180:183], v[196:199], v[54:57]
	s_barrier
	s_mov_b32 m0, s39
	ds_read_b128 v[142:145], v159
	global_load_lds_dwordx4 v130, s[34:35]
	s_mov_b32 m0, s40
	ds_read_b128 v[168:171], v159 offset:1024
	global_load_lds_dwordx4 v134, s[34:35]
	s_add_u32 s34, s34, 0x2b0000
	s_addc_u32 s35, s35, 0
	s_mov_b32 m0, s41
	ds_read_b128 v[172:175], v159 offset:2048
	global_load_lds_dwordx4 v130, s[34:35]
	s_mov_b32 m0, s42
	ds_read_b128 v[176:179], v159 offset:3072
	global_load_lds_dwordx4 v134, s[34:35]
	ds_read_b128 v[180:183], v160
	ds_read_b128 v[184:187], v160 offset:1024
	ds_read_b128 v[188:191], v160 offset:2048
	ds_read_b128 v[192:195], v160 offset:3072
	ds_read_b128 v[196:199], v158 offset:32768
	ds_read_b128 v[200:203], v158 offset:33792
	ds_read_b128 v[204:207], v158 offset:34816
	ds_read_b128 v[208:211], v158 offset:35840
	ds_read_b128 v[212:215], v158 offset:36864
	ds_read_b128 v[216:219], v158 offset:37888
	ds_read_b128 v[220:223], v158 offset:38912
	ds_read_b128 v[224:227], v158 offset:39936
	s_waitcnt vmcnt(8)
	s_waitcnt lgkmcnt(0)
	s_barrier
	v_mfma_f32_16x16x32_bf16 v[126:129], v[142:145], v[196:199], v[126:129]
	v_mfma_f32_16x16x32_bf16 v[126:129], v[168:171], v[200:203], v[126:129]
	v_mfma_f32_16x16x32_bf16 v[122:125], v[176:179], v[200:203], v[122:125]
	v_mfma_f32_16x16x32_bf16 v[122:125], v[172:175], v[196:199], v[122:125]
	v_mfma_f32_16x16x32_bf16 v[106:109], v[172:175], v[204:207], v[106:109]
	v_mfma_f32_16x16x32_bf16 v[106:109], v[176:179], v[208:211], v[106:109]
	v_mfma_f32_16x16x32_bf16 v[110:113], v[168:171], v[208:211], v[110:113]
	v_mfma_f32_16x16x32_bf16 v[110:113], v[142:145], v[204:207], v[110:113]
	v_mfma_f32_16x16x32_bf16 v[94:97], v[142:145], v[212:215], v[94:97]
	v_mfma_f32_16x16x32_bf16 v[94:97], v[168:171], v[216:219], v[94:97]
	v_mfma_f32_16x16x32_bf16 v[90:93], v[176:179], v[216:219], v[90:93]
	v_mfma_f32_16x16x32_bf16 v[90:93], v[172:175], v[212:215], v[90:93]
	v_mfma_f32_16x16x32_bf16 v[74:77], v[172:175], v[220:223], v[74:77]
	v_mfma_f32_16x16x32_bf16 v[74:77], v[176:179], v[224:227], v[74:77]
	v_mfma_f32_16x16x32_bf16 v[78:81], v[168:171], v[224:227], v[78:81]
	v_mfma_f32_16x16x32_bf16 v[78:81], v[142:145], v[220:223], v[78:81]
	v_mfma_f32_16x16x32_bf16 v[70:73], v[180:183], v[220:223], v[70:73]
	v_mfma_f32_16x16x32_bf16 v[70:73], v[184:187], v[224:227], v[70:73]
	v_mfma_f32_16x16x32_bf16 v[66:69], v[192:195], v[224:227], v[66:69]
	v_mfma_f32_16x16x32_bf16 v[66:69], v[188:191], v[220:223], v[66:69]
	v_mfma_f32_16x16x32_bf16 v[82:85], v[188:191], v[212:215], v[82:85]
	v_mfma_f32_16x16x32_bf16 v[82:85], v[192:195], v[216:219], v[82:85]
	v_mfma_f32_16x16x32_bf16 v[86:89], v[184:187], v[216:219], v[86:89]
	v_mfma_f32_16x16x32_bf16 v[86:89], v[180:183], v[212:215], v[86:89]
	v_mfma_f32_16x16x32_bf16 v[102:105], v[180:183], v[204:207], v[102:105]
	v_mfma_f32_16x16x32_bf16 v[102:105], v[184:187], v[208:211], v[102:105]
	v_mfma_f32_16x16x32_bf16 v[98:101], v[192:195], v[208:211], v[98:101]
	v_mfma_f32_16x16x32_bf16 v[98:101], v[188:191], v[204:207], v[98:101]
	v_mfma_f32_16x16x32_bf16 v[114:117], v[188:191], v[196:199], v[114:117]
	v_mfma_f32_16x16x32_bf16 v[114:117], v[192:195], v[200:203], v[114:117]
	v_mfma_f32_16x16x32_bf16 v[118:121], v[184:187], v[200:203], v[118:121]
	v_mfma_f32_16x16x32_bf16 v[118:121], v[180:183], v[196:199], v[118:121]
	s_barrier
	s_mov_b32 m0, s52
	s_add_u32 s30, s30, 0x80
	s_addc_u32 s31, s31, 0
	global_load_lds_dwordx4 v132, s[30:31]
	s_mov_b32 m0, s53
	ds_read_b128 v[196:199], v158 offset:49152
	global_load_lds_dwordx4 v136, s[30:31]
	s_mov_b32 m0, s54
	s_add_u32 s30, s30, 0x2b0000
	s_addc_u32 s31, s31, 0
	global_load_lds_dwordx4 v132, s[30:31]
	s_mov_b32 m0, s55
	ds_read_b128 v[200:203], v158 offset:50176
	global_load_lds_dwordx4 v136, s[30:31]
	ds_read_b128 v[204:207], v158 offset:51200
	ds_read_b128 v[208:211], v158 offset:52224
	ds_read_b128 v[212:215], v158 offset:53248
	ds_read_b128 v[216:219], v158 offset:54272
	ds_read_b128 v[220:223], v158 offset:55296
	ds_read_b128 v[224:227], v158 offset:56320
	s_waitcnt vmcnt(6)
	s_waitcnt lgkmcnt(0)
	s_barrier
	v_mfma_f32_16x16x32_bf16 v[62:65], v[142:145], v[196:199], v[62:65]
	v_mfma_f32_16x16x32_bf16 v[62:65], v[168:171], v[200:203], v[62:65]
	v_mfma_f32_16x16x32_bf16 v[58:61], v[176:179], v[200:203], v[58:61]
	v_mfma_f32_16x16x32_bf16 v[58:61], v[172:175], v[196:199], v[58:61]
	v_mfma_f32_16x16x32_bf16 v[42:45], v[172:175], v[204:207], v[42:45]
	v_mfma_f32_16x16x32_bf16 v[42:45], v[176:179], v[208:211], v[42:45]
	v_mfma_f32_16x16x32_bf16 v[46:49], v[168:171], v[208:211], v[46:49]
	v_mfma_f32_16x16x32_bf16 v[46:49], v[142:145], v[204:207], v[46:49]
	v_mfma_f32_16x16x32_bf16 v[30:33], v[142:145], v[212:215], v[30:33]
	v_mfma_f32_16x16x32_bf16 v[30:33], v[168:171], v[216:219], v[30:33]
	v_mfma_f32_16x16x32_bf16 v[26:29], v[176:179], v[216:219], v[26:29]
	v_mfma_f32_16x16x32_bf16 v[26:29], v[172:175], v[212:215], v[26:29]
	v_mfma_f32_16x16x32_bf16 v[10:13], v[172:175], v[220:223], v[10:13]
	v_mfma_f32_16x16x32_bf16 v[10:13], v[176:179], v[224:227], v[10:13]
	v_mfma_f32_16x16x32_bf16 v[14:17], v[168:171], v[224:227], v[14:17]
	v_mfma_f32_16x16x32_bf16 v[14:17], v[142:145], v[220:223], v[14:17]
	v_mfma_f32_16x16x32_bf16 v[6:9], v[180:183], v[220:223], v[6:9]
	v_mfma_f32_16x16x32_bf16 v[6:9], v[184:187], v[224:227], v[6:9]
	v_mfma_f32_16x16x32_bf16 v[2:5], v[192:195], v[224:227], v[2:5]
	v_mfma_f32_16x16x32_bf16 v[2:5], v[188:191], v[220:223], v[2:5]
	v_mfma_f32_16x16x32_bf16 v[18:21], v[188:191], v[212:215], v[18:21]
	v_mfma_f32_16x16x32_bf16 v[18:21], v[192:195], v[216:219], v[18:21]
	v_mfma_f32_16x16x32_bf16 v[22:25], v[184:187], v[216:219], v[22:25]
	v_mfma_f32_16x16x32_bf16 v[22:25], v[180:183], v[212:215], v[22:25]
	v_mfma_f32_16x16x32_bf16 v[38:41], v[180:183], v[204:207], v[38:41]
	v_mfma_f32_16x16x32_bf16 v[38:41], v[184:187], v[208:211], v[38:41]
	v_mfma_f32_16x16x32_bf16 v[34:37], v[192:195], v[208:211], v[34:37]
	v_mfma_f32_16x16x32_bf16 v[34:37], v[188:191], v[204:207], v[34:37]
	v_mfma_f32_16x16x32_bf16 v[50:53], v[188:191], v[196:199], v[50:53]
	v_mfma_f32_16x16x32_bf16 v[50:53], v[192:195], v[200:203], v[50:53]
	v_mfma_f32_16x16x32_bf16 v[54:57], v[184:187], v[200:203], v[54:57]
	v_mfma_f32_16x16x32_bf16 v[54:57], v[180:183], v[196:199], v[54:57]
	s_barrier
	s_add_i32 s62, s62, 2
	s_add_u32 s28, s28, 0x100
	s_addc_u32 s29, s29, 0
	s_add_u32 s60, s60, 0x100
	s_addc_u32 s61, s61, 0
.LBB0_2618:
	s_add_u32 s64, s28, 0xffd50000
	s_addc_u32 s65, s29, -1
	s_mov_b32 m0, s44
	ds_read_b128 v[142:145], v156
	global_load_lds_dwordx4 v130, s[64:65]
	s_mov_b32 m0, s45
	ds_read_b128 v[168:171], v156 offset:1024
	global_load_lds_dwordx4 v134, s[64:65]
	s_mov_b32 m0, s46
	ds_read_b128 v[172:175], v156 offset:2048
	global_load_lds_dwordx4 v138, s[28:29]
	s_mov_b32 m0, s47
	ds_read_b128 v[176:179], v156 offset:3072
	global_load_lds_dwordx4 v140, s[28:29]
	ds_read_b128 v[180:183], v157
	ds_read_b128 v[184:187], v157 offset:1024
	ds_read_b128 v[188:191], v157 offset:2048
	ds_read_b128 v[192:195], v157 offset:3072
	s_add_u32 s30, s28, 0xffd50080
	s_addc_u32 s31, s29, -1
	s_cmpk_eq_i32 s62, 0xa8
	s_cselect_b32 s35, s25, s31
	s_cselect_b32 s34, s24, s30
	s_cselect_b32 s31, s23, s61
	s_cselect_b32 s30, s22, s60
	ds_read_b128 v[196:199], v158
	ds_read_b128 v[200:203], v158 offset:1024
	ds_read_b128 v[204:207], v158 offset:2048
	ds_read_b128 v[208:211], v158 offset:3072
	ds_read_b128 v[212:215], v158 offset:4096
	ds_read_b128 v[216:219], v158 offset:5120
	ds_read_b128 v[220:223], v158 offset:6144
	ds_read_b128 v[224:227], v158 offset:7168
	s_waitcnt vmcnt(8)
	s_waitcnt lgkmcnt(0)
	s_barrier
	v_mfma_f32_16x16x32_bf16 v[126:129], v[142:145], v[196:199], v[126:129]
	v_mfma_f32_16x16x32_bf16 v[126:129], v[168:171], v[200:203], v[126:129]
	v_mfma_f32_16x16x32_bf16 v[122:125], v[176:179], v[200:203], v[122:125]
	v_mfma_f32_16x16x32_bf16 v[122:125], v[172:175], v[196:199], v[122:125]
	v_mfma_f32_16x16x32_bf16 v[106:109], v[172:175], v[204:207], v[106:109]
	v_mfma_f32_16x16x32_bf16 v[106:109], v[176:179], v[208:211], v[106:109]
	v_mfma_f32_16x16x32_bf16 v[110:113], v[168:171], v[208:211], v[110:113]
	v_mfma_f32_16x16x32_bf16 v[110:113], v[142:145], v[204:207], v[110:113]
	v_mfma_f32_16x16x32_bf16 v[94:97], v[142:145], v[212:215], v[94:97]
	v_mfma_f32_16x16x32_bf16 v[94:97], v[168:171], v[216:219], v[94:97]
	v_mfma_f32_16x16x32_bf16 v[90:93], v[176:179], v[216:219], v[90:93]
	v_mfma_f32_16x16x32_bf16 v[90:93], v[172:175], v[212:215], v[90:93]
	v_mfma_f32_16x16x32_bf16 v[74:77], v[172:175], v[220:223], v[74:77]
	v_mfma_f32_16x16x32_bf16 v[74:77], v[176:179], v[224:227], v[74:77]
	v_mfma_f32_16x16x32_bf16 v[78:81], v[168:171], v[224:227], v[78:81]
	v_mfma_f32_16x16x32_bf16 v[78:81], v[142:145], v[220:223], v[78:81]
	v_mfma_f32_16x16x32_bf16 v[70:73], v[180:183], v[220:223], v[70:73]
	v_mfma_f32_16x16x32_bf16 v[70:73], v[184:187], v[224:227], v[70:73]
	v_mfma_f32_16x16x32_bf16 v[66:69], v[192:195], v[224:227], v[66:69]
	v_mfma_f32_16x16x32_bf16 v[66:69], v[188:191], v[220:223], v[66:69]
	v_mfma_f32_16x16x32_bf16 v[82:85], v[188:191], v[212:215], v[82:85]
	v_mfma_f32_16x16x32_bf16 v[82:85], v[192:195], v[216:219], v[82:85]
	v_mfma_f32_16x16x32_bf16 v[86:89], v[184:187], v[216:219], v[86:89]
	v_mfma_f32_16x16x32_bf16 v[86:89], v[180:183], v[212:215], v[86:89]
	v_mfma_f32_16x16x32_bf16 v[102:105], v[180:183], v[204:207], v[102:105]
	v_mfma_f32_16x16x32_bf16 v[102:105], v[184:187], v[208:211], v[102:105]
	v_mfma_f32_16x16x32_bf16 v[98:101], v[192:195], v[208:211], v[98:101]
	v_mfma_f32_16x16x32_bf16 v[98:101], v[188:191], v[204:207], v[98:101]
	v_mfma_f32_16x16x32_bf16 v[114:117], v[188:191], v[196:199], v[114:117]
	v_mfma_f32_16x16x32_bf16 v[114:117], v[192:195], v[200:203], v[114:117]
	v_mfma_f32_16x16x32_bf16 v[118:121], v[184:187], v[200:203], v[118:121]
	v_mfma_f32_16x16x32_bf16 v[118:121], v[180:183], v[196:199], v[118:121]
	s_barrier
	s_mov_b32 m0, s48
	s_add_u32 s64, s30, 0x2b0000
	global_load_lds_dwordx4 v132, s[30:31]
	s_mov_b32 m0, s49
	s_addc_u32 s65, s31, 0
	global_load_lds_dwordx4 v136, s[30:31]
	s_mov_b32 m0, s50
	ds_read_b128 v[196:199], v158 offset:16384
	global_load_lds_dwordx4 v132, s[64:65]
	s_mov_b32 m0, s51
	ds_read_b128 v[200:203], v158 offset:17408
	global_load_lds_dwordx4 v136, s[64:65]
	ds_read_b128 v[204:207], v158 offset:18432
	ds_read_b128 v[208:211], v158 offset:19456
	ds_read_b128 v[212:215], v158 offset:20480
	ds_read_b128 v[216:219], v158 offset:21504
	ds_read_b128 v[220:223], v158 offset:22528
	ds_read_b128 v[224:227], v158 offset:23552
	s_waitcnt vmcnt(6)
	s_waitcnt lgkmcnt(0)
	s_barrier
	v_mfma_f32_16x16x32_bf16 v[62:65], v[142:145], v[196:199], v[62:65]
	v_mfma_f32_16x16x32_bf16 v[62:65], v[168:171], v[200:203], v[62:65]
	v_mfma_f32_16x16x32_bf16 v[58:61], v[176:179], v[200:203], v[58:61]
	v_mfma_f32_16x16x32_bf16 v[58:61], v[172:175], v[196:199], v[58:61]
	v_mfma_f32_16x16x32_bf16 v[42:45], v[172:175], v[204:207], v[42:45]
	v_mfma_f32_16x16x32_bf16 v[42:45], v[176:179], v[208:211], v[42:45]
	v_mfma_f32_16x16x32_bf16 v[46:49], v[168:171], v[208:211], v[46:49]
	v_mfma_f32_16x16x32_bf16 v[46:49], v[142:145], v[204:207], v[46:49]
	v_mfma_f32_16x16x32_bf16 v[30:33], v[142:145], v[212:215], v[30:33]
	v_mfma_f32_16x16x32_bf16 v[30:33], v[168:171], v[216:219], v[30:33]
	v_mfma_f32_16x16x32_bf16 v[26:29], v[176:179], v[216:219], v[26:29]
	v_mfma_f32_16x16x32_bf16 v[26:29], v[172:175], v[212:215], v[26:29]
	v_mfma_f32_16x16x32_bf16 v[10:13], v[172:175], v[220:223], v[10:13]
	v_mfma_f32_16x16x32_bf16 v[10:13], v[176:179], v[224:227], v[10:13]
	v_mfma_f32_16x16x32_bf16 v[14:17], v[168:171], v[224:227], v[14:17]
	v_mfma_f32_16x16x32_bf16 v[14:17], v[142:145], v[220:223], v[14:17]
	v_mfma_f32_16x16x32_bf16 v[6:9], v[180:183], v[220:223], v[6:9]
	v_mfma_f32_16x16x32_bf16 v[6:9], v[184:187], v[224:227], v[6:9]
	v_mfma_f32_16x16x32_bf16 v[2:5], v[192:195], v[224:227], v[2:5]
	v_mfma_f32_16x16x32_bf16 v[2:5], v[188:191], v[220:223], v[2:5]
	v_mfma_f32_16x16x32_bf16 v[18:21], v[188:191], v[212:215], v[18:21]
	v_mfma_f32_16x16x32_bf16 v[18:21], v[192:195], v[216:219], v[18:21]
	v_mfma_f32_16x16x32_bf16 v[22:25], v[184:187], v[216:219], v[22:25]
	v_mfma_f32_16x16x32_bf16 v[22:25], v[180:183], v[212:215], v[22:25]
	v_mfma_f32_16x16x32_bf16 v[38:41], v[180:183], v[204:207], v[38:41]
	v_mfma_f32_16x16x32_bf16 v[38:41], v[184:187], v[208:211], v[38:41]
	v_mfma_f32_16x16x32_bf16 v[34:37], v[192:195], v[208:211], v[34:37]
	v_mfma_f32_16x16x32_bf16 v[34:37], v[188:191], v[204:207], v[34:37]
	v_mfma_f32_16x16x32_bf16 v[50:53], v[188:191], v[196:199], v[50:53]
	v_mfma_f32_16x16x32_bf16 v[50:53], v[192:195], v[200:203], v[50:53]
	v_mfma_f32_16x16x32_bf16 v[54:57], v[184:187], v[200:203], v[54:57]
	v_mfma_f32_16x16x32_bf16 v[54:57], v[180:183], v[196:199], v[54:57]
	s_barrier
	s_mov_b32 m0, s39
	ds_read_b128 v[142:145], v159
	global_load_lds_dwordx4 v130, s[34:35]
	s_mov_b32 m0, s40
	ds_read_b128 v[168:171], v159 offset:1024
	global_load_lds_dwordx4 v134, s[34:35]
	s_add_u32 s34, s34, 0x2b0000
	s_addc_u32 s35, s35, 0
	s_mov_b32 m0, s41
	ds_read_b128 v[172:175], v159 offset:2048
	global_load_lds_dwordx4 v130, s[34:35]
	s_mov_b32 m0, s42
	ds_read_b128 v[176:179], v159 offset:3072
	global_load_lds_dwordx4 v134, s[34:35]
	ds_read_b128 v[180:183], v160
	ds_read_b128 v[184:187], v160 offset:1024
	ds_read_b128 v[188:191], v160 offset:2048
	ds_read_b128 v[192:195], v160 offset:3072
	ds_read_b128 v[196:199], v158 offset:32768
	ds_read_b128 v[200:203], v158 offset:33792
	ds_read_b128 v[204:207], v158 offset:34816
	ds_read_b128 v[208:211], v158 offset:35840
	ds_read_b128 v[212:215], v158 offset:36864
	ds_read_b128 v[216:219], v158 offset:37888
	ds_read_b128 v[220:223], v158 offset:38912
	ds_read_b128 v[224:227], v158 offset:39936
	s_waitcnt vmcnt(8)
	s_waitcnt lgkmcnt(0)
	s_barrier
	v_mfma_f32_16x16x32_bf16 v[126:129], v[142:145], v[196:199], v[126:129]
	v_mfma_f32_16x16x32_bf16 v[126:129], v[168:171], v[200:203], v[126:129]
	v_mfma_f32_16x16x32_bf16 v[122:125], v[176:179], v[200:203], v[122:125]
	v_mfma_f32_16x16x32_bf16 v[122:125], v[172:175], v[196:199], v[122:125]
	v_mfma_f32_16x16x32_bf16 v[106:109], v[172:175], v[204:207], v[106:109]
	v_mfma_f32_16x16x32_bf16 v[106:109], v[176:179], v[208:211], v[106:109]
	v_mfma_f32_16x16x32_bf16 v[110:113], v[168:171], v[208:211], v[110:113]
	v_mfma_f32_16x16x32_bf16 v[110:113], v[142:145], v[204:207], v[110:113]
	v_mfma_f32_16x16x32_bf16 v[94:97], v[142:145], v[212:215], v[94:97]
	v_mfma_f32_16x16x32_bf16 v[94:97], v[168:171], v[216:219], v[94:97]
	v_mfma_f32_16x16x32_bf16 v[90:93], v[176:179], v[216:219], v[90:93]
	v_mfma_f32_16x16x32_bf16 v[90:93], v[172:175], v[212:215], v[90:93]
	v_mfma_f32_16x16x32_bf16 v[74:77], v[172:175], v[220:223], v[74:77]
	v_mfma_f32_16x16x32_bf16 v[74:77], v[176:179], v[224:227], v[74:77]
	v_mfma_f32_16x16x32_bf16 v[78:81], v[168:171], v[224:227], v[78:81]
	v_mfma_f32_16x16x32_bf16 v[78:81], v[142:145], v[220:223], v[78:81]
	v_mfma_f32_16x16x32_bf16 v[70:73], v[180:183], v[220:223], v[70:73]
	v_mfma_f32_16x16x32_bf16 v[70:73], v[184:187], v[224:227], v[70:73]
	v_mfma_f32_16x16x32_bf16 v[66:69], v[192:195], v[224:227], v[66:69]
	v_mfma_f32_16x16x32_bf16 v[66:69], v[188:191], v[220:223], v[66:69]
	v_mfma_f32_16x16x32_bf16 v[82:85], v[188:191], v[212:215], v[82:85]
	v_mfma_f32_16x16x32_bf16 v[82:85], v[192:195], v[216:219], v[82:85]
	v_mfma_f32_16x16x32_bf16 v[86:89], v[184:187], v[216:219], v[86:89]
	v_mfma_f32_16x16x32_bf16 v[86:89], v[180:183], v[212:215], v[86:89]
	v_mfma_f32_16x16x32_bf16 v[102:105], v[180:183], v[204:207], v[102:105]
	v_mfma_f32_16x16x32_bf16 v[102:105], v[184:187], v[208:211], v[102:105]
	v_mfma_f32_16x16x32_bf16 v[98:101], v[192:195], v[208:211], v[98:101]
	v_mfma_f32_16x16x32_bf16 v[98:101], v[188:191], v[204:207], v[98:101]
	v_mfma_f32_16x16x32_bf16 v[114:117], v[188:191], v[196:199], v[114:117]
	v_mfma_f32_16x16x32_bf16 v[114:117], v[192:195], v[200:203], v[114:117]
	v_mfma_f32_16x16x32_bf16 v[118:121], v[184:187], v[200:203], v[118:121]
	v_mfma_f32_16x16x32_bf16 v[118:121], v[180:183], v[196:199], v[118:121]
	s_barrier
	s_mov_b32 m0, s52
	s_add_u32 s30, s30, 0x80
	s_addc_u32 s31, s31, 0
	global_load_lds_dwordx4 v132, s[30:31]
	s_mov_b32 m0, s53
	ds_read_b128 v[196:199], v158 offset:49152
	global_load_lds_dwordx4 v136, s[30:31]
	s_mov_b32 m0, s54
	s_add_u32 s30, s30, 0x2b0000
	s_addc_u32 s31, s31, 0
	global_load_lds_dwordx4 v132, s[30:31]
	s_mov_b32 m0, s55
	ds_read_b128 v[200:203], v158 offset:50176
	global_load_lds_dwordx4 v136, s[30:31]
	ds_read_b128 v[204:207], v158 offset:51200
	ds_read_b128 v[208:211], v158 offset:52224
	ds_read_b128 v[212:215], v158 offset:53248
	ds_read_b128 v[216:219], v158 offset:54272
	ds_read_b128 v[220:223], v158 offset:55296
	ds_read_b128 v[224:227], v158 offset:56320
	s_waitcnt vmcnt(6)
	s_waitcnt lgkmcnt(0)
	s_barrier
	v_mfma_f32_16x16x32_bf16 v[62:65], v[142:145], v[196:199], v[62:65]
	v_mfma_f32_16x16x32_bf16 v[62:65], v[168:171], v[200:203], v[62:65]
	v_mfma_f32_16x16x32_bf16 v[58:61], v[176:179], v[200:203], v[58:61]
	v_mfma_f32_16x16x32_bf16 v[58:61], v[172:175], v[196:199], v[58:61]
	v_mfma_f32_16x16x32_bf16 v[42:45], v[172:175], v[204:207], v[42:45]
	v_mfma_f32_16x16x32_bf16 v[42:45], v[176:179], v[208:211], v[42:45]
	v_mfma_f32_16x16x32_bf16 v[46:49], v[168:171], v[208:211], v[46:49]
	v_mfma_f32_16x16x32_bf16 v[46:49], v[142:145], v[204:207], v[46:49]
	v_mfma_f32_16x16x32_bf16 v[30:33], v[142:145], v[212:215], v[30:33]
	v_mfma_f32_16x16x32_bf16 v[30:33], v[168:171], v[216:219], v[30:33]
	v_mfma_f32_16x16x32_bf16 v[26:29], v[176:179], v[216:219], v[26:29]
	v_mfma_f32_16x16x32_bf16 v[26:29], v[172:175], v[212:215], v[26:29]
	v_mfma_f32_16x16x32_bf16 v[10:13], v[172:175], v[220:223], v[10:13]
	v_mfma_f32_16x16x32_bf16 v[10:13], v[176:179], v[224:227], v[10:13]
	v_mfma_f32_16x16x32_bf16 v[14:17], v[168:171], v[224:227], v[14:17]
	v_mfma_f32_16x16x32_bf16 v[14:17], v[142:145], v[220:223], v[14:17]
	v_mfma_f32_16x16x32_bf16 v[6:9], v[180:183], v[220:223], v[6:9]
	v_mfma_f32_16x16x32_bf16 v[6:9], v[184:187], v[224:227], v[6:9]
	v_mfma_f32_16x16x32_bf16 v[2:5], v[192:195], v[224:227], v[2:5]
	v_mfma_f32_16x16x32_bf16 v[2:5], v[188:191], v[220:223], v[2:5]
	v_mfma_f32_16x16x32_bf16 v[18:21], v[188:191], v[212:215], v[18:21]
	v_mfma_f32_16x16x32_bf16 v[18:21], v[192:195], v[216:219], v[18:21]
	v_mfma_f32_16x16x32_bf16 v[22:25], v[184:187], v[216:219], v[22:25]
	v_mfma_f32_16x16x32_bf16 v[22:25], v[180:183], v[212:215], v[22:25]
	v_mfma_f32_16x16x32_bf16 v[38:41], v[180:183], v[204:207], v[38:41]
	v_mfma_f32_16x16x32_bf16 v[38:41], v[184:187], v[208:211], v[38:41]
	v_mfma_f32_16x16x32_bf16 v[34:37], v[192:195], v[208:211], v[34:37]
	v_mfma_f32_16x16x32_bf16 v[34:37], v[188:191], v[204:207], v[34:37]
	v_mfma_f32_16x16x32_bf16 v[50:53], v[188:191], v[196:199], v[50:53]
	v_mfma_f32_16x16x32_bf16 v[50:53], v[192:195], v[200:203], v[50:53]
	v_mfma_f32_16x16x32_bf16 v[54:57], v[184:187], v[200:203], v[54:57]
	v_mfma_f32_16x16x32_bf16 v[54:57], v[180:183], v[196:199], v[54:57]
	s_barrier
	s_add_i32 s62, s62, 2
	s_add_u32 s28, s28, 0x100
	s_addc_u32 s29, s29, 0
	s_add_u32 s60, s60, 0x100
	s_addc_u32 s61, s61, 0
	s_cmpk_gt_u32 s62, 0xa9
	s_cbranch_scc0 .LBB0_2618
	s_setprio 0
	s_and_b64 vcc, exec, s[12:13]
	s_cbranch_vccz .LBB0_2621
	s_barrier
